# v69 + GEMM read sections: M0-write to LDS-DMA wait state filled by the load's own v_lshl_add_u64 instead of s_nop 0 (98 nops removed)
# speedup vs baseline: 1.0193x; 1.0027x over previous
; #define PG8_STAGE(bufoff, gbase, voff) do { _Pragma("unroll") for (int _i = 0; _i < 2; ++_i) \
;         __builtin_amdgcn_global_load_lds((const unsigned*)((const char*)(gbase) + (voff)[_i]), (LAS unsigned*)(lds + (bufoff) + ldsw + _i * 8192), 16, 0, 0); } while (0)
; #define PG8_LDA(dst, b, h) do { _Pragma("unroll") for (int m = 0; m < 4; ++m) _Pragma("unroll") for (int k = 0; k < 2; ++k) dst[m][k] = *(const LAS bf16x8*)(lds + PG8_SA(b, h) + aoff + m * 2048 + k * 1024); } while (0)
; #define PG8_LDB(dst, b, h) do { _Pragma("unroll") for (int n = 0; n < 2; ++n) _Pragma("unroll") for (int k = 0; k < 2; ++k) dst[n][k] = *(const LAS bf16x8*)(lds + PG8_SB(b, h) + boff + n * 2048 + k * 1024); } while (0)
; #define PG8_MMA(ai, bj, At, Bt) do { __builtin_amdgcn_s_setprio(1); _Pragma("unroll") for (int m = 0; m < 4; ++m) _Pragma("unroll") for (int n = 0; n < 2; ++n) _Pragma("unroll") for (int k = 0; k < 2; ++k) \
;         acc[ai][bj][m][n] = __builtin_amdgcn_mfma_f32_16x16x32_bf16(Bt[n][k], At[m][k], acc[ai][bj][m][n], 0, 0, 0); __builtin_amdgcn_s_setprio(0); } while (0)
; #define PG8_WAIT_V(n) asm volatile("s_waitcnt vmcnt(" #n ")" ::: "memory")
; #define PG8_WAIT_L(n) asm volatile("s_waitcnt lgkmcnt(" #n ")" ::: "memory")
; #define PG8_BAR __builtin_amdgcn_s_barrier()
; #define PG8_SCHED __builtin_amdgcn_sched_barrier(0)
; template <class Epi, bool ALIGN_EPI = PG8_ALIGN, bool SP2 = PG8_SP2>
; __device__ __forceinline__ void gemm_phase(LAS uchar* lds, const Gemm g, const StaticOrder& S, const Epi& E) {
;     ...
;             const bool last = (t == nt - 2);
;             const char* a1 = cA + (size_t)(t + 1) * kstep;
;             const char* a2 = last ? nA : cA + (size_t)(t + 2) * kstep; const char* b2 = last ? nB : cB + (size_t)(t + 2) * kstep;
;             const char* a3 = a2 + kstep; const char* b3 = b2 + kstep;
;             if constexpr (SP2) {
;             PG8_LDB(B0, 0, 0); PG8_LDB(B1, 0, 1); PG8_SCHED; PG8_LDA(At, 0, 0); PG8_STAGE(PG8_SA(1, 1), a1 + hstepA, voffA);
;             PG8_WAIT_V(8); PG8_WAIT_L(0); PG8_BAR; PG8_MMA(0, 0, At, B0); PG8_MMA(0, 1, At, B1); PG8_BAR; PG8_SCHED;
.LBB0_344:
	s_add_u32 s38, s4, 0x100
	s_addc_u32 s39, s5, 0
	s_mov_b32 s40, -2
	s_add_u32 s18, s16, 0x100
	s_addc_u32 s19, s17, 0
	s_add_i32 s41, 0, 0x10000
	s_cmp_eq_u32 s40, 12
	s_cselect_b32 s21, s7, s19
	s_cselect_b32 s20, s6, s18
	v_add_u32_e32 v168, s41, v139
	s_cselect_b32 s5, s15, s39
	s_cselect_b32 s4, s14, s38
	s_add_i32 s42, 0, 0x14000
	ds_read_b128 v[164:167], v168
	ds_read_b128 v[172:175], v168 offset:1024
	ds_read_b128 v[176:179], v168 offset:2048
	ds_read_b128 v[184:187], v168 offset:3072
	v_add_u32_e32 v168, s42, v139
	ds_read_b128 v[188:191], v168
	ds_read_b128 v[192:195], v168 offset:1024
	ds_read_b128 v[196:199], v168 offset:2048
	ds_read_b128 v[200:203], v168 offset:3072
	v_lshl_add_u64 v[168:169], s[16:17], 0, v[160:161]
	s_add_i32 m0, s25, 0xc000
	ds_read_b128 v[204:207], v171
	ds_read_b128 v[208:211], v171 offset:1024
	ds_read_b128 v[212:215], v171 offset:2048
	ds_read_b128 v[216:219], v171 offset:3072
	ds_read_b128 v[220:223], v171 offset:4096
	ds_read_b128 v[224:227], v171 offset:5120
	ds_read_b128 v[228:231], v171 offset:6144
	ds_read_b128 v[232:235], v171 offset:7168
	global_load_lds_dwordx4 v[168:169], off
	s_add_i32 m0, s25, 0xe000
	v_lshl_add_u64 v[168:169], s[16:17], 0, v[162:163]
	global_load_lds_dwordx4 v[168:169], off
	s_cmp_eq_u32 s97, 1
	s_cbranch_scc0 .Lrw_std_345_0_pl
	s_waitcnt vmcnt(24)
	s_branch .Lrw_done_345_0_pl

; #define PG8_STAGE(bufoff, gbase, voff) do { _Pragma("unroll") for (int _i = 0; _i < 2; ++_i) \
;         __builtin_amdgcn_global_load_lds((const unsigned*)((const char*)(gbase) + (voff)[_i]), (LAS unsigned*)(lds + (bufoff) + ldsw + _i * 8192), 16, 0, 0); } while (0)
; #define PG8_LDA(dst, b, h) do { _Pragma("unroll") for (int m = 0; m < 4; ++m) _Pragma("unroll") for (int k = 0; k < 2; ++k) dst[m][k] = *(const LAS bf16x8*)(lds + PG8_SA(b, h) + aoff + m * 2048 + k * 1024); } while (0)
; #define PG8_MMA(ai, bj, At, Bt) do { __builtin_amdgcn_s_setprio(1); _Pragma("unroll") for (int m = 0; m < 4; ++m) _Pragma("unroll") for (int n = 0; n < 2; ++n) _Pragma("unroll") for (int k = 0; k < 2; ++k) \
;         acc[ai][bj][m][n] = __builtin_amdgcn_mfma_f32_16x16x32_bf16(Bt[n][k], At[m][k], acc[ai][bj][m][n], 0, 0, 0); __builtin_amdgcn_s_setprio(0); } while (0)
; #define PG8_WAIT_V(n) asm volatile("s_waitcnt vmcnt(" #n ")" ::: "memory")
; #define PG8_WAIT_L(n) asm volatile("s_waitcnt lgkmcnt(" #n ")" ::: "memory")
; #define PG8_BAR __builtin_amdgcn_s_barrier()
; #define PG8_SCHED __builtin_amdgcn_sched_barrier(0)
; template <class Epi, bool ALIGN_EPI = PG8_ALIGN, bool SP2 = PG8_SP2>
; __device__ __forceinline__ void gemm_phase(LAS uchar* lds, const Gemm g, const StaticOrder& S, const Epi& E) {
;     ...
;             PG8_WAIT_V(8); PG8_WAIT_L(0); PG8_BAR; PG8_MMA(0, 0, At, B0); PG8_MMA(0, 1, At, B1); PG8_BAR; PG8_SCHED;
;             PG8_LDA(At, 0, 1); PG8_STAGE(PG8_SB(0, 0), b2, voffB); PG8_STAGE(PG8_SB(0, 1), b2 + hstepB, voffB); PG8_STAGE(PG8_SA(0, 0), a2, voffA);
.Lrw_done_345_0_pl:
	s_waitcnt lgkmcnt(0)
	s_setprio 1
	s_barrier
	v_mfma_f32_16x16x32_bf16 v[126:129], v[164:167], v[204:207], 0
	v_mfma_f32_16x16x32_bf16 v[122:125], v[176:179], v[204:207], 0
	v_mfma_f32_16x16x32_bf16 v[118:121], v[164:167], v[212:215], 0
	v_mfma_f32_16x16x32_bf16 v[110:113], v[176:179], v[212:215], 0
	v_mfma_f32_16x16x32_bf16 v[102:105], v[164:167], v[220:223], 0
	v_mfma_f32_16x16x32_bf16 v[94:97], v[176:179], v[220:223], 0
	v_mfma_f32_16x16x32_bf16 v[86:89], v[164:167], v[228:231], 0
	v_mfma_f32_16x16x32_bf16 v[78:81], v[176:179], v[228:231], 0
	v_mfma_f32_16x16x32_bf16 v[126:129], v[172:175], v[208:211], v[126:129]
	v_mfma_f32_16x16x32_bf16 v[122:125], v[184:187], v[208:211], v[122:125]
	v_mfma_f32_16x16x32_bf16 v[118:121], v[172:175], v[216:219], v[118:121]
	v_mfma_f32_16x16x32_bf16 v[110:113], v[184:187], v[216:219], v[110:113]
	v_mfma_f32_16x16x32_bf16 v[102:105], v[172:175], v[224:227], v[102:105]
	v_mfma_f32_16x16x32_bf16 v[94:97], v[184:187], v[224:227], v[94:97]
	v_mfma_f32_16x16x32_bf16 v[86:89], v[172:175], v[232:235], v[86:89]
	v_mfma_f32_16x16x32_bf16 v[78:81], v[184:187], v[232:235], v[78:81]
	v_mfma_f32_16x16x32_bf16 v[114:117], v[188:191], v[204:207], 0
	v_mfma_f32_16x16x32_bf16 v[106:109], v[196:199], v[204:207], 0
	v_mfma_f32_16x16x32_bf16 v[98:101], v[188:191], v[212:215], 0
	v_mfma_f32_16x16x32_bf16 v[90:93], v[196:199], v[212:215], 0
	v_mfma_f32_16x16x32_bf16 v[82:85], v[188:191], v[220:223], 0
	v_mfma_f32_16x16x32_bf16 v[74:77], v[196:199], v[220:223], 0
	v_mfma_f32_16x16x32_bf16 v[70:73], v[188:191], v[228:231], 0
	v_mfma_f32_16x16x32_bf16 v[66:69], v[196:199], v[228:231], 0
	v_mfma_f32_16x16x32_bf16 v[114:117], v[192:195], v[208:211], v[114:117]
	v_mfma_f32_16x16x32_bf16 v[106:109], v[200:203], v[208:211], v[106:109]
	v_mfma_f32_16x16x32_bf16 v[98:101], v[192:195], v[216:219], v[98:101]
	v_mfma_f32_16x16x32_bf16 v[90:93], v[200:203], v[216:219], v[90:93]
	v_mfma_f32_16x16x32_bf16 v[82:85], v[192:195], v[224:227], v[82:85]
	v_mfma_f32_16x16x32_bf16 v[74:77], v[200:203], v[224:227], v[74:77]
	v_mfma_f32_16x16x32_bf16 v[70:73], v[192:195], v[232:235], v[70:73]
	v_mfma_f32_16x16x32_bf16 v[66:69], v[200:203], v[232:235], v[66:69]
	s_barrier
	s_setprio 0
	s_add_i32 s16, s41, s23
	v_lshl_add_u64 v[168:169], s[4:5], 0, v[134:135]
	s_mov_b32 m0, s16
	ds_read_b128 v[204:207], v171 offset:16384
	ds_read_b128 v[208:211], v171 offset:17408
	ds_read_b128 v[212:215], v171 offset:18432
	ds_read_b128 v[216:219], v171 offset:19456
	ds_read_b128 v[220:223], v171 offset:20480
	ds_read_b128 v[224:227], v171 offset:21504
	ds_read_b128 v[228:231], v171 offset:22528
	ds_read_b128 v[232:235], v171 offset:23552
	global_load_lds_dwordx4 v[168:169], off
	s_add_i32 m0, s16, 0x2000
	s_add_u32 s16, s4, 0x44000
	v_lshl_add_u64 v[180:181], s[4:5], 0, v[130:131]
	s_addc_u32 s17, s5, 0
	s_add_i32 s41, s42, s23
	global_load_lds_dwordx4 v[180:181], off
	v_lshl_add_u64 v[236:237], s[16:17], 0, v[134:135]
	s_mov_b32 m0, s41
	global_load_lds_dwordx4 v[236:237], off
	s_add_i32 m0, s41, 0x2000
	v_lshl_add_u64 v[236:237], s[16:17], 0, v[130:131]
	global_load_lds_dwordx4 v[236:237], off
	s_mov_b32 m0, s25
	v_lshl_add_u64 v[236:237], s[20:21], 0, v[156:157]
	global_load_lds_dwordx4 v[236:237], off
	s_mov_b32 m0, s26
	v_lshl_add_u64 v[238:239], s[20:21], 0, v[132:133]
	global_load_lds_dwordx4 v[238:239], off
	s_cmp_eq_u32 s97, 1
	s_cbranch_scc0 .Lrw_std_345_1_pl
	s_waitcnt vmcnt(24)
	s_branch .Lrw_done_345_1_pl

; #define PG8_STAGE(bufoff, gbase, voff) do { _Pragma("unroll") for (int _i = 0; _i < 2; ++_i) \
;         __builtin_amdgcn_global_load_lds((const unsigned*)((const char*)(gbase) + (voff)[_i]), (LAS unsigned*)(lds + (bufoff) + ldsw + _i * 8192), 16, 0, 0); } while (0)
; #define PG8_LDA(dst, b, h) do { _Pragma("unroll") for (int m = 0; m < 4; ++m) _Pragma("unroll") for (int k = 0; k < 2; ++k) dst[m][k] = *(const LAS bf16x8*)(lds + PG8_SA(b, h) + aoff + m * 2048 + k * 1024); } while (0)
; #define PG8_LDB(dst, b, h) do { _Pragma("unroll") for (int n = 0; n < 2; ++n) _Pragma("unroll") for (int k = 0; k < 2; ++k) dst[n][k] = *(const LAS bf16x8*)(lds + PG8_SB(b, h) + boff + n * 2048 + k * 1024); } while (0)
; #define PG8_MMA(ai, bj, At, Bt) do { __builtin_amdgcn_s_setprio(1); _Pragma("unroll") for (int m = 0; m < 4; ++m) _Pragma("unroll") for (int n = 0; n < 2; ++n) _Pragma("unroll") for (int k = 0; k < 2; ++k) \
;         acc[ai][bj][m][n] = __builtin_amdgcn_mfma_f32_16x16x32_bf16(Bt[n][k], At[m][k], acc[ai][bj][m][n], 0, 0, 0); __builtin_amdgcn_s_setprio(0); } while (0)
; #define PG8_WAIT_V(n) asm volatile("s_waitcnt vmcnt(" #n ")" ::: "memory")
; #define PG8_WAIT_L(n) asm volatile("s_waitcnt lgkmcnt(" #n ")" ::: "memory")
; #define PG8_BAR __builtin_amdgcn_s_barrier()
; #define PG8_SCHED __builtin_amdgcn_sched_barrier(0)
; template <class Epi, bool ALIGN_EPI = PG8_ALIGN, bool SP2 = PG8_SP2>
; __device__ __forceinline__ void gemm_phase(LAS uchar* lds, const Gemm g, const StaticOrder& S, const Epi& E) {
;     ...
;             PG8_WAIT_V(8); PG8_WAIT_L(0); PG8_BAR; PG8_MMA(1, 0, At, B0); PG8_MMA(1, 1, At, B1); PG8_BAR; PG8_SCHED;
;             PG8_LDB(B0, 1, 0); PG8_LDB(B1, 1, 1); PG8_SCHED; PG8_LDA(At, 1, 0); PG8_STAGE(PG8_SA(0, 1), a2 + hstepA, voffA);
;             PG8_WAIT_V(8); PG8_WAIT_L(0); PG8_BAR; PG8_MMA(0, 0, At, B0); PG8_MMA(0, 1, At, B1); PG8_BAR; PG8_SCHED;
.Lrw_done_345_1_pl:
	s_waitcnt lgkmcnt(0)
	s_setprio 1
	s_barrier
	v_mfma_f32_16x16x32_bf16 v[62:65], v[164:167], v[204:207], 0
	v_mfma_f32_16x16x32_bf16 v[58:61], v[176:179], v[204:207], 0
	v_mfma_f32_16x16x32_bf16 v[54:57], v[164:167], v[212:215], 0
	v_mfma_f32_16x16x32_bf16 v[46:49], v[176:179], v[212:215], 0
	v_mfma_f32_16x16x32_bf16 v[38:41], v[164:167], v[220:223], 0
	v_mfma_f32_16x16x32_bf16 v[30:33], v[176:179], v[220:223], 0
	v_mfma_f32_16x16x32_bf16 v[22:25], v[164:167], v[228:231], 0
	v_mfma_f32_16x16x32_bf16 v[14:17], v[176:179], v[228:231], 0
	v_mfma_f32_16x16x32_bf16 v[62:65], v[172:175], v[208:211], v[62:65]
	v_mfma_f32_16x16x32_bf16 v[58:61], v[184:187], v[208:211], v[58:61]
	v_mfma_f32_16x16x32_bf16 v[54:57], v[172:175], v[216:219], v[54:57]
	v_mfma_f32_16x16x32_bf16 v[46:49], v[184:187], v[216:219], v[46:49]
	v_mfma_f32_16x16x32_bf16 v[38:41], v[172:175], v[224:227], v[38:41]
	v_mfma_f32_16x16x32_bf16 v[30:33], v[184:187], v[224:227], v[30:33]
	v_mfma_f32_16x16x32_bf16 v[22:25], v[172:175], v[232:235], v[22:25]
	v_mfma_f32_16x16x32_bf16 v[14:17], v[184:187], v[232:235], v[14:17]
	v_mfma_f32_16x16x32_bf16 v[50:53], v[188:191], v[204:207], 0
	v_mfma_f32_16x16x32_bf16 v[42:45], v[196:199], v[204:207], 0
	v_mfma_f32_16x16x32_bf16 v[34:37], v[188:191], v[212:215], 0
	v_mfma_f32_16x16x32_bf16 v[26:29], v[196:199], v[212:215], 0
	v_mfma_f32_16x16x32_bf16 v[18:21], v[188:191], v[220:223], 0
	v_mfma_f32_16x16x32_bf16 v[10:13], v[196:199], v[220:223], 0
	v_mfma_f32_16x16x32_bf16 v[6:9], v[188:191], v[228:231], 0
	v_mfma_f32_16x16x32_bf16 v[2:5], v[196:199], v[228:231], 0
	v_mfma_f32_16x16x32_bf16 v[50:53], v[192:195], v[208:211], v[50:53]
	v_mfma_f32_16x16x32_bf16 v[42:45], v[200:203], v[208:211], v[42:45]
	v_mfma_f32_16x16x32_bf16 v[34:37], v[192:195], v[216:219], v[34:37]
	v_mfma_f32_16x16x32_bf16 v[26:29], v[200:203], v[216:219], v[26:29]
	v_mfma_f32_16x16x32_bf16 v[18:21], v[192:195], v[224:227], v[18:21]
	v_mfma_f32_16x16x32_bf16 v[10:13], v[200:203], v[224:227], v[10:13]
	v_mfma_f32_16x16x32_bf16 v[6:9], v[192:195], v[232:235], v[6:9]
	v_mfma_f32_16x16x32_bf16 v[2:5], v[200:203], v[232:235], v[2:5]
	s_barrier
	s_setprio 0
	s_add_i32 s41, 0, 0x18000
	s_add_i32 s42, 0, 0x1c000
	v_add_u32_e32 v184, s41, v139
	v_add_u32_e32 v200, s42, v139
	ds_read_b128 v[164:167], v184
	ds_read_b128 v[172:175], v184 offset:1024
	ds_read_b128 v[176:179], v184 offset:2048
	ds_read_b128 v[184:187], v184 offset:3072
	ds_read_b128 v[188:191], v200
	ds_read_b128 v[192:195], v200 offset:1024
	ds_read_b128 v[196:199], v200 offset:2048
	ds_read_b128 v[200:203], v200 offset:3072
	s_add_u32 s16, s20, 0x44000
	s_addc_u32 s17, s21, 0
	s_mov_b32 m0, s27
	v_lshl_add_u64 v[240:241], s[16:17], 0, v[156:157]
	ds_read_b128 v[204:207], v171 offset:32768
	ds_read_b128 v[208:211], v171 offset:33792
	ds_read_b128 v[212:215], v171 offset:34816
	ds_read_b128 v[216:219], v171 offset:35840
	ds_read_b128 v[220:223], v171 offset:36864
	ds_read_b128 v[224:227], v171 offset:37888
	ds_read_b128 v[228:231], v171 offset:38912
	ds_read_b128 v[232:235], v171 offset:39936
	global_load_lds_dwordx4 v[240:241], off
	s_mov_b32 m0, s28
	v_lshl_add_u64 v[240:241], s[16:17], 0, v[132:133]
	global_load_lds_dwordx4 v[240:241], off
	s_waitcnt vmcnt(8)
	s_waitcnt lgkmcnt(0)
	s_setprio 1
	s_barrier
	v_mfma_f32_16x16x32_bf16 v[126:129], v[164:167], v[204:207], v[126:129]
	v_mfma_f32_16x16x32_bf16 v[122:125], v[176:179], v[204:207], v[122:125]
	v_mfma_f32_16x16x32_bf16 v[118:121], v[164:167], v[212:215], v[118:121]
	v_mfma_f32_16x16x32_bf16 v[110:113], v[176:179], v[212:215], v[110:113]
	v_mfma_f32_16x16x32_bf16 v[102:105], v[164:167], v[220:223], v[102:105]
	v_mfma_f32_16x16x32_bf16 v[94:97], v[176:179], v[220:223], v[94:97]
	v_mfma_f32_16x16x32_bf16 v[86:89], v[164:167], v[228:231], v[86:89]
	v_mfma_f32_16x16x32_bf16 v[78:81], v[176:179], v[228:231], v[78:81]
	v_mfma_f32_16x16x32_bf16 v[126:129], v[172:175], v[208:211], v[126:129]
	v_mfma_f32_16x16x32_bf16 v[122:125], v[184:187], v[208:211], v[122:125]
	v_mfma_f32_16x16x32_bf16 v[118:121], v[172:175], v[216:219], v[118:121]
	v_mfma_f32_16x16x32_bf16 v[110:113], v[184:187], v[216:219], v[110:113]
	v_mfma_f32_16x16x32_bf16 v[102:105], v[172:175], v[224:227], v[102:105]
	v_mfma_f32_16x16x32_bf16 v[94:97], v[184:187], v[224:227], v[94:97]
	v_mfma_f32_16x16x32_bf16 v[86:89], v[172:175], v[232:235], v[86:89]
	v_mfma_f32_16x16x32_bf16 v[78:81], v[184:187], v[232:235], v[78:81]
	v_mfma_f32_16x16x32_bf16 v[114:117], v[188:191], v[204:207], v[114:117]
	v_mfma_f32_16x16x32_bf16 v[106:109], v[196:199], v[204:207], v[106:109]
	v_mfma_f32_16x16x32_bf16 v[98:101], v[188:191], v[212:215], v[98:101]
	v_mfma_f32_16x16x32_bf16 v[90:93], v[196:199], v[212:215], v[90:93]
	v_mfma_f32_16x16x32_bf16 v[82:85], v[188:191], v[220:223], v[82:85]
	v_mfma_f32_16x16x32_bf16 v[74:77], v[196:199], v[220:223], v[74:77]
	v_mfma_f32_16x16x32_bf16 v[70:73], v[188:191], v[228:231], v[70:73]
	v_mfma_f32_16x16x32_bf16 v[66:69], v[196:199], v[228:231], v[66:69]
	v_mfma_f32_16x16x32_bf16 v[114:117], v[192:195], v[208:211], v[114:117]
	v_mfma_f32_16x16x32_bf16 v[106:109], v[200:203], v[208:211], v[106:109]
	v_mfma_f32_16x16x32_bf16 v[98:101], v[192:195], v[216:219], v[98:101]
	v_mfma_f32_16x16x32_bf16 v[90:93], v[200:203], v[216:219], v[90:93]
	v_mfma_f32_16x16x32_bf16 v[82:85], v[192:195], v[224:227], v[82:85]
	v_mfma_f32_16x16x32_bf16 v[74:77], v[200:203], v[224:227], v[74:77]
	v_mfma_f32_16x16x32_bf16 v[70:73], v[192:195], v[232:235], v[70:73]
	v_mfma_f32_16x16x32_bf16 v[66:69], v[200:203], v[232:235], v[66:69]
	s_barrier
; #define PG8_STAGE(bufoff, gbase, voff) do { _Pragma("unroll") for (int _i = 0; _i < 2; ++_i) \
;         __builtin_amdgcn_global_load_lds((const unsigned*)((const char*)(gbase) + (voff)[_i]), (LAS unsigned*)(lds + (bufoff) + ldsw + _i * 8192), 16, 0, 0); } while (0)
; #define PG8_LDA(dst, b, h) do { _Pragma("unroll") for (int m = 0; m < 4; ++m) _Pragma("unroll") for (int k = 0; k < 2; ++k) dst[m][k] = *(const LAS bf16x8*)(lds + PG8_SA(b, h) + aoff + m * 2048 + k * 1024); } while (0)
; #define PG8_LDB(dst, b, h) do { _Pragma("unroll") for (int n = 0; n < 2; ++n) _Pragma("unroll") for (int k = 0; k < 2; ++k) dst[n][k] = *(const LAS bf16x8*)(lds + PG8_SB(b, h) + boff + n * 2048 + k * 1024); } while (0)
; #define PG8_WAIT_V(n) asm volatile("s_waitcnt vmcnt(" #n ")" ::: "memory")
; #define PG8_BAR __builtin_amdgcn_s_barrier()
; template <class Epi, bool ALIGN_EPI = PG8_ALIGN, bool SP2 = PG8_SP2>
; __device__ __forceinline__ void gemm_phase(LAS uchar* lds, const Gemm g, const StaticOrder& S, const Epi& E) {
;     ...
;             const bool last = (t == nt - 2);
;             const char* a1 = cA + (size_t)(t + 1) * kstep;
;             const char* a2 = last ? nA : cA + (size_t)(t + 2) * kstep; const char* b2 = last ? nB : cB + (size_t)(t + 2) * kstep;
;             const char* a3 = a2 + kstep; const char* b3 = b2 + kstep;
;             if constexpr (SP2) {
;             PG8_LDB(B0, 0, 0); PG8_LDB(B1, 0, 1); PG8_SCHED; PG8_LDA(At, 0, 0); PG8_STAGE(PG8_SA(1, 1), a1 + hstepA, voffA);
;             PG8_WAIT_V(8); PG8_WAIT_L(0); PG8_BAR; PG8_MMA(0, 0, At, B0); PG8_MMA(0, 1, At, B1); PG8_BAR; PG8_SCHED;
;             PG8_LDA(At, 0, 1); PG8_STAGE(PG8_SB(0, 0), b2, voffB); PG8_STAGE(PG8_SB(0, 1), b2 + hstepB, voffB); PG8_STAGE(PG8_SA(0, 0), a2, voffA);
;             PG8_WAIT_V(8); PG8_WAIT_L(0); PG8_BAR; PG8_MMA(1, 0, At, B0); PG8_MMA(1, 1, At, B1); PG8_BAR; PG8_SCHED;
;             PG8_LDB(B0, 1, 0); PG8_LDB(B1, 1, 1); PG8_SCHED; PG8_LDA(At, 1, 0); PG8_STAGE(PG8_SA(0, 1), a2 + hstepA, voffA);
;             PG8_WAIT_V(8); PG8_WAIT_L(0); PG8_BAR; PG8_MMA(0, 0, At, B0); PG8_MMA(0, 1, At, B1); PG8_BAR; PG8_SCHED;
;             PG8_LDA(At, 1, 1); PG8_STAGE(PG8_SB(1, 0), b3, voffB); PG8_STAGE(PG8_SB(1, 1), b3 + hstepB, voffB); PG8_STAGE(PG8_SA(1, 0), a3, voffA);
;             PG8_WAIT_V(8); PG8_WAIT_L(0); PG8_BAR; PG8_MMA(1, 0, At, B0); PG8_MMA(1, 1, At, B1); PG8_BAR; PG8_SCHED;
	s_setprio 0
	s_add_i32 s16, s41, s23
	v_lshl_add_u64 v[168:169], v[168:169], 0, s[84:85]
	s_mov_b32 m0, s16
	ds_read_b128 v[204:207], v171 offset:49152
	ds_read_b128 v[208:211], v171 offset:50176
	ds_read_b128 v[212:215], v171 offset:51200
	ds_read_b128 v[216:219], v171 offset:52224
	ds_read_b128 v[220:223], v171 offset:53248
	ds_read_b128 v[224:227], v171 offset:54272
	ds_read_b128 v[228:231], v171 offset:55296
	ds_read_b128 v[232:235], v171 offset:56320
	global_load_lds_dwordx4 v[168:169], off
	s_add_i32 m0, s16, 0x2000
	s_add_u32 s4, s4, 0x44080
	v_lshl_add_u64 v[168:169], v[180:181], 0, s[84:85]
	s_addc_u32 s5, s5, 0
	s_add_i32 s16, s42, s23
	global_load_lds_dwordx4 v[168:169], off
	s_mov_b32 m0, s16
	v_lshl_add_u64 v[168:169], s[4:5], 0, v[134:135]
	global_load_lds_dwordx4 v[168:169], off
	s_add_i32 m0, s16, 0x2000
	v_lshl_add_u64 v[168:169], s[4:5], 0, v[130:131]
	global_load_lds_dwordx4 v[168:169], off
	s_mov_b32 m0, s29
	v_lshl_add_u64 v[168:169], v[236:237], 0, s[84:85]
	global_load_lds_dwordx4 v[168:169], off
	s_mov_b32 m0, s30
	v_lshl_add_u64 v[168:169], v[238:239], 0, s[84:85]
	global_load_lds_dwordx4 v[168:169], off
	s_waitcnt vmcnt(8)
	s_waitcnt lgkmcnt(0)
	s_setprio 1
	s_barrier
	v_mfma_f32_16x16x32_bf16 v[62:65], v[164:167], v[204:207], v[62:65]
	v_mfma_f32_16x16x32_bf16 v[58:61], v[176:179], v[204:207], v[58:61]
	v_mfma_f32_16x16x32_bf16 v[54:57], v[164:167], v[212:215], v[54:57]
	v_mfma_f32_16x16x32_bf16 v[46:49], v[176:179], v[212:215], v[46:49]
	v_mfma_f32_16x16x32_bf16 v[38:41], v[164:167], v[220:223], v[38:41]
	v_mfma_f32_16x16x32_bf16 v[30:33], v[176:179], v[220:223], v[30:33]
	v_mfma_f32_16x16x32_bf16 v[22:25], v[164:167], v[228:231], v[22:25]
	v_mfma_f32_16x16x32_bf16 v[14:17], v[176:179], v[228:231], v[14:17]
	v_mfma_f32_16x16x32_bf16 v[62:65], v[172:175], v[208:211], v[62:65]
	v_mfma_f32_16x16x32_bf16 v[58:61], v[184:187], v[208:211], v[58:61]
	v_mfma_f32_16x16x32_bf16 v[54:57], v[172:175], v[216:219], v[54:57]
	v_mfma_f32_16x16x32_bf16 v[46:49], v[184:187], v[216:219], v[46:49]
	v_mfma_f32_16x16x32_bf16 v[38:41], v[172:175], v[224:227], v[38:41]
	v_mfma_f32_16x16x32_bf16 v[30:33], v[184:187], v[224:227], v[30:33]
	v_mfma_f32_16x16x32_bf16 v[22:25], v[172:175], v[232:235], v[22:25]
	v_mfma_f32_16x16x32_bf16 v[14:17], v[184:187], v[232:235], v[14:17]
	v_mfma_f32_16x16x32_bf16 v[50:53], v[188:191], v[204:207], v[50:53]
	v_mfma_f32_16x16x32_bf16 v[42:45], v[196:199], v[204:207], v[42:45]
	v_mfma_f32_16x16x32_bf16 v[34:37], v[188:191], v[212:215], v[34:37]
	v_mfma_f32_16x16x32_bf16 v[26:29], v[196:199], v[212:215], v[26:29]
	v_mfma_f32_16x16x32_bf16 v[18:21], v[188:191], v[220:223], v[18:21]
	v_mfma_f32_16x16x32_bf16 v[10:13], v[196:199], v[220:223], v[10:13]
	v_mfma_f32_16x16x32_bf16 v[6:9], v[188:191], v[228:231], v[6:9]
	v_mfma_f32_16x16x32_bf16 v[2:5], v[196:199], v[228:231], v[2:5]
	v_mfma_f32_16x16x32_bf16 v[50:53], v[192:195], v[208:211], v[50:53]
	v_mfma_f32_16x16x32_bf16 v[42:45], v[200:203], v[208:211], v[42:45]
	v_mfma_f32_16x16x32_bf16 v[34:37], v[192:195], v[216:219], v[34:37]
	v_mfma_f32_16x16x32_bf16 v[26:29], v[200:203], v[216:219], v[26:29]
	v_mfma_f32_16x16x32_bf16 v[18:21], v[192:195], v[224:227], v[18:21]
	v_mfma_f32_16x16x32_bf16 v[10:13], v[200:203], v[224:227], v[10:13]
	v_mfma_f32_16x16x32_bf16 v[6:9], v[192:195], v[232:235], v[6:9]
	v_mfma_f32_16x16x32_bf16 v[2:5], v[200:203], v[232:235], v[2:5]
	s_barrier
	s_setprio 0
	s_add_i32 s40, s40, 2
	s_add_u32 s38, s38, 0x100
	s_addc_u32 s39, s39, 0
	s_cmp_gt_u32 s40, 13
	s_mov_b64 s[16:17], s[18:19]
.LBB0_345:
	s_add_u32 s18, s16, 0x100
	s_addc_u32 s19, s17, 0
	s_add_i32 s41, 0, 0x10000
	s_cmp_eq_u32 s40, 12
	s_cselect_b32 s21, s7, s19
	s_cselect_b32 s20, s6, s18
	v_add_u32_e32 v168, s41, v139
	s_cselect_b32 s5, s15, s39
	s_cselect_b32 s4, s14, s38
	s_add_i32 s42, 0, 0x14000
	ds_read_b128 v[164:167], v168
	ds_read_b128 v[172:175], v168 offset:1024
	ds_read_b128 v[176:179], v168 offset:2048
	ds_read_b128 v[184:187], v168 offset:3072
	v_add_u32_e32 v168, s42, v139
	ds_read_b128 v[188:191], v168
	ds_read_b128 v[192:195], v168 offset:1024
	ds_read_b128 v[196:199], v168 offset:2048
	ds_read_b128 v[200:203], v168 offset:3072
	v_lshl_add_u64 v[168:169], s[16:17], 0, v[160:161]
	s_add_i32 m0, s25, 0xc000
	ds_read_b128 v[204:207], v171
	ds_read_b128 v[208:211], v171 offset:1024
	ds_read_b128 v[212:215], v171 offset:2048
	ds_read_b128 v[216:219], v171 offset:3072
	ds_read_b128 v[220:223], v171 offset:4096
	ds_read_b128 v[224:227], v171 offset:5120
	ds_read_b128 v[228:231], v171 offset:6144
	ds_read_b128 v[232:235], v171 offset:7168
	global_load_lds_dwordx4 v[168:169], off
	s_add_i32 m0, s25, 0xe000
	v_lshl_add_u64 v[168:169], s[16:17], 0, v[162:163]
	global_load_lds_dwordx4 v[168:169], off
	s_waitcnt vmcnt(8)
	s_waitcnt lgkmcnt(0)
	s_setprio 1
	s_barrier
; #define PG8_STAGE(bufoff, gbase, voff) do { _Pragma("unroll") for (int _i = 0; _i < 2; ++_i) \
;         __builtin_amdgcn_global_load_lds((const unsigned*)((const char*)(gbase) + (voff)[_i]), (LAS unsigned*)(lds + (bufoff) + ldsw + _i * 8192), 16, 0, 0); } while (0)
; #define PG8_LDA(dst, b, h) do { _Pragma("unroll") for (int m = 0; m < 4; ++m) _Pragma("unroll") for (int k = 0; k < 2; ++k) dst[m][k] = *(const LAS bf16x8*)(lds + PG8_SA(b, h) + aoff + m * 2048 + k * 1024); } while (0)
; #define PG8_MMA(ai, bj, At, Bt) do { __builtin_amdgcn_s_setprio(1); _Pragma("unroll") for (int m = 0; m < 4; ++m) _Pragma("unroll") for (int n = 0; n < 2; ++n) _Pragma("unroll") for (int k = 0; k < 2; ++k) \
;         acc[ai][bj][m][n] = __builtin_amdgcn_mfma_f32_16x16x32_bf16(Bt[n][k], At[m][k], acc[ai][bj][m][n], 0, 0, 0); __builtin_amdgcn_s_setprio(0); } while (0)
; #define PG8_WAIT_V(n) asm volatile("s_waitcnt vmcnt(" #n ")" ::: "memory")
; #define PG8_WAIT_L(n) asm volatile("s_waitcnt lgkmcnt(" #n ")" ::: "memory")
; #define PG8_BAR __builtin_amdgcn_s_barrier()
; #define PG8_SCHED __builtin_amdgcn_sched_barrier(0)
; template <class Epi, bool ALIGN_EPI = PG8_ALIGN, bool SP2 = PG8_SP2>
; __device__ __forceinline__ void gemm_phase(LAS uchar* lds, const Gemm g, const StaticOrder& S, const Epi& E) {
;     ...
;             PG8_WAIT_V(8); PG8_WAIT_L(0); PG8_BAR; PG8_MMA(0, 0, At, B0); PG8_MMA(0, 1, At, B1); PG8_BAR; PG8_SCHED;
;             PG8_LDA(At, 0, 1); PG8_STAGE(PG8_SB(0, 0), b2, voffB); PG8_STAGE(PG8_SB(0, 1), b2 + hstepB, voffB); PG8_STAGE(PG8_SA(0, 0), a2, voffA);
;             PG8_WAIT_V(8); PG8_WAIT_L(0); PG8_BAR; PG8_MMA(1, 0, At, B0); PG8_MMA(1, 1, At, B1); PG8_BAR; PG8_SCHED;
	v_mfma_f32_16x16x32_bf16 v[126:129], v[164:167], v[204:207], v[126:129]
	v_mfma_f32_16x16x32_bf16 v[122:125], v[176:179], v[204:207], v[122:125]
	v_mfma_f32_16x16x32_bf16 v[118:121], v[164:167], v[212:215], v[118:121]
	v_mfma_f32_16x16x32_bf16 v[110:113], v[176:179], v[212:215], v[110:113]
	v_mfma_f32_16x16x32_bf16 v[102:105], v[164:167], v[220:223], v[102:105]
	v_mfma_f32_16x16x32_bf16 v[94:97], v[176:179], v[220:223], v[94:97]
	v_mfma_f32_16x16x32_bf16 v[86:89], v[164:167], v[228:231], v[86:89]
	v_mfma_f32_16x16x32_bf16 v[78:81], v[176:179], v[228:231], v[78:81]
	v_mfma_f32_16x16x32_bf16 v[126:129], v[172:175], v[208:211], v[126:129]
	v_mfma_f32_16x16x32_bf16 v[122:125], v[184:187], v[208:211], v[122:125]
	v_mfma_f32_16x16x32_bf16 v[118:121], v[172:175], v[216:219], v[118:121]
	v_mfma_f32_16x16x32_bf16 v[110:113], v[184:187], v[216:219], v[110:113]
	v_mfma_f32_16x16x32_bf16 v[102:105], v[172:175], v[224:227], v[102:105]
	v_mfma_f32_16x16x32_bf16 v[94:97], v[184:187], v[224:227], v[94:97]
	v_mfma_f32_16x16x32_bf16 v[86:89], v[172:175], v[232:235], v[86:89]
	v_mfma_f32_16x16x32_bf16 v[78:81], v[184:187], v[232:235], v[78:81]
	v_mfma_f32_16x16x32_bf16 v[114:117], v[188:191], v[204:207], v[114:117]
	v_mfma_f32_16x16x32_bf16 v[106:109], v[196:199], v[204:207], v[106:109]
	v_mfma_f32_16x16x32_bf16 v[98:101], v[188:191], v[212:215], v[98:101]
	v_mfma_f32_16x16x32_bf16 v[90:93], v[196:199], v[212:215], v[90:93]
	v_mfma_f32_16x16x32_bf16 v[82:85], v[188:191], v[220:223], v[82:85]
	v_mfma_f32_16x16x32_bf16 v[74:77], v[196:199], v[220:223], v[74:77]
	v_mfma_f32_16x16x32_bf16 v[70:73], v[188:191], v[228:231], v[70:73]
	v_mfma_f32_16x16x32_bf16 v[66:69], v[196:199], v[228:231], v[66:69]
	v_mfma_f32_16x16x32_bf16 v[114:117], v[192:195], v[208:211], v[114:117]
	v_mfma_f32_16x16x32_bf16 v[106:109], v[200:203], v[208:211], v[106:109]
	v_mfma_f32_16x16x32_bf16 v[98:101], v[192:195], v[216:219], v[98:101]
	v_mfma_f32_16x16x32_bf16 v[90:93], v[200:203], v[216:219], v[90:93]
	v_mfma_f32_16x16x32_bf16 v[82:85], v[192:195], v[224:227], v[82:85]
	v_mfma_f32_16x16x32_bf16 v[74:77], v[200:203], v[224:227], v[74:77]
	v_mfma_f32_16x16x32_bf16 v[70:73], v[192:195], v[232:235], v[70:73]
	v_mfma_f32_16x16x32_bf16 v[66:69], v[200:203], v[232:235], v[66:69]
	s_barrier
	s_setprio 0
	s_add_i32 s16, s41, s23
	v_lshl_add_u64 v[168:169], s[4:5], 0, v[134:135]
	s_mov_b32 m0, s16
	ds_read_b128 v[204:207], v171 offset:16384
	ds_read_b128 v[208:211], v171 offset:17408
	ds_read_b128 v[212:215], v171 offset:18432
	ds_read_b128 v[216:219], v171 offset:19456
	ds_read_b128 v[220:223], v171 offset:20480
	ds_read_b128 v[224:227], v171 offset:21504
	ds_read_b128 v[228:231], v171 offset:22528
	ds_read_b128 v[232:235], v171 offset:23552
	global_load_lds_dwordx4 v[168:169], off
	s_add_i32 m0, s16, 0x2000
	s_add_u32 s16, s4, 0x44000
	v_lshl_add_u64 v[180:181], s[4:5], 0, v[130:131]
	s_addc_u32 s17, s5, 0
	s_add_i32 s41, s42, s23
	global_load_lds_dwordx4 v[180:181], off
	v_lshl_add_u64 v[236:237], s[16:17], 0, v[134:135]
	s_mov_b32 m0, s41
	global_load_lds_dwordx4 v[236:237], off
	s_add_i32 m0, s41, 0x2000
	v_lshl_add_u64 v[236:237], s[16:17], 0, v[130:131]
	global_load_lds_dwordx4 v[236:237], off
	s_mov_b32 m0, s25
	v_lshl_add_u64 v[236:237], s[20:21], 0, v[156:157]
	global_load_lds_dwordx4 v[236:237], off
	s_mov_b32 m0, s26
	v_lshl_add_u64 v[238:239], s[20:21], 0, v[132:133]
	global_load_lds_dwordx4 v[238:239], off
	s_waitcnt vmcnt(8)
	s_waitcnt lgkmcnt(0)
	s_setprio 1
	s_barrier
	v_mfma_f32_16x16x32_bf16 v[62:65], v[164:167], v[204:207], v[62:65]
	v_mfma_f32_16x16x32_bf16 v[58:61], v[176:179], v[204:207], v[58:61]
	v_mfma_f32_16x16x32_bf16 v[54:57], v[164:167], v[212:215], v[54:57]
	v_mfma_f32_16x16x32_bf16 v[46:49], v[176:179], v[212:215], v[46:49]
	v_mfma_f32_16x16x32_bf16 v[38:41], v[164:167], v[220:223], v[38:41]
	v_mfma_f32_16x16x32_bf16 v[30:33], v[176:179], v[220:223], v[30:33]
	v_mfma_f32_16x16x32_bf16 v[22:25], v[164:167], v[228:231], v[22:25]
	v_mfma_f32_16x16x32_bf16 v[14:17], v[176:179], v[228:231], v[14:17]
	v_mfma_f32_16x16x32_bf16 v[62:65], v[172:175], v[208:211], v[62:65]
	v_mfma_f32_16x16x32_bf16 v[58:61], v[184:187], v[208:211], v[58:61]
	v_mfma_f32_16x16x32_bf16 v[54:57], v[172:175], v[216:219], v[54:57]
	v_mfma_f32_16x16x32_bf16 v[46:49], v[184:187], v[216:219], v[46:49]
	v_mfma_f32_16x16x32_bf16 v[38:41], v[172:175], v[224:227], v[38:41]
	v_mfma_f32_16x16x32_bf16 v[30:33], v[184:187], v[224:227], v[30:33]
	v_mfma_f32_16x16x32_bf16 v[22:25], v[172:175], v[232:235], v[22:25]
	v_mfma_f32_16x16x32_bf16 v[14:17], v[184:187], v[232:235], v[14:17]
	v_mfma_f32_16x16x32_bf16 v[50:53], v[188:191], v[204:207], v[50:53]
	v_mfma_f32_16x16x32_bf16 v[42:45], v[196:199], v[204:207], v[42:45]
	v_mfma_f32_16x16x32_bf16 v[34:37], v[188:191], v[212:215], v[34:37]
	v_mfma_f32_16x16x32_bf16 v[26:29], v[196:199], v[212:215], v[26:29]
	v_mfma_f32_16x16x32_bf16 v[18:21], v[188:191], v[220:223], v[18:21]
	v_mfma_f32_16x16x32_bf16 v[10:13], v[196:199], v[220:223], v[10:13]
	v_mfma_f32_16x16x32_bf16 v[6:9], v[188:191], v[228:231], v[6:9]
	v_mfma_f32_16x16x32_bf16 v[2:5], v[196:199], v[228:231], v[2:5]
	v_mfma_f32_16x16x32_bf16 v[50:53], v[192:195], v[208:211], v[50:53]
	v_mfma_f32_16x16x32_bf16 v[42:45], v[200:203], v[208:211], v[42:45]
	v_mfma_f32_16x16x32_bf16 v[34:37], v[192:195], v[216:219], v[34:37]
	v_mfma_f32_16x16x32_bf16 v[26:29], v[200:203], v[216:219], v[26:29]
	v_mfma_f32_16x16x32_bf16 v[18:21], v[192:195], v[224:227], v[18:21]
	v_mfma_f32_16x16x32_bf16 v[10:13], v[200:203], v[224:227], v[10:13]
	v_mfma_f32_16x16x32_bf16 v[6:9], v[192:195], v[232:235], v[6:9]
	v_mfma_f32_16x16x32_bf16 v[2:5], v[200:203], v[232:235], v[2:5]
	s_barrier
; #define PG8_STAGE(bufoff, gbase, voff) do { _Pragma("unroll") for (int _i = 0; _i < 2; ++_i) \
;         __builtin_amdgcn_global_load_lds((const unsigned*)((const char*)(gbase) + (voff)[_i]), (LAS unsigned*)(lds + (bufoff) + ldsw + _i * 8192), 16, 0, 0); } while (0)
; #define PG8_LDA(dst, b, h) do { _Pragma("unroll") for (int m = 0; m < 4; ++m) _Pragma("unroll") for (int k = 0; k < 2; ++k) dst[m][k] = *(const LAS bf16x8*)(lds + PG8_SA(b, h) + aoff + m * 2048 + k * 1024); } while (0)
; #define PG8_LDB(dst, b, h) do { _Pragma("unroll") for (int n = 0; n < 2; ++n) _Pragma("unroll") for (int k = 0; k < 2; ++k) dst[n][k] = *(const LAS bf16x8*)(lds + PG8_SB(b, h) + boff + n * 2048 + k * 1024); } while (0)
; #define PG8_MMA(ai, bj, At, Bt) do { __builtin_amdgcn_s_setprio(1); _Pragma("unroll") for (int m = 0; m < 4; ++m) _Pragma("unroll") for (int n = 0; n < 2; ++n) _Pragma("unroll") for (int k = 0; k < 2; ++k) \
;         acc[ai][bj][m][n] = __builtin_amdgcn_mfma_f32_16x16x32_bf16(Bt[n][k], At[m][k], acc[ai][bj][m][n], 0, 0, 0); __builtin_amdgcn_s_setprio(0); } while (0)
; #define PG8_WAIT_V(n) asm volatile("s_waitcnt vmcnt(" #n ")" ::: "memory")
; #define PG8_WAIT_L(n) asm volatile("s_waitcnt lgkmcnt(" #n ")" ::: "memory")
; #define PG8_BAR __builtin_amdgcn_s_barrier()
; #define PG8_SCHED __builtin_amdgcn_sched_barrier(0)
; template <class Epi, bool ALIGN_EPI = PG8_ALIGN, bool SP2 = PG8_SP2>
; __device__ __forceinline__ void gemm_phase(LAS uchar* lds, const Gemm g, const StaticOrder& S, const Epi& E) {
;     ...
;             PG8_LDB(B0, 1, 0); PG8_LDB(B1, 1, 1); PG8_SCHED; PG8_LDA(At, 1, 0); PG8_STAGE(PG8_SA(0, 1), a2 + hstepA, voffA);
;             PG8_WAIT_V(8); PG8_WAIT_L(0); PG8_BAR; PG8_MMA(0, 0, At, B0); PG8_MMA(0, 1, At, B1); PG8_BAR; PG8_SCHED;
	s_setprio 0
	s_add_i32 s41, 0, 0x18000
	s_add_i32 s42, 0, 0x1c000
	v_add_u32_e32 v184, s41, v139
	v_add_u32_e32 v200, s42, v139
	ds_read_b128 v[164:167], v184
	ds_read_b128 v[172:175], v184 offset:1024
	ds_read_b128 v[176:179], v184 offset:2048
	ds_read_b128 v[184:187], v184 offset:3072
	ds_read_b128 v[188:191], v200
	ds_read_b128 v[192:195], v200 offset:1024
	ds_read_b128 v[196:199], v200 offset:2048
	ds_read_b128 v[200:203], v200 offset:3072
	s_add_u32 s16, s20, 0x44000
	s_addc_u32 s17, s21, 0
	s_mov_b32 m0, s27
	v_lshl_add_u64 v[240:241], s[16:17], 0, v[156:157]
	ds_read_b128 v[204:207], v171 offset:32768
	ds_read_b128 v[208:211], v171 offset:33792
	ds_read_b128 v[212:215], v171 offset:34816
	ds_read_b128 v[216:219], v171 offset:35840
	ds_read_b128 v[220:223], v171 offset:36864
	ds_read_b128 v[224:227], v171 offset:37888
	ds_read_b128 v[228:231], v171 offset:38912
	ds_read_b128 v[232:235], v171 offset:39936
	global_load_lds_dwordx4 v[240:241], off
	s_mov_b32 m0, s28
	v_lshl_add_u64 v[240:241], s[16:17], 0, v[132:133]
	global_load_lds_dwordx4 v[240:241], off
	s_waitcnt vmcnt(8)
	s_waitcnt lgkmcnt(0)
	s_setprio 1
	s_barrier
	v_mfma_f32_16x16x32_bf16 v[126:129], v[164:167], v[204:207], v[126:129]
	v_mfma_f32_16x16x32_bf16 v[122:125], v[176:179], v[204:207], v[122:125]
	v_mfma_f32_16x16x32_bf16 v[118:121], v[164:167], v[212:215], v[118:121]
	v_mfma_f32_16x16x32_bf16 v[110:113], v[176:179], v[212:215], v[110:113]
	v_mfma_f32_16x16x32_bf16 v[102:105], v[164:167], v[220:223], v[102:105]
	v_mfma_f32_16x16x32_bf16 v[94:97], v[176:179], v[220:223], v[94:97]
	v_mfma_f32_16x16x32_bf16 v[86:89], v[164:167], v[228:231], v[86:89]
	v_mfma_f32_16x16x32_bf16 v[78:81], v[176:179], v[228:231], v[78:81]
	v_mfma_f32_16x16x32_bf16 v[126:129], v[172:175], v[208:211], v[126:129]
	v_mfma_f32_16x16x32_bf16 v[122:125], v[184:187], v[208:211], v[122:125]
	v_mfma_f32_16x16x32_bf16 v[118:121], v[172:175], v[216:219], v[118:121]
	v_mfma_f32_16x16x32_bf16 v[110:113], v[184:187], v[216:219], v[110:113]
	v_mfma_f32_16x16x32_bf16 v[102:105], v[172:175], v[224:227], v[102:105]
	v_mfma_f32_16x16x32_bf16 v[94:97], v[184:187], v[224:227], v[94:97]
	v_mfma_f32_16x16x32_bf16 v[86:89], v[172:175], v[232:235], v[86:89]
	v_mfma_f32_16x16x32_bf16 v[78:81], v[184:187], v[232:235], v[78:81]
	v_mfma_f32_16x16x32_bf16 v[114:117], v[188:191], v[204:207], v[114:117]
	v_mfma_f32_16x16x32_bf16 v[106:109], v[196:199], v[204:207], v[106:109]
	v_mfma_f32_16x16x32_bf16 v[98:101], v[188:191], v[212:215], v[98:101]
	v_mfma_f32_16x16x32_bf16 v[90:93], v[196:199], v[212:215], v[90:93]
	v_mfma_f32_16x16x32_bf16 v[82:85], v[188:191], v[220:223], v[82:85]
	v_mfma_f32_16x16x32_bf16 v[74:77], v[196:199], v[220:223], v[74:77]
	v_mfma_f32_16x16x32_bf16 v[70:73], v[188:191], v[228:231], v[70:73]
	v_mfma_f32_16x16x32_bf16 v[66:69], v[196:199], v[228:231], v[66:69]
	v_mfma_f32_16x16x32_bf16 v[114:117], v[192:195], v[208:211], v[114:117]
	v_mfma_f32_16x16x32_bf16 v[106:109], v[200:203], v[208:211], v[106:109]
	v_mfma_f32_16x16x32_bf16 v[98:101], v[192:195], v[216:219], v[98:101]
	v_mfma_f32_16x16x32_bf16 v[90:93], v[200:203], v[216:219], v[90:93]
	v_mfma_f32_16x16x32_bf16 v[82:85], v[192:195], v[224:227], v[82:85]
	v_mfma_f32_16x16x32_bf16 v[74:77], v[200:203], v[224:227], v[74:77]
	v_mfma_f32_16x16x32_bf16 v[70:73], v[192:195], v[232:235], v[70:73]
	v_mfma_f32_16x16x32_bf16 v[66:69], v[200:203], v[232:235], v[66:69]
	s_barrier
; #define PG8_STAGE(bufoff, gbase, voff) do { _Pragma("unroll") for (int _i = 0; _i < 2; ++_i) \
;         __builtin_amdgcn_global_load_lds((const unsigned*)((const char*)(gbase) + (voff)[_i]), (LAS unsigned*)(lds + (bufoff) + ldsw + _i * 8192), 16, 0, 0); } while (0)
; #define PG8_LDA(dst, b, h) do { _Pragma("unroll") for (int m = 0; m < 4; ++m) _Pragma("unroll") for (int k = 0; k < 2; ++k) dst[m][k] = *(const LAS bf16x8*)(lds + PG8_SA(b, h) + aoff + m * 2048 + k * 1024); } while (0)
; #define PG8_MMA(ai, bj, At, Bt) do { __builtin_amdgcn_s_setprio(1); _Pragma("unroll") for (int m = 0; m < 4; ++m) _Pragma("unroll") for (int n = 0; n < 2; ++n) _Pragma("unroll") for (int k = 0; k < 2; ++k) \
;         acc[ai][bj][m][n] = __builtin_amdgcn_mfma_f32_16x16x32_bf16(Bt[n][k], At[m][k], acc[ai][bj][m][n], 0, 0, 0); __builtin_amdgcn_s_setprio(0); } while (0)
; #define PG8_WAIT_V(n) asm volatile("s_waitcnt vmcnt(" #n ")" ::: "memory")
; #define PG8_WAIT_L(n) asm volatile("s_waitcnt lgkmcnt(" #n ")" ::: "memory")
; #define PG8_BAR __builtin_amdgcn_s_barrier()
; #define PG8_SCHED __builtin_amdgcn_sched_barrier(0)
; template <class Epi, bool ALIGN_EPI = PG8_ALIGN, bool SP2 = PG8_SP2>
; __device__ __forceinline__ void gemm_phase(LAS uchar* lds, const Gemm g, const StaticOrder& S, const Epi& E) {
;     ...
;             PG8_LDA(At, 1, 1); PG8_STAGE(PG8_SB(1, 0), b3, voffB); PG8_STAGE(PG8_SB(1, 1), b3 + hstepB, voffB); PG8_STAGE(PG8_SA(1, 0), a3, voffA);
;             PG8_WAIT_V(8); PG8_WAIT_L(0); PG8_BAR; PG8_MMA(1, 0, At, B0); PG8_MMA(1, 1, At, B1); PG8_BAR; PG8_SCHED;
;     __device__ __forceinline__ void operator()(const f32x4 (&acc)[2][2][4][2], const pg8::Unit& u, int wr, int wc, int fr, int fq, int) const {
;         const int row0 = u.pm * 256 + wr * 64 + fr;
;         if (u.pn < 24) {
	s_setprio 0
	s_add_i32 s16, s41, s23
	v_lshl_add_u64 v[168:169], v[168:169], 0, s[84:85]
	s_mov_b32 m0, s16
	ds_read_b128 v[204:207], v171 offset:49152
	ds_read_b128 v[208:211], v171 offset:50176
	ds_read_b128 v[212:215], v171 offset:51200
	ds_read_b128 v[216:219], v171 offset:52224
	ds_read_b128 v[220:223], v171 offset:53248
	ds_read_b128 v[224:227], v171 offset:54272
	ds_read_b128 v[228:231], v171 offset:55296
	ds_read_b128 v[232:235], v171 offset:56320
	global_load_lds_dwordx4 v[168:169], off
	s_add_i32 m0, s16, 0x2000
	s_add_u32 s4, s4, 0x44080
	v_lshl_add_u64 v[168:169], v[180:181], 0, s[84:85]
	s_addc_u32 s5, s5, 0
	s_add_i32 s16, s42, s23
	global_load_lds_dwordx4 v[168:169], off
	s_mov_b32 m0, s16
	v_lshl_add_u64 v[168:169], s[4:5], 0, v[134:135]
	global_load_lds_dwordx4 v[168:169], off
	s_add_i32 m0, s16, 0x2000
	v_lshl_add_u64 v[168:169], s[4:5], 0, v[130:131]
	global_load_lds_dwordx4 v[168:169], off
	s_mov_b32 m0, s29
	v_lshl_add_u64 v[168:169], v[236:237], 0, s[84:85]
	global_load_lds_dwordx4 v[168:169], off
	s_mov_b32 m0, s30
	v_lshl_add_u64 v[168:169], v[238:239], 0, s[84:85]
	global_load_lds_dwordx4 v[168:169], off
	s_waitcnt vmcnt(8)
	s_waitcnt lgkmcnt(0)
	s_setprio 1
	s_barrier
	v_mfma_f32_16x16x32_bf16 v[62:65], v[164:167], v[204:207], v[62:65]
	v_mfma_f32_16x16x32_bf16 v[58:61], v[176:179], v[204:207], v[58:61]
	v_mfma_f32_16x16x32_bf16 v[54:57], v[164:167], v[212:215], v[54:57]
	v_mfma_f32_16x16x32_bf16 v[46:49], v[176:179], v[212:215], v[46:49]
	v_mfma_f32_16x16x32_bf16 v[38:41], v[164:167], v[220:223], v[38:41]
	v_mfma_f32_16x16x32_bf16 v[30:33], v[176:179], v[220:223], v[30:33]
	v_mfma_f32_16x16x32_bf16 v[22:25], v[164:167], v[228:231], v[22:25]
	v_mfma_f32_16x16x32_bf16 v[14:17], v[176:179], v[228:231], v[14:17]
	v_mfma_f32_16x16x32_bf16 v[62:65], v[172:175], v[208:211], v[62:65]
	v_mfma_f32_16x16x32_bf16 v[58:61], v[184:187], v[208:211], v[58:61]
	v_mfma_f32_16x16x32_bf16 v[54:57], v[172:175], v[216:219], v[54:57]
	v_mfma_f32_16x16x32_bf16 v[46:49], v[184:187], v[216:219], v[46:49]
	v_mfma_f32_16x16x32_bf16 v[38:41], v[172:175], v[224:227], v[38:41]
	v_mfma_f32_16x16x32_bf16 v[30:33], v[184:187], v[224:227], v[30:33]
	v_mfma_f32_16x16x32_bf16 v[22:25], v[172:175], v[232:235], v[22:25]
	v_mfma_f32_16x16x32_bf16 v[14:17], v[184:187], v[232:235], v[14:17]
	v_mfma_f32_16x16x32_bf16 v[50:53], v[188:191], v[204:207], v[50:53]
	v_mfma_f32_16x16x32_bf16 v[42:45], v[196:199], v[204:207], v[42:45]
	v_mfma_f32_16x16x32_bf16 v[34:37], v[188:191], v[212:215], v[34:37]
	v_mfma_f32_16x16x32_bf16 v[26:29], v[196:199], v[212:215], v[26:29]
	v_mfma_f32_16x16x32_bf16 v[18:21], v[188:191], v[220:223], v[18:21]
	v_mfma_f32_16x16x32_bf16 v[10:13], v[196:199], v[220:223], v[10:13]
	v_mfma_f32_16x16x32_bf16 v[6:9], v[188:191], v[228:231], v[6:9]
	v_mfma_f32_16x16x32_bf16 v[2:5], v[196:199], v[228:231], v[2:5]
	v_mfma_f32_16x16x32_bf16 v[50:53], v[192:195], v[208:211], v[50:53]
	v_mfma_f32_16x16x32_bf16 v[42:45], v[200:203], v[208:211], v[42:45]
	v_mfma_f32_16x16x32_bf16 v[34:37], v[192:195], v[216:219], v[34:37]
	v_mfma_f32_16x16x32_bf16 v[26:29], v[200:203], v[216:219], v[26:29]
	v_mfma_f32_16x16x32_bf16 v[18:21], v[192:195], v[224:227], v[18:21]
	v_mfma_f32_16x16x32_bf16 v[10:13], v[200:203], v[224:227], v[10:13]
	v_mfma_f32_16x16x32_bf16 v[6:9], v[192:195], v[232:235], v[6:9]
	v_mfma_f32_16x16x32_bf16 v[2:5], v[200:203], v[232:235], v[2:5]
	s_barrier
	s_setprio 0
	s_add_i32 s40, s40, 2
	s_add_u32 s38, s38, 0x100
	s_addc_u32 s39, s39, 0
	s_cmp_gt_u32 s40, 13
	s_mov_b64 s[16:17], s[18:19]
	s_cbranch_scc0 .LBB0_345
	s_mov_b32 s97, 0
	s_and_b64 vcc, exec, s[10:11]
	s_cbranch_vccnz .LBB0_350
	v_lshl_add_u32 v164, s37, 8, v1
	s_cmp_gt_i32 s36, 23
	s_mov_b64 s[4:5], -1
	s_cbranch_scc1 .LBB0_351

; #define PG8_STAGE(bufoff, gbase, voff) do { _Pragma("unroll") for (int _i = 0; _i < 2; ++_i) \
;         __builtin_amdgcn_global_load_lds((const unsigned*)((const char*)(gbase) + (voff)[_i]), (LAS unsigned*)(lds + (bufoff) + ldsw + _i * 8192), 16, 0, 0); } while (0)
; #define PG8_LDA(dst, b, h) do { _Pragma("unroll") for (int m = 0; m < 4; ++m) _Pragma("unroll") for (int k = 0; k < 2; ++k) dst[m][k] = *(const LAS bf16x8*)(lds + PG8_SA(b, h) + aoff + m * 2048 + k * 1024); } while (0)
; #define PG8_LDB(dst, b, h) do { _Pragma("unroll") for (int n = 0; n < 2; ++n) _Pragma("unroll") for (int k = 0; k < 2; ++k) dst[n][k] = *(const LAS bf16x8*)(lds + PG8_SB(b, h) + boff + n * 2048 + k * 1024); } while (0)
; #define PG8_MMA(ai, bj, At, Bt) do { __builtin_amdgcn_s_setprio(1); _Pragma("unroll") for (int m = 0; m < 4; ++m) _Pragma("unroll") for (int n = 0; n < 2; ++n) _Pragma("unroll") for (int k = 0; k < 2; ++k) \
;         acc[ai][bj][m][n] = __builtin_amdgcn_mfma_f32_16x16x32_bf16(Bt[n][k], At[m][k], acc[ai][bj][m][n], 0, 0, 0); __builtin_amdgcn_s_setprio(0); } while (0)
; #define PG8_WAIT_V(n) asm volatile("s_waitcnt vmcnt(" #n ")" ::: "memory")
; #define PG8_WAIT_L(n) asm volatile("s_waitcnt lgkmcnt(" #n ")" ::: "memory")
; #define PG8_BAR __builtin_amdgcn_s_barrier()
; #define PG8_SCHED __builtin_amdgcn_sched_barrier(0)
; template <class Epi, bool ALIGN_EPI = PG8_ALIGN, bool SP2 = PG8_SP2>
; __device__ __forceinline__ void gemm_phase(LAS uchar* lds, const Gemm g, const StaticOrder& S, const Epi& E) {
;     ...
;         for (int t = tb; t < tb + tblk; t += 2) {
;             const bool last = (t == nt - 2);
;             const char* a1 = cA + (size_t)(t + 1) * kstep;
;             const char* a2 = last ? nA : cA + (size_t)(t + 2) * kstep; const char* b2 = last ? nB : cB + (size_t)(t + 2) * kstep;
;             const char* a3 = a2 + kstep; const char* b3 = b2 + kstep;
;             if constexpr (SP2) {
;             PG8_LDB(B0, 0, 0); PG8_LDB(B1, 0, 1); PG8_SCHED; PG8_LDA(At, 0, 0); PG8_STAGE(PG8_SA(1, 1), a1 + hstepA, voffA);
;             PG8_WAIT_V(8); PG8_WAIT_L(0); PG8_BAR; PG8_MMA(0, 0, At, B0); PG8_MMA(0, 1, At, B1); PG8_BAR; PG8_SCHED;
;             PG8_LDA(At, 0, 1); PG8_STAGE(PG8_SB(0, 0), b2, voffB); PG8_STAGE(PG8_SB(0, 1), b2 + hstepB, voffB); PG8_STAGE(PG8_SA(0, 0), a2, voffA);
.LBB0_580:
	s_add_i32 s42, s42, 2
	s_add_u32 s4, s14, s18
	s_addc_u32 s5, s15, s19
	s_add_u32 s4, s4, 0x100
	s_addc_u32 s5, s5, 0
	s_add_u32 s43, s38, s18
	s_addc_u32 s44, s39, s19
	s_add_i32 s45, 0, 0x10000
	s_cmpk_eq_i32 s18, 0xf00
	s_cselect_b32 s21, s1, s5
	s_cselect_b32 s20, s0, s4
	v_add_u32_e32 v1, s45, v168
	s_cselect_b32 s5, s13, s44
	s_cselect_b32 s4, s12, s43
	s_add_i32 s43, 0, 0x14000
	ds_read_b128 v[174:177], v1
	ds_read_b128 v[178:181], v1 offset:1024
	ds_read_b128 v[184:187], v1 offset:2048
	ds_read_b128 v[188:191], v1 offset:3072
	v_add_u32_e32 v1, s43, v168
	ds_read_b128 v[192:195], v1
	ds_read_b128 v[196:199], v1 offset:1024
	ds_read_b128 v[200:203], v1 offset:2048
	ds_read_b128 v[204:207], v1 offset:3072
	v_lshl_add_u64 v[2:3], v[164:165], 0, s[18:19]
	s_add_i32 m0, s25, 0xc000
	ds_read_b128 v[208:211], v170
	ds_read_b128 v[212:215], v170 offset:1024
	ds_read_b128 v[216:219], v170 offset:2048
	ds_read_b128 v[220:223], v170 offset:3072
	ds_read_b128 v[224:227], v170 offset:4096
	ds_read_b128 v[228:231], v170 offset:5120
	ds_read_b128 v[232:235], v170 offset:6144
	ds_read_b128 v[236:239], v170 offset:7168
	global_load_lds_dwordx4 v[2:3], off
	s_add_i32 m0, s25, 0xe000
	v_lshl_add_u64 v[2:3], v[166:167], 0, s[18:19]
	global_load_lds_dwordx4 v[2:3], off
	s_waitcnt vmcnt(8)
	s_waitcnt lgkmcnt(0)
	s_setprio 1
	s_barrier
	v_mfma_f32_16x16x32_bf16 v[128:131], v[174:177], v[208:211], v[128:131]
	v_mfma_f32_16x16x32_bf16 v[124:127], v[184:187], v[208:211], v[124:127]
	v_mfma_f32_16x16x32_bf16 v[112:115], v[174:177], v[216:219], v[112:115]
	v_mfma_f32_16x16x32_bf16 v[108:111], v[184:187], v[216:219], v[108:111]
	v_mfma_f32_16x16x32_bf16 v[96:99], v[174:177], v[224:227], v[96:99]
	v_mfma_f32_16x16x32_bf16 v[92:95], v[184:187], v[224:227], v[92:95]
	v_mfma_f32_16x16x32_bf16 v[80:83], v[174:177], v[232:235], v[80:83]
	v_mfma_f32_16x16x32_bf16 v[76:79], v[184:187], v[232:235], v[76:79]
	v_mfma_f32_16x16x32_bf16 v[128:131], v[178:181], v[212:215], v[128:131]
	v_mfma_f32_16x16x32_bf16 v[124:127], v[188:191], v[212:215], v[124:127]
	v_mfma_f32_16x16x32_bf16 v[112:115], v[178:181], v[220:223], v[112:115]
	v_mfma_f32_16x16x32_bf16 v[108:111], v[188:191], v[220:223], v[108:111]
	v_mfma_f32_16x16x32_bf16 v[96:99], v[178:181], v[228:231], v[96:99]
	v_mfma_f32_16x16x32_bf16 v[92:95], v[188:191], v[228:231], v[92:95]
	v_mfma_f32_16x16x32_bf16 v[80:83], v[178:181], v[236:239], v[80:83]
	v_mfma_f32_16x16x32_bf16 v[76:79], v[188:191], v[236:239], v[76:79]
	v_mfma_f32_16x16x32_bf16 v[120:123], v[192:195], v[208:211], v[120:123]
	v_mfma_f32_16x16x32_bf16 v[116:119], v[200:203], v[208:211], v[116:119]
	v_mfma_f32_16x16x32_bf16 v[104:107], v[192:195], v[216:219], v[104:107]
	v_mfma_f32_16x16x32_bf16 v[100:103], v[200:203], v[216:219], v[100:103]
	v_mfma_f32_16x16x32_bf16 v[88:91], v[192:195], v[224:227], v[88:91]
	v_mfma_f32_16x16x32_bf16 v[84:87], v[200:203], v[224:227], v[84:87]
	v_mfma_f32_16x16x32_bf16 v[72:75], v[192:195], v[232:235], v[72:75]
	v_mfma_f32_16x16x32_bf16 v[68:71], v[200:203], v[232:235], v[68:71]
	v_mfma_f32_16x16x32_bf16 v[120:123], v[196:199], v[212:215], v[120:123]
	v_mfma_f32_16x16x32_bf16 v[116:119], v[204:207], v[212:215], v[116:119]
	v_mfma_f32_16x16x32_bf16 v[104:107], v[196:199], v[220:223], v[104:107]
	v_mfma_f32_16x16x32_bf16 v[100:103], v[204:207], v[220:223], v[100:103]
	v_mfma_f32_16x16x32_bf16 v[88:91], v[196:199], v[228:231], v[88:91]
	v_mfma_f32_16x16x32_bf16 v[84:87], v[204:207], v[228:231], v[84:87]
	v_mfma_f32_16x16x32_bf16 v[72:75], v[196:199], v[236:239], v[72:75]
	v_mfma_f32_16x16x32_bf16 v[68:71], v[204:207], v[236:239], v[68:71]
	s_barrier
	s_setprio 0
	s_add_i32 s44, s45, s24
	v_lshl_add_u64 v[240:241], s[4:5], 0, v[134:135]
	s_mov_b32 m0, s44
	ds_read_b128 v[208:211], v170 offset:16384
	ds_read_b128 v[212:215], v170 offset:17408
	ds_read_b128 v[216:219], v170 offset:18432
	ds_read_b128 v[220:223], v170 offset:19456
	ds_read_b128 v[224:227], v170 offset:20480
	ds_read_b128 v[228:231], v170 offset:21504
	ds_read_b128 v[232:235], v170 offset:22528
	ds_read_b128 v[236:239], v170 offset:23552
	global_load_lds_dwordx4 v[240:241], off
	s_add_i32 m0, s44, 0x2000
	s_add_u32 s44, s4, 0x84000
	v_lshl_add_u64 v[242:243], s[4:5], 0, v[158:159]
	s_addc_u32 s45, s5, 0
	s_add_i32 s43, s43, s24
	global_load_lds_dwordx4 v[242:243], off
	v_lshl_add_u64 v[2:3], s[44:45], 0, v[134:135]
	s_mov_b32 m0, s43
	global_load_lds_dwordx4 v[2:3], off
	v_lshl_add_u64 v[2:3], s[44:45], 0, v[158:159]
	s_add_i32 m0, s43, 0x2000
	global_load_lds_dwordx4 v[2:3], off
	s_mov_b32 m0, s25
	v_lshl_add_u64 v[244:245], s[20:21], 0, v[132:133]
	global_load_lds_dwordx4 v[244:245], off
	s_mov_b32 m0, s26
	v_lshl_add_u64 v[246:247], s[20:21], 0, v[156:157]
	global_load_lds_dwordx4 v[246:247], off
	s_waitcnt vmcnt(8)
	s_waitcnt lgkmcnt(0)
	s_setprio 1
	s_barrier
; #define PG8_STAGE(bufoff, gbase, voff) do { _Pragma("unroll") for (int _i = 0; _i < 2; ++_i) \
;         __builtin_amdgcn_global_load_lds((const unsigned*)((const char*)(gbase) + (voff)[_i]), (LAS unsigned*)(lds + (bufoff) + ldsw + _i * 8192), 16, 0, 0); } while (0)
; #define PG8_LDA(dst, b, h) do { _Pragma("unroll") for (int m = 0; m < 4; ++m) _Pragma("unroll") for (int k = 0; k < 2; ++k) dst[m][k] = *(const LAS bf16x8*)(lds + PG8_SA(b, h) + aoff + m * 2048 + k * 1024); } while (0)
; #define PG8_LDB(dst, b, h) do { _Pragma("unroll") for (int n = 0; n < 2; ++n) _Pragma("unroll") for (int k = 0; k < 2; ++k) dst[n][k] = *(const LAS bf16x8*)(lds + PG8_SB(b, h) + boff + n * 2048 + k * 1024); } while (0)
; #define PG8_MMA(ai, bj, At, Bt) do { __builtin_amdgcn_s_setprio(1); _Pragma("unroll") for (int m = 0; m < 4; ++m) _Pragma("unroll") for (int n = 0; n < 2; ++n) _Pragma("unroll") for (int k = 0; k < 2; ++k) \
;         acc[ai][bj][m][n] = __builtin_amdgcn_mfma_f32_16x16x32_bf16(Bt[n][k], At[m][k], acc[ai][bj][m][n], 0, 0, 0); __builtin_amdgcn_s_setprio(0); } while (0)
; #define PG8_WAIT_V(n) asm volatile("s_waitcnt vmcnt(" #n ")" ::: "memory")
; #define PG8_WAIT_L(n) asm volatile("s_waitcnt lgkmcnt(" #n ")" ::: "memory")
; #define PG8_BAR __builtin_amdgcn_s_barrier()
; #define PG8_SCHED __builtin_amdgcn_sched_barrier(0)
; template <class Epi, bool ALIGN_EPI = PG8_ALIGN, bool SP2 = PG8_SP2>
; __device__ __forceinline__ void gemm_phase(LAS uchar* lds, const Gemm g, const StaticOrder& S, const Epi& E) {
;     ...
;             PG8_WAIT_V(8); PG8_WAIT_L(0); PG8_BAR; PG8_MMA(1, 0, At, B0); PG8_MMA(1, 1, At, B1); PG8_BAR; PG8_SCHED;
;             PG8_LDB(B0, 1, 0); PG8_LDB(B1, 1, 1); PG8_SCHED; PG8_LDA(At, 1, 0); PG8_STAGE(PG8_SA(0, 1), a2 + hstepA, voffA);
;             PG8_WAIT_V(8); PG8_WAIT_L(0); PG8_BAR; PG8_MMA(0, 0, At, B0); PG8_MMA(0, 1, At, B1); PG8_BAR; PG8_SCHED;
	v_mfma_f32_16x16x32_bf16 v[64:67], v[174:177], v[208:211], v[64:67]
	v_mfma_f32_16x16x32_bf16 v[60:63], v[184:187], v[208:211], v[60:63]
	v_mfma_f32_16x16x32_bf16 v[48:51], v[174:177], v[216:219], v[48:51]
	v_mfma_f32_16x16x32_bf16 v[44:47], v[184:187], v[216:219], v[44:47]
	v_mfma_f32_16x16x32_bf16 v[32:35], v[174:177], v[224:227], v[32:35]
	v_mfma_f32_16x16x32_bf16 v[28:31], v[184:187], v[224:227], v[28:31]
	v_mfma_f32_16x16x32_bf16 v[16:19], v[174:177], v[232:235], v[16:19]
	v_mfma_f32_16x16x32_bf16 v[12:15], v[184:187], v[232:235], v[12:15]
	v_mfma_f32_16x16x32_bf16 v[64:67], v[178:181], v[212:215], v[64:67]
	v_mfma_f32_16x16x32_bf16 v[60:63], v[188:191], v[212:215], v[60:63]
	v_mfma_f32_16x16x32_bf16 v[48:51], v[178:181], v[220:223], v[48:51]
	v_mfma_f32_16x16x32_bf16 v[44:47], v[188:191], v[220:223], v[44:47]
	v_mfma_f32_16x16x32_bf16 v[32:35], v[178:181], v[228:231], v[32:35]
	v_mfma_f32_16x16x32_bf16 v[28:31], v[188:191], v[228:231], v[28:31]
	v_mfma_f32_16x16x32_bf16 v[16:19], v[178:181], v[236:239], v[16:19]
	v_mfma_f32_16x16x32_bf16 v[12:15], v[188:191], v[236:239], v[12:15]
	v_mfma_f32_16x16x32_bf16 v[56:59], v[192:195], v[208:211], v[56:59]
	v_mfma_f32_16x16x32_bf16 v[52:55], v[200:203], v[208:211], v[52:55]
	v_mfma_f32_16x16x32_bf16 v[40:43], v[192:195], v[216:219], v[40:43]
	v_mfma_f32_16x16x32_bf16 v[36:39], v[200:203], v[216:219], v[36:39]
	v_mfma_f32_16x16x32_bf16 v[24:27], v[192:195], v[224:227], v[24:27]
	v_mfma_f32_16x16x32_bf16 v[20:23], v[200:203], v[224:227], v[20:23]
	v_mfma_f32_16x16x32_bf16 v[8:11], v[192:195], v[232:235], v[8:11]
	v_mfma_f32_16x16x32_bf16 v[2:5], v[200:203], v[232:235], v[4:7]
	v_mfma_f32_16x16x32_bf16 v[56:59], v[196:199], v[212:215], v[56:59]
	v_mfma_f32_16x16x32_bf16 v[52:55], v[204:207], v[212:215], v[52:55]
	v_mfma_f32_16x16x32_bf16 v[40:43], v[196:199], v[220:223], v[40:43]
	v_mfma_f32_16x16x32_bf16 v[36:39], v[204:207], v[220:223], v[36:39]
	v_mfma_f32_16x16x32_bf16 v[24:27], v[196:199], v[228:231], v[24:27]
	v_mfma_f32_16x16x32_bf16 v[20:23], v[204:207], v[228:231], v[20:23]
	v_mfma_f32_16x16x32_bf16 v[8:11], v[196:199], v[236:239], v[8:11]
	v_mfma_f32_16x16x32_bf16 v[2:5], v[204:207], v[236:239], v[2:5]
	s_barrier
	s_setprio 0
	s_add_i32 s43, 0, 0x18000
	v_add_u32_e32 v1, s43, v168
	s_add_i32 s44, 0, 0x1c000
	ds_read_b128 v[174:177], v1
	ds_read_b128 v[178:181], v1 offset:1024
	ds_read_b128 v[184:187], v1 offset:2048
	ds_read_b128 v[188:191], v1 offset:3072
	v_add_u32_e32 v1, s44, v168
	ds_read_b128 v[192:195], v1
	ds_read_b128 v[196:199], v1 offset:1024
	ds_read_b128 v[200:203], v1 offset:2048
	ds_read_b128 v[204:207], v1 offset:3072
	s_add_u32 s20, s20, 0x184000
	s_addc_u32 s21, s21, 0
	s_mov_b32 m0, s27
	v_lshl_add_u64 v[6:7], s[20:21], 0, v[132:133]
	ds_read_b128 v[208:211], v170 offset:32768
	ds_read_b128 v[212:215], v170 offset:33792
	ds_read_b128 v[216:219], v170 offset:34816
	ds_read_b128 v[220:223], v170 offset:35840
	ds_read_b128 v[224:227], v170 offset:36864
	ds_read_b128 v[228:231], v170 offset:37888
	ds_read_b128 v[232:235], v170 offset:38912
	ds_read_b128 v[236:239], v170 offset:39936
	global_load_lds_dwordx4 v[6:7], off
	s_mov_b32 m0, s28
	v_lshl_add_u64 v[6:7], s[20:21], 0, v[156:157]
	global_load_lds_dwordx4 v[6:7], off
	s_waitcnt vmcnt(8)
	s_waitcnt lgkmcnt(0)
	s_setprio 1
	s_barrier
	v_mfma_f32_16x16x32_bf16 v[128:131], v[174:177], v[208:211], v[128:131]
	v_mfma_f32_16x16x32_bf16 v[124:127], v[184:187], v[208:211], v[124:127]
	v_mfma_f32_16x16x32_bf16 v[112:115], v[174:177], v[216:219], v[112:115]
	v_mfma_f32_16x16x32_bf16 v[108:111], v[184:187], v[216:219], v[108:111]
	v_mfma_f32_16x16x32_bf16 v[96:99], v[174:177], v[224:227], v[96:99]
	v_mfma_f32_16x16x32_bf16 v[92:95], v[184:187], v[224:227], v[92:95]
	v_mfma_f32_16x16x32_bf16 v[80:83], v[174:177], v[232:235], v[80:83]
	v_mfma_f32_16x16x32_bf16 v[76:79], v[184:187], v[232:235], v[76:79]
	v_mfma_f32_16x16x32_bf16 v[128:131], v[178:181], v[212:215], v[128:131]
	v_mfma_f32_16x16x32_bf16 v[124:127], v[188:191], v[212:215], v[124:127]
	v_mfma_f32_16x16x32_bf16 v[112:115], v[178:181], v[220:223], v[112:115]
	v_mfma_f32_16x16x32_bf16 v[108:111], v[188:191], v[220:223], v[108:111]
	v_mfma_f32_16x16x32_bf16 v[96:99], v[178:181], v[228:231], v[96:99]
	v_mfma_f32_16x16x32_bf16 v[92:95], v[188:191], v[228:231], v[92:95]
	v_mfma_f32_16x16x32_bf16 v[80:83], v[178:181], v[236:239], v[80:83]
	v_mfma_f32_16x16x32_bf16 v[76:79], v[188:191], v[236:239], v[76:79]
	v_mfma_f32_16x16x32_bf16 v[120:123], v[192:195], v[208:211], v[120:123]
	v_mfma_f32_16x16x32_bf16 v[116:119], v[200:203], v[208:211], v[116:119]
	v_mfma_f32_16x16x32_bf16 v[104:107], v[192:195], v[216:219], v[104:107]
	v_mfma_f32_16x16x32_bf16 v[100:103], v[200:203], v[216:219], v[100:103]
	v_mfma_f32_16x16x32_bf16 v[88:91], v[192:195], v[224:227], v[88:91]
	v_mfma_f32_16x16x32_bf16 v[84:87], v[200:203], v[224:227], v[84:87]
	v_mfma_f32_16x16x32_bf16 v[72:75], v[192:195], v[232:235], v[72:75]
	v_mfma_f32_16x16x32_bf16 v[68:71], v[200:203], v[232:235], v[68:71]
	v_mfma_f32_16x16x32_bf16 v[120:123], v[196:199], v[212:215], v[120:123]
	v_mfma_f32_16x16x32_bf16 v[116:119], v[204:207], v[212:215], v[116:119]
	v_mfma_f32_16x16x32_bf16 v[104:107], v[196:199], v[220:223], v[104:107]
	v_mfma_f32_16x16x32_bf16 v[100:103], v[204:207], v[220:223], v[100:103]
	v_mfma_f32_16x16x32_bf16 v[88:91], v[196:199], v[228:231], v[88:91]
	v_mfma_f32_16x16x32_bf16 v[84:87], v[204:207], v[228:231], v[84:87]
	v_mfma_f32_16x16x32_bf16 v[72:75], v[196:199], v[236:239], v[72:75]
	v_mfma_f32_16x16x32_bf16 v[68:71], v[204:207], v[236:239], v[68:71]
	s_barrier
; #define LAS __attribute__((address_space(3)))
; #define PG8_STAGE(bufoff, gbase, voff) do { _Pragma("unroll") for (int _i = 0; _i < 2; ++_i) \
;         __builtin_amdgcn_global_load_lds((const unsigned*)((const char*)(gbase) + (voff)[_i]), (LAS unsigned*)(lds + (bufoff) + ldsw + _i * 8192), 16, 0, 0); } while (0)
; #define PG8_LDA(dst, b, h) do { _Pragma("unroll") for (int m = 0; m < 4; ++m) _Pragma("unroll") for (int k = 0; k < 2; ++k) dst[m][k] = *(const LAS bf16x8*)(lds + PG8_SA(b, h) + aoff + m * 2048 + k * 1024); } while (0)
; #define PG8_MMA(ai, bj, At, Bt) do { __builtin_amdgcn_s_setprio(1); _Pragma("unroll") for (int m = 0; m < 4; ++m) _Pragma("unroll") for (int n = 0; n < 2; ++n) _Pragma("unroll") for (int k = 0; k < 2; ++k) \
;         acc[ai][bj][m][n] = __builtin_amdgcn_mfma_f32_16x16x32_bf16(Bt[n][k], At[m][k], acc[ai][bj][m][n], 0, 0, 0); __builtin_amdgcn_s_setprio(0); } while (0)
; #define PG8_WAIT_V(n) asm volatile("s_waitcnt vmcnt(" #n ")" ::: "memory")
; #define PG8_WAIT_L(n) asm volatile("s_waitcnt lgkmcnt(" #n ")" ::: "memory")
; #define PG8_BAR __builtin_amdgcn_s_barrier()
; #define PG8_SCHED __builtin_amdgcn_sched_barrier(0)
; template <class Epi, bool ALIGN_EPI = PG8_ALIGN, bool SP2 = PG8_SP2>
; __device__ __forceinline__ void gemm_phase(LAS uchar* lds, const Gemm g, const StaticOrder& S, const Epi& E) {
;     ...
;         for (int tb = 0; tb < nt; tb += tblk) {
;         if constexpr (Epi::GROUPS) { if (tb > 0) {
;             const LAS float* rt = (const LAS float*)(lds + LDS_RT) + ((ui & 1) * 256 + wr * 64 + fr) * 8 + ((tb >> 2) - 1);
;     ...
;             PG8_LDA(At, 1, 1); PG8_STAGE(PG8_SB(1, 0), b3, voffB); PG8_STAGE(PG8_SB(1, 1), b3 + hstepB, voffB); PG8_STAGE(PG8_SA(1, 0), a3, voffA);
;             PG8_WAIT_V(8); PG8_WAIT_L(0); PG8_BAR; PG8_MMA(1, 0, At, B0); PG8_MMA(1, 1, At, B1); PG8_BAR; PG8_SCHED;
	s_setprio 0
	s_add_i32 s20, s43, s24
	v_lshl_add_u64 v[6:7], v[240:241], 0, s[84:85]
	s_mov_b32 m0, s20
	ds_read_b128 v[208:211], v170 offset:49152
	ds_read_b128 v[212:215], v170 offset:50176
	ds_read_b128 v[216:219], v170 offset:51200
	ds_read_b128 v[220:223], v170 offset:52224
	ds_read_b128 v[224:227], v170 offset:53248
	ds_read_b128 v[228:231], v170 offset:54272
	ds_read_b128 v[232:235], v170 offset:55296
	ds_read_b128 v[236:239], v170 offset:56320
	global_load_lds_dwordx4 v[6:7], off
	s_add_i32 m0, s20, 0x2000
	s_add_u32 s4, s4, 0x84080
	v_lshl_add_u64 v[6:7], v[242:243], 0, s[84:85]
	s_addc_u32 s5, s5, 0
	s_add_i32 s20, s44, s24
	global_load_lds_dwordx4 v[6:7], off
	s_mov_b32 m0, s20
	v_lshl_add_u64 v[6:7], s[4:5], 0, v[134:135]
	global_load_lds_dwordx4 v[6:7], off
	s_add_i32 m0, s20, 0x2000
	v_lshl_add_u64 v[6:7], s[4:5], 0, v[158:159]
	global_load_lds_dwordx4 v[6:7], off
	s_mov_b32 m0, s29
	v_lshl_add_u64 v[6:7], v[244:245], 0, s[84:85]
	global_load_lds_dwordx4 v[6:7], off
	s_mov_b32 m0, s30
	v_lshl_add_u64 v[6:7], v[246:247], 0, s[84:85]
	global_load_lds_dwordx4 v[6:7], off
	s_waitcnt vmcnt(8)
	s_waitcnt lgkmcnt(0)
	s_setprio 1
	s_barrier
	v_mfma_f32_16x16x32_bf16 v[64:67], v[174:177], v[208:211], v[64:67]
	v_mfma_f32_16x16x32_bf16 v[60:63], v[184:187], v[208:211], v[60:63]
	v_mfma_f32_16x16x32_bf16 v[48:51], v[174:177], v[216:219], v[48:51]
	v_mfma_f32_16x16x32_bf16 v[44:47], v[184:187], v[216:219], v[44:47]
	v_mfma_f32_16x16x32_bf16 v[32:35], v[174:177], v[224:227], v[32:35]
	v_mfma_f32_16x16x32_bf16 v[28:31], v[184:187], v[224:227], v[28:31]
	v_mfma_f32_16x16x32_bf16 v[16:19], v[174:177], v[232:235], v[16:19]
	v_mfma_f32_16x16x32_bf16 v[12:15], v[184:187], v[232:235], v[12:15]
	v_mfma_f32_16x16x32_bf16 v[64:67], v[178:181], v[212:215], v[64:67]
	v_mfma_f32_16x16x32_bf16 v[60:63], v[188:191], v[212:215], v[60:63]
	v_mfma_f32_16x16x32_bf16 v[48:51], v[178:181], v[220:223], v[48:51]
	v_mfma_f32_16x16x32_bf16 v[44:47], v[188:191], v[220:223], v[44:47]
	v_mfma_f32_16x16x32_bf16 v[32:35], v[178:181], v[228:231], v[32:35]
	v_mfma_f32_16x16x32_bf16 v[28:31], v[188:191], v[228:231], v[28:31]
	v_mfma_f32_16x16x32_bf16 v[16:19], v[178:181], v[236:239], v[16:19]
	v_mfma_f32_16x16x32_bf16 v[12:15], v[188:191], v[236:239], v[12:15]
	v_mfma_f32_16x16x32_bf16 v[56:59], v[192:195], v[208:211], v[56:59]
	v_mfma_f32_16x16x32_bf16 v[52:55], v[200:203], v[208:211], v[52:55]
	v_mfma_f32_16x16x32_bf16 v[40:43], v[192:195], v[216:219], v[40:43]
	v_mfma_f32_16x16x32_bf16 v[36:39], v[200:203], v[216:219], v[36:39]
	v_mfma_f32_16x16x32_bf16 v[24:27], v[192:195], v[224:227], v[24:27]
	v_mfma_f32_16x16x32_bf16 v[20:23], v[200:203], v[224:227], v[20:23]
	v_mfma_f32_16x16x32_bf16 v[6:9], v[192:195], v[232:235], v[8:11]
	v_mfma_f32_16x16x32_bf16 v[2:5], v[200:203], v[232:235], v[2:5]
	v_mfma_f32_16x16x32_bf16 v[56:59], v[196:199], v[212:215], v[56:59]
	v_mfma_f32_16x16x32_bf16 v[52:55], v[204:207], v[212:215], v[52:55]
	v_mfma_f32_16x16x32_bf16 v[40:43], v[196:199], v[220:223], v[40:43]
	v_mfma_f32_16x16x32_bf16 v[36:39], v[204:207], v[220:223], v[36:39]
	v_mfma_f32_16x16x32_bf16 v[24:27], v[196:199], v[228:231], v[24:27]
	v_mfma_f32_16x16x32_bf16 v[20:23], v[204:207], v[228:231], v[20:23]
	v_mfma_f32_16x16x32_bf16 v[8:11], v[196:199], v[236:239], v[6:9]
	v_mfma_f32_16x16x32_bf16 v[4:7], v[204:207], v[236:239], v[2:5]
	s_barrier
	s_setprio 0
	s_add_u32 s18, s18, 0x100
	s_addc_u32 s19, s19, 0
	s_cmp_ge_u32 s42, s41
	s_cbranch_scc0 .LBB0_580
	s_add_u32 s16, s16, 0x200
	s_addc_u32 s17, s17, 0
	s_cmp_lt_u32 s40, 28
	s_cbranch_scc0 .LBB0_583
	s_mov_b32 s40, s41
	s_cmp_eq_u32 s40, 0
	s_cbranch_scc0 .LBB0_578
	s_branch .LBB0_579

; #define PG8_STAGE(bufoff, gbase, voff) do { _Pragma("unroll") for (int _i = 0; _i < 2; ++_i) \
;         __builtin_amdgcn_global_load_lds((const unsigned*)((const char*)(gbase) + (voff)[_i]), (LAS unsigned*)(lds + (bufoff) + ldsw + _i * 8192), 16, 0, 0); } while (0)
; #define PG8_LDA(dst, b, h) do { _Pragma("unroll") for (int m = 0; m < 4; ++m) _Pragma("unroll") for (int k = 0; k < 2; ++k) dst[m][k] = *(const LAS bf16x8*)(lds + PG8_SA(b, h) + aoff + m * 2048 + k * 1024); } while (0)
; #define PG8_LDB(dst, b, h) do { _Pragma("unroll") for (int n = 0; n < 2; ++n) _Pragma("unroll") for (int k = 0; k < 2; ++k) dst[n][k] = *(const LAS bf16x8*)(lds + PG8_SB(b, h) + boff + n * 2048 + k * 1024); } while (0)
; #define PG8_MMA(ai, bj, At, Bt) do { __builtin_amdgcn_s_setprio(1); _Pragma("unroll") for (int m = 0; m < 4; ++m) _Pragma("unroll") for (int n = 0; n < 2; ++n) _Pragma("unroll") for (int k = 0; k < 2; ++k) \
;         acc[ai][bj][m][n] = __builtin_amdgcn_mfma_f32_16x16x32_bf16(Bt[n][k], At[m][k], acc[ai][bj][m][n], 0, 0, 0); __builtin_amdgcn_s_setprio(0); } while (0)
; #define PG8_WAIT_V(n) asm volatile("s_waitcnt vmcnt(" #n ")" ::: "memory")
; #define PG8_WAIT_L(n) asm volatile("s_waitcnt lgkmcnt(" #n ")" ::: "memory")
; #define PG8_BAR __builtin_amdgcn_s_barrier()
; #define PG8_SCHED __builtin_amdgcn_sched_barrier(0)
; template <class Epi, bool ALIGN_EPI = PG8_ALIGN, bool SP2 = PG8_SP2>
; __device__ __forceinline__ void gemm_phase(LAS uchar* lds, const Gemm g, const StaticOrder& S, const Epi& E) {
;     ...
;             const bool last = (t == nt - 2);
;             const char* a1 = cA + (size_t)(t + 1) * kstep;
;             const char* a2 = last ? nA : cA + (size_t)(t + 2) * kstep; const char* b2 = last ? nB : cB + (size_t)(t + 2) * kstep;
;             const char* a3 = a2 + kstep; const char* b3 = b2 + kstep;
;             if constexpr (SP2) {
;             PG8_LDB(B0, 0, 0); PG8_LDB(B1, 0, 1); PG8_SCHED; PG8_LDA(At, 0, 0); PG8_STAGE(PG8_SA(1, 1), a1 + hstepA, voffA);
;             PG8_WAIT_V(8); PG8_WAIT_L(0); PG8_BAR; PG8_MMA(0, 0, At, B0); PG8_MMA(0, 1, At, B1); PG8_BAR; PG8_SCHED;
;             PG8_LDA(At, 0, 1); PG8_STAGE(PG8_SB(0, 0), b2, voffB); PG8_STAGE(PG8_SB(0, 1), b2 + hstepB, voffB); PG8_STAGE(PG8_SA(0, 0), a2, voffA);
;             PG8_WAIT_V(8); PG8_WAIT_L(0); PG8_BAR; PG8_MMA(1, 0, At, B0); PG8_MMA(1, 1, At, B1); PG8_BAR; PG8_SCHED;
.LBB0_668:
	s_add_u32 s36, s14, 0x100
	s_addc_u32 s37, s15, 0
	s_mov_b32 s38, -2
	s_add_u32 s14, s12, 0x100
	s_addc_u32 s15, s13, 0
	s_add_i32 s39, 0, 0x10000
	s_cmp_eq_u32 s38, 12
	s_cselect_b32 s19, s5, s15
	s_cselect_b32 s18, s4, s14
	s_cselect_b32 s17, s11, s37
	s_cselect_b32 s16, s10, s36
	s_add_i32 s40, 0, 0x14000
	v_add_u32_e32 v174, s39, v139
	v_add_u32_e32 v192, s40, v139
	ds_read_b128 v[160:163], v174
	ds_read_b128 v[164:167], v174 offset:1024
	ds_read_b128 v[168:171], v174 offset:2048
	ds_read_b128 v[174:177], v174 offset:3072
	ds_read_b128 v[178:181], v192
	ds_read_b128 v[184:187], v192 offset:1024
	ds_read_b128 v[188:191], v192 offset:2048
	ds_read_b128 v[192:195], v192 offset:3072
	v_lshl_add_u64 v[228:229], s[12:13], 0, v[156:157]
	s_add_i32 m0, s23, 0xc000
	ds_read_b128 v[196:199], v173
	ds_read_b128 v[200:203], v173 offset:1024
	ds_read_b128 v[204:207], v173 offset:2048
	ds_read_b128 v[208:211], v173 offset:3072
	ds_read_b128 v[212:215], v173 offset:4096
	ds_read_b128 v[216:219], v173 offset:5120
	ds_read_b128 v[220:223], v173 offset:6144
	ds_read_b128 v[224:227], v173 offset:7168
	global_load_lds_dwordx4 v[228:229], off
	s_add_i32 m0, s23, 0xe000
	v_lshl_add_u64 v[228:229], s[12:13], 0, v[158:159]
	global_load_lds_dwordx4 v[228:229], off
	s_waitcnt vmcnt(8)
	s_waitcnt lgkmcnt(0)
	s_setprio 1
	s_barrier
	v_mfma_f32_16x16x32_bf16 v[126:129], v[160:163], v[196:199], 0
	v_mfma_f32_16x16x32_bf16 v[122:125], v[168:171], v[196:199], 0
	v_mfma_f32_16x16x32_bf16 v[118:121], v[160:163], v[204:207], 0
	v_mfma_f32_16x16x32_bf16 v[110:113], v[168:171], v[204:207], 0
	v_mfma_f32_16x16x32_bf16 v[102:105], v[160:163], v[212:215], 0
	v_mfma_f32_16x16x32_bf16 v[94:97], v[168:171], v[212:215], 0
	v_mfma_f32_16x16x32_bf16 v[86:89], v[160:163], v[220:223], 0
	v_mfma_f32_16x16x32_bf16 v[78:81], v[168:171], v[220:223], 0
	v_mfma_f32_16x16x32_bf16 v[126:129], v[164:167], v[200:203], v[126:129]
	v_mfma_f32_16x16x32_bf16 v[122:125], v[174:177], v[200:203], v[122:125]
	v_mfma_f32_16x16x32_bf16 v[118:121], v[164:167], v[208:211], v[118:121]
	v_mfma_f32_16x16x32_bf16 v[110:113], v[174:177], v[208:211], v[110:113]
	v_mfma_f32_16x16x32_bf16 v[102:105], v[164:167], v[216:219], v[102:105]
	v_mfma_f32_16x16x32_bf16 v[94:97], v[174:177], v[216:219], v[94:97]
	v_mfma_f32_16x16x32_bf16 v[86:89], v[164:167], v[224:227], v[86:89]
	v_mfma_f32_16x16x32_bf16 v[78:81], v[174:177], v[224:227], v[78:81]
	v_mfma_f32_16x16x32_bf16 v[114:117], v[178:181], v[196:199], 0
	v_mfma_f32_16x16x32_bf16 v[106:109], v[188:191], v[196:199], 0
	v_mfma_f32_16x16x32_bf16 v[98:101], v[178:181], v[204:207], 0
	v_mfma_f32_16x16x32_bf16 v[90:93], v[188:191], v[204:207], 0
	v_mfma_f32_16x16x32_bf16 v[82:85], v[178:181], v[212:215], 0
	v_mfma_f32_16x16x32_bf16 v[74:77], v[188:191], v[212:215], 0
	v_mfma_f32_16x16x32_bf16 v[70:73], v[178:181], v[220:223], 0
	v_mfma_f32_16x16x32_bf16 v[66:69], v[188:191], v[220:223], 0
	v_mfma_f32_16x16x32_bf16 v[114:117], v[184:187], v[200:203], v[114:117]
	v_mfma_f32_16x16x32_bf16 v[106:109], v[192:195], v[200:203], v[106:109]
	v_mfma_f32_16x16x32_bf16 v[98:101], v[184:187], v[208:211], v[98:101]
	v_mfma_f32_16x16x32_bf16 v[90:93], v[192:195], v[208:211], v[90:93]
	v_mfma_f32_16x16x32_bf16 v[82:85], v[184:187], v[216:219], v[82:85]
	v_mfma_f32_16x16x32_bf16 v[74:77], v[192:195], v[216:219], v[74:77]
	v_mfma_f32_16x16x32_bf16 v[70:73], v[184:187], v[224:227], v[70:73]
	v_mfma_f32_16x16x32_bf16 v[66:69], v[192:195], v[224:227], v[66:69]
	s_barrier
	s_setprio 0
	s_add_i32 s12, s39, s21
	v_lshl_add_u64 v[228:229], s[16:17], 0, v[134:135]
	s_mov_b32 m0, s12
	ds_read_b128 v[196:199], v173 offset:16384
	ds_read_b128 v[200:203], v173 offset:17408
	ds_read_b128 v[204:207], v173 offset:18432
	ds_read_b128 v[208:211], v173 offset:19456
	ds_read_b128 v[212:215], v173 offset:20480
	ds_read_b128 v[216:219], v173 offset:21504
	ds_read_b128 v[220:223], v173 offset:22528
	ds_read_b128 v[224:227], v173 offset:23552
	global_load_lds_dwordx4 v[228:229], off
	s_add_i32 m0, s12, 0x2000
	s_add_u32 s12, s16, 0x44000
	v_lshl_add_u64 v[230:231], s[16:17], 0, v[130:131]
	s_addc_u32 s13, s17, 0
	s_add_i32 s39, s40, s21
	global_load_lds_dwordx4 v[230:231], off
	v_lshl_add_u64 v[232:233], s[12:13], 0, v[134:135]
	s_mov_b32 m0, s39
	global_load_lds_dwordx4 v[232:233], off
	s_add_i32 m0, s39, 0x2000
	v_lshl_add_u64 v[232:233], s[12:13], 0, v[130:131]
	global_load_lds_dwordx4 v[232:233], off
	s_mov_b32 m0, s23
	v_lshl_add_u64 v[232:233], s[18:19], 0, v[152:153]
	global_load_lds_dwordx4 v[232:233], off
	s_mov_b32 m0, s24
	v_lshl_add_u64 v[234:235], s[18:19], 0, v[132:133]
	global_load_lds_dwordx4 v[234:235], off
	s_waitcnt vmcnt(8)
	s_waitcnt lgkmcnt(0)
	s_setprio 1
	s_barrier
; #define PG8_STAGE(bufoff, gbase, voff) do { _Pragma("unroll") for (int _i = 0; _i < 2; ++_i) \
;         __builtin_amdgcn_global_load_lds((const unsigned*)((const char*)(gbase) + (voff)[_i]), (LAS unsigned*)(lds + (bufoff) + ldsw + _i * 8192), 16, 0, 0); } while (0)
; #define PG8_LDA(dst, b, h) do { _Pragma("unroll") for (int m = 0; m < 4; ++m) _Pragma("unroll") for (int k = 0; k < 2; ++k) dst[m][k] = *(const LAS bf16x8*)(lds + PG8_SA(b, h) + aoff + m * 2048 + k * 1024); } while (0)
; #define PG8_LDB(dst, b, h) do { _Pragma("unroll") for (int n = 0; n < 2; ++n) _Pragma("unroll") for (int k = 0; k < 2; ++k) dst[n][k] = *(const LAS bf16x8*)(lds + PG8_SB(b, h) + boff + n * 2048 + k * 1024); } while (0)
; #define PG8_MMA(ai, bj, At, Bt) do { __builtin_amdgcn_s_setprio(1); _Pragma("unroll") for (int m = 0; m < 4; ++m) _Pragma("unroll") for (int n = 0; n < 2; ++n) _Pragma("unroll") for (int k = 0; k < 2; ++k) \
;         acc[ai][bj][m][n] = __builtin_amdgcn_mfma_f32_16x16x32_bf16(Bt[n][k], At[m][k], acc[ai][bj][m][n], 0, 0, 0); __builtin_amdgcn_s_setprio(0); } while (0)
; #define PG8_WAIT_V(n) asm volatile("s_waitcnt vmcnt(" #n ")" ::: "memory")
; #define PG8_WAIT_L(n) asm volatile("s_waitcnt lgkmcnt(" #n ")" ::: "memory")
; #define PG8_BAR __builtin_amdgcn_s_barrier()
; #define PG8_SCHED __builtin_amdgcn_sched_barrier(0)
; template <class Epi, bool ALIGN_EPI = PG8_ALIGN, bool SP2 = PG8_SP2>
; __device__ __forceinline__ void gemm_phase(LAS uchar* lds, const Gemm g, const StaticOrder& S, const Epi& E) {
;     ...
;             PG8_WAIT_V(8); PG8_WAIT_L(0); PG8_BAR; PG8_MMA(1, 0, At, B0); PG8_MMA(1, 1, At, B1); PG8_BAR; PG8_SCHED;
;             PG8_LDB(B0, 1, 0); PG8_LDB(B1, 1, 1); PG8_SCHED; PG8_LDA(At, 1, 0); PG8_STAGE(PG8_SA(0, 1), a2 + hstepA, voffA);
;             PG8_WAIT_V(8); PG8_WAIT_L(0); PG8_BAR; PG8_MMA(0, 0, At, B0); PG8_MMA(0, 1, At, B1); PG8_BAR; PG8_SCHED;
	v_mfma_f32_16x16x32_bf16 v[62:65], v[160:163], v[196:199], 0
	v_mfma_f32_16x16x32_bf16 v[58:61], v[168:171], v[196:199], 0
	v_mfma_f32_16x16x32_bf16 v[54:57], v[160:163], v[204:207], 0
	v_mfma_f32_16x16x32_bf16 v[46:49], v[168:171], v[204:207], 0
	v_mfma_f32_16x16x32_bf16 v[38:41], v[160:163], v[212:215], 0
	v_mfma_f32_16x16x32_bf16 v[30:33], v[168:171], v[212:215], 0
	v_mfma_f32_16x16x32_bf16 v[22:25], v[160:163], v[220:223], 0
	v_mfma_f32_16x16x32_bf16 v[14:17], v[168:171], v[220:223], 0
	v_mfma_f32_16x16x32_bf16 v[62:65], v[164:167], v[200:203], v[62:65]
	v_mfma_f32_16x16x32_bf16 v[58:61], v[174:177], v[200:203], v[58:61]
	v_mfma_f32_16x16x32_bf16 v[54:57], v[164:167], v[208:211], v[54:57]
	v_mfma_f32_16x16x32_bf16 v[46:49], v[174:177], v[208:211], v[46:49]
	v_mfma_f32_16x16x32_bf16 v[38:41], v[164:167], v[216:219], v[38:41]
	v_mfma_f32_16x16x32_bf16 v[30:33], v[174:177], v[216:219], v[30:33]
	v_mfma_f32_16x16x32_bf16 v[22:25], v[164:167], v[224:227], v[22:25]
	v_mfma_f32_16x16x32_bf16 v[14:17], v[174:177], v[224:227], v[14:17]
	v_mfma_f32_16x16x32_bf16 v[50:53], v[178:181], v[196:199], 0
	v_mfma_f32_16x16x32_bf16 v[42:45], v[188:191], v[196:199], 0
	v_mfma_f32_16x16x32_bf16 v[34:37], v[178:181], v[204:207], 0
	v_mfma_f32_16x16x32_bf16 v[26:29], v[188:191], v[204:207], 0
	v_mfma_f32_16x16x32_bf16 v[18:21], v[178:181], v[212:215], 0
	v_mfma_f32_16x16x32_bf16 v[10:13], v[188:191], v[212:215], 0
	v_mfma_f32_16x16x32_bf16 v[6:9], v[178:181], v[220:223], 0
	v_mfma_f32_16x16x32_bf16 v[2:5], v[188:191], v[220:223], 0
	v_mfma_f32_16x16x32_bf16 v[50:53], v[184:187], v[200:203], v[50:53]
	v_mfma_f32_16x16x32_bf16 v[42:45], v[192:195], v[200:203], v[42:45]
	v_mfma_f32_16x16x32_bf16 v[34:37], v[184:187], v[208:211], v[34:37]
	v_mfma_f32_16x16x32_bf16 v[26:29], v[192:195], v[208:211], v[26:29]
	v_mfma_f32_16x16x32_bf16 v[18:21], v[184:187], v[216:219], v[18:21]
	v_mfma_f32_16x16x32_bf16 v[10:13], v[192:195], v[216:219], v[10:13]
	v_mfma_f32_16x16x32_bf16 v[6:9], v[184:187], v[224:227], v[6:9]
	v_mfma_f32_16x16x32_bf16 v[2:5], v[192:195], v[224:227], v[2:5]
	s_barrier
	s_setprio 0
	s_add_i32 s39, 0, 0x18000
	s_add_i32 s40, 0, 0x1c000
	v_add_u32_e32 v174, s39, v139
	v_add_u32_e32 v192, s40, v139
	ds_read_b128 v[160:163], v174
	ds_read_b128 v[164:167], v174 offset:1024
	ds_read_b128 v[168:171], v174 offset:2048
	ds_read_b128 v[174:177], v174 offset:3072
	ds_read_b128 v[178:181], v192
	ds_read_b128 v[184:187], v192 offset:1024
	ds_read_b128 v[188:191], v192 offset:2048
	ds_read_b128 v[192:195], v192 offset:3072
	s_add_u32 s12, s18, 0x44000
	s_addc_u32 s13, s19, 0
	s_mov_b32 m0, s25
	v_lshl_add_u64 v[236:237], s[12:13], 0, v[152:153]
	ds_read_b128 v[196:199], v173 offset:32768
	ds_read_b128 v[200:203], v173 offset:33792
	ds_read_b128 v[204:207], v173 offset:34816
	ds_read_b128 v[208:211], v173 offset:35840
	ds_read_b128 v[212:215], v173 offset:36864
	ds_read_b128 v[216:219], v173 offset:37888
	ds_read_b128 v[220:223], v173 offset:38912
	ds_read_b128 v[224:227], v173 offset:39936
	global_load_lds_dwordx4 v[236:237], off
	s_mov_b32 m0, s26
	v_lshl_add_u64 v[236:237], s[12:13], 0, v[132:133]
	global_load_lds_dwordx4 v[236:237], off
	s_waitcnt vmcnt(8)
	s_waitcnt lgkmcnt(0)
	s_setprio 1
	s_barrier
	v_mfma_f32_16x16x32_bf16 v[126:129], v[160:163], v[196:199], v[126:129]
	v_mfma_f32_16x16x32_bf16 v[122:125], v[168:171], v[196:199], v[122:125]
	v_mfma_f32_16x16x32_bf16 v[118:121], v[160:163], v[204:207], v[118:121]
	v_mfma_f32_16x16x32_bf16 v[110:113], v[168:171], v[204:207], v[110:113]
	v_mfma_f32_16x16x32_bf16 v[102:105], v[160:163], v[212:215], v[102:105]
	v_mfma_f32_16x16x32_bf16 v[94:97], v[168:171], v[212:215], v[94:97]
	v_mfma_f32_16x16x32_bf16 v[86:89], v[160:163], v[220:223], v[86:89]
	v_mfma_f32_16x16x32_bf16 v[78:81], v[168:171], v[220:223], v[78:81]
	v_mfma_f32_16x16x32_bf16 v[126:129], v[164:167], v[200:203], v[126:129]
	v_mfma_f32_16x16x32_bf16 v[122:125], v[174:177], v[200:203], v[122:125]
	v_mfma_f32_16x16x32_bf16 v[118:121], v[164:167], v[208:211], v[118:121]
	v_mfma_f32_16x16x32_bf16 v[110:113], v[174:177], v[208:211], v[110:113]
	v_mfma_f32_16x16x32_bf16 v[102:105], v[164:167], v[216:219], v[102:105]
	v_mfma_f32_16x16x32_bf16 v[94:97], v[174:177], v[216:219], v[94:97]
	v_mfma_f32_16x16x32_bf16 v[86:89], v[164:167], v[224:227], v[86:89]
	v_mfma_f32_16x16x32_bf16 v[78:81], v[174:177], v[224:227], v[78:81]
	v_mfma_f32_16x16x32_bf16 v[114:117], v[178:181], v[196:199], v[114:117]
	v_mfma_f32_16x16x32_bf16 v[106:109], v[188:191], v[196:199], v[106:109]
	v_mfma_f32_16x16x32_bf16 v[98:101], v[178:181], v[204:207], v[98:101]
	v_mfma_f32_16x16x32_bf16 v[90:93], v[188:191], v[204:207], v[90:93]
	v_mfma_f32_16x16x32_bf16 v[82:85], v[178:181], v[212:215], v[82:85]
	v_mfma_f32_16x16x32_bf16 v[74:77], v[188:191], v[212:215], v[74:77]
	v_mfma_f32_16x16x32_bf16 v[70:73], v[178:181], v[220:223], v[70:73]
	v_mfma_f32_16x16x32_bf16 v[66:69], v[188:191], v[220:223], v[66:69]
	v_mfma_f32_16x16x32_bf16 v[114:117], v[184:187], v[200:203], v[114:117]
	v_mfma_f32_16x16x32_bf16 v[106:109], v[192:195], v[200:203], v[106:109]
	v_mfma_f32_16x16x32_bf16 v[98:101], v[184:187], v[208:211], v[98:101]
	v_mfma_f32_16x16x32_bf16 v[90:93], v[192:195], v[208:211], v[90:93]
	v_mfma_f32_16x16x32_bf16 v[82:85], v[184:187], v[216:219], v[82:85]
	v_mfma_f32_16x16x32_bf16 v[74:77], v[192:195], v[216:219], v[74:77]
	v_mfma_f32_16x16x32_bf16 v[70:73], v[184:187], v[224:227], v[70:73]
	v_mfma_f32_16x16x32_bf16 v[66:69], v[192:195], v[224:227], v[66:69]
	s_barrier
; #define PG8_STAGE(bufoff, gbase, voff) do { _Pragma("unroll") for (int _i = 0; _i < 2; ++_i) \
;         __builtin_amdgcn_global_load_lds((const unsigned*)((const char*)(gbase) + (voff)[_i]), (LAS unsigned*)(lds + (bufoff) + ldsw + _i * 8192), 16, 0, 0); } while (0)
; #define PG8_LDA(dst, b, h) do { _Pragma("unroll") for (int m = 0; m < 4; ++m) _Pragma("unroll") for (int k = 0; k < 2; ++k) dst[m][k] = *(const LAS bf16x8*)(lds + PG8_SA(b, h) + aoff + m * 2048 + k * 1024); } while (0)
; #define PG8_LDB(dst, b, h) do { _Pragma("unroll") for (int n = 0; n < 2; ++n) _Pragma("unroll") for (int k = 0; k < 2; ++k) dst[n][k] = *(const LAS bf16x8*)(lds + PG8_SB(b, h) + boff + n * 2048 + k * 1024); } while (0)
; #define PG8_BAR __builtin_amdgcn_s_barrier()
; template <class Epi, bool ALIGN_EPI = PG8_ALIGN, bool SP2 = PG8_SP2>
; __device__ __forceinline__ void gemm_phase(LAS uchar* lds, const Gemm g, const StaticOrder& S, const Epi& E) {
;     ...
;         for (int t = tb; t < tb + tblk; t += 2) {
;             const bool last = (t == nt - 2);
;             const char* a1 = cA + (size_t)(t + 1) * kstep;
;             const char* a2 = last ? nA : cA + (size_t)(t + 2) * kstep; const char* b2 = last ? nB : cB + (size_t)(t + 2) * kstep;
;             const char* a3 = a2 + kstep; const char* b3 = b2 + kstep;
;             if constexpr (SP2) {
;             PG8_LDB(B0, 0, 0); PG8_LDB(B1, 0, 1); PG8_SCHED; PG8_LDA(At, 0, 0); PG8_STAGE(PG8_SA(1, 1), a1 + hstepA, voffA);
;             PG8_WAIT_V(8); PG8_WAIT_L(0); PG8_BAR; PG8_MMA(0, 0, At, B0); PG8_MMA(0, 1, At, B1); PG8_BAR; PG8_SCHED;
;             PG8_LDA(At, 0, 1); PG8_STAGE(PG8_SB(0, 0), b2, voffB); PG8_STAGE(PG8_SB(0, 1), b2 + hstepB, voffB); PG8_STAGE(PG8_SA(0, 0), a2, voffA);
;             PG8_WAIT_V(8); PG8_WAIT_L(0); PG8_BAR; PG8_MMA(1, 0, At, B0); PG8_MMA(1, 1, At, B1); PG8_BAR; PG8_SCHED;
;             PG8_LDB(B0, 1, 0); PG8_LDB(B1, 1, 1); PG8_SCHED; PG8_LDA(At, 1, 0); PG8_STAGE(PG8_SA(0, 1), a2 + hstepA, voffA);
;             PG8_WAIT_V(8); PG8_WAIT_L(0); PG8_BAR; PG8_MMA(0, 0, At, B0); PG8_MMA(0, 1, At, B1); PG8_BAR; PG8_SCHED;
;             PG8_LDA(At, 1, 1); PG8_STAGE(PG8_SB(1, 0), b3, voffB); PG8_STAGE(PG8_SB(1, 1), b3 + hstepB, voffB); PG8_STAGE(PG8_SA(1, 0), a3, voffA);
;             PG8_WAIT_V(8); PG8_WAIT_L(0); PG8_BAR; PG8_MMA(1, 0, At, B0); PG8_MMA(1, 1, At, B1); PG8_BAR; PG8_SCHED;
	s_setprio 0
	s_add_i32 s12, s39, s21
	v_lshl_add_u64 v[228:229], v[228:229], 0, s[84:85]
	s_mov_b32 m0, s12
	ds_read_b128 v[196:199], v173 offset:49152
	ds_read_b128 v[200:203], v173 offset:50176
	ds_read_b128 v[204:207], v173 offset:51200
	ds_read_b128 v[208:211], v173 offset:52224
	ds_read_b128 v[212:215], v173 offset:53248
	ds_read_b128 v[216:219], v173 offset:54272
	ds_read_b128 v[220:223], v173 offset:55296
	ds_read_b128 v[224:227], v173 offset:56320
	global_load_lds_dwordx4 v[228:229], off
	s_add_i32 m0, s12, 0x2000
	s_add_u32 s12, s16, 0x44080
	v_lshl_add_u64 v[228:229], v[230:231], 0, s[84:85]
	s_addc_u32 s13, s17, 0
	s_add_i32 s16, s40, s21
	global_load_lds_dwordx4 v[228:229], off
	s_mov_b32 m0, s16
	v_lshl_add_u64 v[228:229], s[12:13], 0, v[134:135]
	global_load_lds_dwordx4 v[228:229], off
	s_add_i32 m0, s16, 0x2000
	v_lshl_add_u64 v[228:229], s[12:13], 0, v[130:131]
	global_load_lds_dwordx4 v[228:229], off
	s_mov_b32 m0, s27
	v_lshl_add_u64 v[228:229], v[232:233], 0, s[84:85]
	global_load_lds_dwordx4 v[228:229], off
	s_mov_b32 m0, s28
	v_lshl_add_u64 v[228:229], v[234:235], 0, s[84:85]
	global_load_lds_dwordx4 v[228:229], off
	s_waitcnt vmcnt(8)
	s_waitcnt lgkmcnt(0)
	s_setprio 1
	s_barrier
	v_mfma_f32_16x16x32_bf16 v[62:65], v[160:163], v[196:199], v[62:65]
	v_mfma_f32_16x16x32_bf16 v[58:61], v[168:171], v[196:199], v[58:61]
	v_mfma_f32_16x16x32_bf16 v[54:57], v[160:163], v[204:207], v[54:57]
	v_mfma_f32_16x16x32_bf16 v[46:49], v[168:171], v[204:207], v[46:49]
	v_mfma_f32_16x16x32_bf16 v[38:41], v[160:163], v[212:215], v[38:41]
	v_mfma_f32_16x16x32_bf16 v[30:33], v[168:171], v[212:215], v[30:33]
	v_mfma_f32_16x16x32_bf16 v[22:25], v[160:163], v[220:223], v[22:25]
	v_mfma_f32_16x16x32_bf16 v[14:17], v[168:171], v[220:223], v[14:17]
	v_mfma_f32_16x16x32_bf16 v[62:65], v[164:167], v[200:203], v[62:65]
	v_mfma_f32_16x16x32_bf16 v[58:61], v[174:177], v[200:203], v[58:61]
	v_mfma_f32_16x16x32_bf16 v[54:57], v[164:167], v[208:211], v[54:57]
	v_mfma_f32_16x16x32_bf16 v[46:49], v[174:177], v[208:211], v[46:49]
	v_mfma_f32_16x16x32_bf16 v[38:41], v[164:167], v[216:219], v[38:41]
	v_mfma_f32_16x16x32_bf16 v[30:33], v[174:177], v[216:219], v[30:33]
	v_mfma_f32_16x16x32_bf16 v[22:25], v[164:167], v[224:227], v[22:25]
	v_mfma_f32_16x16x32_bf16 v[14:17], v[174:177], v[224:227], v[14:17]
	v_mfma_f32_16x16x32_bf16 v[50:53], v[178:181], v[196:199], v[50:53]
	v_mfma_f32_16x16x32_bf16 v[42:45], v[188:191], v[196:199], v[42:45]
	v_mfma_f32_16x16x32_bf16 v[34:37], v[178:181], v[204:207], v[34:37]
	v_mfma_f32_16x16x32_bf16 v[26:29], v[188:191], v[204:207], v[26:29]
	v_mfma_f32_16x16x32_bf16 v[18:21], v[178:181], v[212:215], v[18:21]
	v_mfma_f32_16x16x32_bf16 v[10:13], v[188:191], v[212:215], v[10:13]
	v_mfma_f32_16x16x32_bf16 v[6:9], v[178:181], v[220:223], v[6:9]
	v_mfma_f32_16x16x32_bf16 v[2:5], v[188:191], v[220:223], v[2:5]
	v_mfma_f32_16x16x32_bf16 v[50:53], v[184:187], v[200:203], v[50:53]
	v_mfma_f32_16x16x32_bf16 v[42:45], v[192:195], v[200:203], v[42:45]
	v_mfma_f32_16x16x32_bf16 v[34:37], v[184:187], v[208:211], v[34:37]
	v_mfma_f32_16x16x32_bf16 v[26:29], v[192:195], v[208:211], v[26:29]
	v_mfma_f32_16x16x32_bf16 v[18:21], v[184:187], v[216:219], v[18:21]
	v_mfma_f32_16x16x32_bf16 v[10:13], v[192:195], v[216:219], v[10:13]
	v_mfma_f32_16x16x32_bf16 v[6:9], v[184:187], v[224:227], v[6:9]
	v_mfma_f32_16x16x32_bf16 v[2:5], v[192:195], v[224:227], v[2:5]
	s_barrier
	s_setprio 0
	s_add_i32 s38, s38, 2
	s_add_u32 s36, s36, 0x100
	s_addc_u32 s37, s37, 0
	s_cmp_gt_u32 s38, 13
	s_mov_b64 s[12:13], s[14:15]
.LBB0_669:
	s_add_u32 s14, s12, 0x100
	s_addc_u32 s15, s13, 0
	s_add_i32 s39, 0, 0x10000
	s_cmp_eq_u32 s38, 12
	s_cselect_b32 s19, s5, s15
	s_cselect_b32 s18, s4, s14
	s_cselect_b32 s17, s11, s37
	s_cselect_b32 s16, s10, s36
	s_add_i32 s40, 0, 0x14000
	v_add_u32_e32 v174, s39, v139
	v_add_u32_e32 v192, s40, v139
	ds_read_b128 v[160:163], v174
	ds_read_b128 v[164:167], v174 offset:1024
	ds_read_b128 v[168:171], v174 offset:2048
	ds_read_b128 v[174:177], v174 offset:3072
	ds_read_b128 v[178:181], v192
	ds_read_b128 v[184:187], v192 offset:1024
	ds_read_b128 v[188:191], v192 offset:2048
	ds_read_b128 v[192:195], v192 offset:3072
	v_lshl_add_u64 v[228:229], s[12:13], 0, v[156:157]
	s_add_i32 m0, s23, 0xc000
	ds_read_b128 v[196:199], v173
	ds_read_b128 v[200:203], v173 offset:1024
	ds_read_b128 v[204:207], v173 offset:2048
	ds_read_b128 v[208:211], v173 offset:3072
	ds_read_b128 v[212:215], v173 offset:4096
	ds_read_b128 v[216:219], v173 offset:5120
	ds_read_b128 v[220:223], v173 offset:6144
	ds_read_b128 v[224:227], v173 offset:7168
	global_load_lds_dwordx4 v[228:229], off
	s_add_i32 m0, s23, 0xe000
	v_lshl_add_u64 v[228:229], s[12:13], 0, v[158:159]
	global_load_lds_dwordx4 v[228:229], off
	s_waitcnt vmcnt(8)
	s_waitcnt lgkmcnt(0)
	s_setprio 1
	s_barrier
; #define PG8_STAGE(bufoff, gbase, voff) do { _Pragma("unroll") for (int _i = 0; _i < 2; ++_i) \
;         __builtin_amdgcn_global_load_lds((const unsigned*)((const char*)(gbase) + (voff)[_i]), (LAS unsigned*)(lds + (bufoff) + ldsw + _i * 8192), 16, 0, 0); } while (0)
; #define PG8_LDA(dst, b, h) do { _Pragma("unroll") for (int m = 0; m < 4; ++m) _Pragma("unroll") for (int k = 0; k < 2; ++k) dst[m][k] = *(const LAS bf16x8*)(lds + PG8_SA(b, h) + aoff + m * 2048 + k * 1024); } while (0)
; #define PG8_LDB(dst, b, h) do { _Pragma("unroll") for (int n = 0; n < 2; ++n) _Pragma("unroll") for (int k = 0; k < 2; ++k) dst[n][k] = *(const LAS bf16x8*)(lds + PG8_SB(b, h) + boff + n * 2048 + k * 1024); } while (0)
; #define PG8_BAR __builtin_amdgcn_s_barrier()
; template <class Epi, bool ALIGN_EPI = PG8_ALIGN, bool SP2 = PG8_SP2>
; __device__ __forceinline__ void gemm_phase(LAS uchar* lds, const Gemm g, const StaticOrder& S, const Epi& E) {
;     ...
;         for (int t = tb; t < tb + tblk; t += 2) {
;             const bool last = (t == nt - 2);
;             const char* a1 = cA + (size_t)(t + 1) * kstep;
;             const char* a2 = last ? nA : cA + (size_t)(t + 2) * kstep; const char* b2 = last ? nB : cB + (size_t)(t + 2) * kstep;
;             const char* a3 = a2 + kstep; const char* b3 = b2 + kstep;
;             if constexpr (SP2) {
;             PG8_LDB(B0, 0, 0); PG8_LDB(B1, 0, 1); PG8_SCHED; PG8_LDA(At, 0, 0); PG8_STAGE(PG8_SA(1, 1), a1 + hstepA, voffA);
;             PG8_WAIT_V(8); PG8_WAIT_L(0); PG8_BAR; PG8_MMA(0, 0, At, B0); PG8_MMA(0, 1, At, B1); PG8_BAR; PG8_SCHED;
;             PG8_LDA(At, 0, 1); PG8_STAGE(PG8_SB(0, 0), b2, voffB); PG8_STAGE(PG8_SB(0, 1), b2 + hstepB, voffB); PG8_STAGE(PG8_SA(0, 0), a2, voffA);
;             PG8_WAIT_V(8); PG8_WAIT_L(0); PG8_BAR; PG8_MMA(1, 0, At, B0); PG8_MMA(1, 1, At, B1); PG8_BAR; PG8_SCHED;
;             PG8_LDB(B0, 1, 0); PG8_LDB(B1, 1, 1); PG8_SCHED; PG8_LDA(At, 1, 0); PG8_STAGE(PG8_SA(0, 1), a2 + hstepA, voffA);
;             PG8_WAIT_V(8); PG8_WAIT_L(0); PG8_BAR; PG8_MMA(0, 0, At, B0); PG8_MMA(0, 1, At, B1); PG8_BAR; PG8_SCHED;
;             PG8_LDA(At, 1, 1); PG8_STAGE(PG8_SB(1, 0), b3, voffB); PG8_STAGE(PG8_SB(1, 1), b3 + hstepB, voffB); PG8_STAGE(PG8_SA(1, 0), a3, voffA);
;             PG8_WAIT_V(8); PG8_WAIT_L(0); PG8_BAR; PG8_MMA(1, 0, At, B0); PG8_MMA(1, 1, At, B1); PG8_BAR; PG8_SCHED;
	v_mfma_f32_16x16x32_bf16 v[126:129], v[160:163], v[196:199], v[126:129]
	v_mfma_f32_16x16x32_bf16 v[122:125], v[168:171], v[196:199], v[122:125]
	v_mfma_f32_16x16x32_bf16 v[118:121], v[160:163], v[204:207], v[118:121]
	v_mfma_f32_16x16x32_bf16 v[110:113], v[168:171], v[204:207], v[110:113]
	v_mfma_f32_16x16x32_bf16 v[102:105], v[160:163], v[212:215], v[102:105]
	v_mfma_f32_16x16x32_bf16 v[94:97], v[168:171], v[212:215], v[94:97]
	v_mfma_f32_16x16x32_bf16 v[86:89], v[160:163], v[220:223], v[86:89]
	v_mfma_f32_16x16x32_bf16 v[78:81], v[168:171], v[220:223], v[78:81]
	v_mfma_f32_16x16x32_bf16 v[126:129], v[164:167], v[200:203], v[126:129]
	v_mfma_f32_16x16x32_bf16 v[122:125], v[174:177], v[200:203], v[122:125]
	v_mfma_f32_16x16x32_bf16 v[118:121], v[164:167], v[208:211], v[118:121]
	v_mfma_f32_16x16x32_bf16 v[110:113], v[174:177], v[208:211], v[110:113]
	v_mfma_f32_16x16x32_bf16 v[102:105], v[164:167], v[216:219], v[102:105]
	v_mfma_f32_16x16x32_bf16 v[94:97], v[174:177], v[216:219], v[94:97]
	v_mfma_f32_16x16x32_bf16 v[86:89], v[164:167], v[224:227], v[86:89]
	v_mfma_f32_16x16x32_bf16 v[78:81], v[174:177], v[224:227], v[78:81]
	v_mfma_f32_16x16x32_bf16 v[114:117], v[178:181], v[196:199], v[114:117]
	v_mfma_f32_16x16x32_bf16 v[106:109], v[188:191], v[196:199], v[106:109]
	v_mfma_f32_16x16x32_bf16 v[98:101], v[178:181], v[204:207], v[98:101]
	v_mfma_f32_16x16x32_bf16 v[90:93], v[188:191], v[204:207], v[90:93]
	v_mfma_f32_16x16x32_bf16 v[82:85], v[178:181], v[212:215], v[82:85]
	v_mfma_f32_16x16x32_bf16 v[74:77], v[188:191], v[212:215], v[74:77]
	v_mfma_f32_16x16x32_bf16 v[70:73], v[178:181], v[220:223], v[70:73]
	v_mfma_f32_16x16x32_bf16 v[66:69], v[188:191], v[220:223], v[66:69]
	v_mfma_f32_16x16x32_bf16 v[114:117], v[184:187], v[200:203], v[114:117]
	v_mfma_f32_16x16x32_bf16 v[106:109], v[192:195], v[200:203], v[106:109]
	v_mfma_f32_16x16x32_bf16 v[98:101], v[184:187], v[208:211], v[98:101]
	v_mfma_f32_16x16x32_bf16 v[90:93], v[192:195], v[208:211], v[90:93]
	v_mfma_f32_16x16x32_bf16 v[82:85], v[184:187], v[216:219], v[82:85]
	v_mfma_f32_16x16x32_bf16 v[74:77], v[192:195], v[216:219], v[74:77]
	v_mfma_f32_16x16x32_bf16 v[70:73], v[184:187], v[224:227], v[70:73]
	v_mfma_f32_16x16x32_bf16 v[66:69], v[192:195], v[224:227], v[66:69]
	s_barrier
	s_setprio 0
	s_add_i32 s12, s39, s21
	v_lshl_add_u64 v[228:229], s[16:17], 0, v[134:135]
	s_mov_b32 m0, s12
	ds_read_b128 v[196:199], v173 offset:16384
	ds_read_b128 v[200:203], v173 offset:17408
	ds_read_b128 v[204:207], v173 offset:18432
	ds_read_b128 v[208:211], v173 offset:19456
	ds_read_b128 v[212:215], v173 offset:20480
	ds_read_b128 v[216:219], v173 offset:21504
	ds_read_b128 v[220:223], v173 offset:22528
	ds_read_b128 v[224:227], v173 offset:23552
	global_load_lds_dwordx4 v[228:229], off
	s_add_i32 m0, s12, 0x2000
	s_add_u32 s12, s16, 0x44000
	v_lshl_add_u64 v[230:231], s[16:17], 0, v[130:131]
	s_addc_u32 s13, s17, 0
	s_add_i32 s39, s40, s21
	global_load_lds_dwordx4 v[230:231], off
	v_lshl_add_u64 v[232:233], s[12:13], 0, v[134:135]
	s_mov_b32 m0, s39
	global_load_lds_dwordx4 v[232:233], off
	s_add_i32 m0, s39, 0x2000
	v_lshl_add_u64 v[232:233], s[12:13], 0, v[130:131]
	global_load_lds_dwordx4 v[232:233], off
	s_mov_b32 m0, s23
	v_lshl_add_u64 v[232:233], s[18:19], 0, v[152:153]
	global_load_lds_dwordx4 v[232:233], off
	s_mov_b32 m0, s24
	v_lshl_add_u64 v[234:235], s[18:19], 0, v[132:133]
	global_load_lds_dwordx4 v[234:235], off
	s_waitcnt vmcnt(8)
	s_waitcnt lgkmcnt(0)
	s_setprio 1
	s_barrier
	v_mfma_f32_16x16x32_bf16 v[62:65], v[160:163], v[196:199], v[62:65]
	v_mfma_f32_16x16x32_bf16 v[58:61], v[168:171], v[196:199], v[58:61]
	v_mfma_f32_16x16x32_bf16 v[54:57], v[160:163], v[204:207], v[54:57]
	v_mfma_f32_16x16x32_bf16 v[46:49], v[168:171], v[204:207], v[46:49]
	v_mfma_f32_16x16x32_bf16 v[38:41], v[160:163], v[212:215], v[38:41]
	v_mfma_f32_16x16x32_bf16 v[30:33], v[168:171], v[212:215], v[30:33]
	v_mfma_f32_16x16x32_bf16 v[22:25], v[160:163], v[220:223], v[22:25]
	v_mfma_f32_16x16x32_bf16 v[14:17], v[168:171], v[220:223], v[14:17]
	v_mfma_f32_16x16x32_bf16 v[62:65], v[164:167], v[200:203], v[62:65]
	v_mfma_f32_16x16x32_bf16 v[58:61], v[174:177], v[200:203], v[58:61]
	v_mfma_f32_16x16x32_bf16 v[54:57], v[164:167], v[208:211], v[54:57]
	v_mfma_f32_16x16x32_bf16 v[46:49], v[174:177], v[208:211], v[46:49]
	v_mfma_f32_16x16x32_bf16 v[38:41], v[164:167], v[216:219], v[38:41]
	v_mfma_f32_16x16x32_bf16 v[30:33], v[174:177], v[216:219], v[30:33]
	v_mfma_f32_16x16x32_bf16 v[22:25], v[164:167], v[224:227], v[22:25]
	v_mfma_f32_16x16x32_bf16 v[14:17], v[174:177], v[224:227], v[14:17]
	v_mfma_f32_16x16x32_bf16 v[50:53], v[178:181], v[196:199], v[50:53]
	v_mfma_f32_16x16x32_bf16 v[42:45], v[188:191], v[196:199], v[42:45]
	v_mfma_f32_16x16x32_bf16 v[34:37], v[178:181], v[204:207], v[34:37]
	v_mfma_f32_16x16x32_bf16 v[26:29], v[188:191], v[204:207], v[26:29]
	v_mfma_f32_16x16x32_bf16 v[18:21], v[178:181], v[212:215], v[18:21]
	v_mfma_f32_16x16x32_bf16 v[10:13], v[188:191], v[212:215], v[10:13]
	v_mfma_f32_16x16x32_bf16 v[6:9], v[178:181], v[220:223], v[6:9]
	v_mfma_f32_16x16x32_bf16 v[2:5], v[188:191], v[220:223], v[2:5]
	v_mfma_f32_16x16x32_bf16 v[50:53], v[184:187], v[200:203], v[50:53]
	v_mfma_f32_16x16x32_bf16 v[42:45], v[192:195], v[200:203], v[42:45]
	v_mfma_f32_16x16x32_bf16 v[34:37], v[184:187], v[208:211], v[34:37]
	v_mfma_f32_16x16x32_bf16 v[26:29], v[192:195], v[208:211], v[26:29]
	v_mfma_f32_16x16x32_bf16 v[18:21], v[184:187], v[216:219], v[18:21]
	v_mfma_f32_16x16x32_bf16 v[10:13], v[192:195], v[216:219], v[10:13]
	v_mfma_f32_16x16x32_bf16 v[6:9], v[184:187], v[224:227], v[6:9]
	v_mfma_f32_16x16x32_bf16 v[2:5], v[192:195], v[224:227], v[2:5]
	s_barrier
; #define PG8_STAGE(bufoff, gbase, voff) do { _Pragma("unroll") for (int _i = 0; _i < 2; ++_i) \
;         __builtin_amdgcn_global_load_lds((const unsigned*)((const char*)(gbase) + (voff)[_i]), (LAS unsigned*)(lds + (bufoff) + ldsw + _i * 8192), 16, 0, 0); } while (0)
; #define PG8_LDA(dst, b, h) do { _Pragma("unroll") for (int m = 0; m < 4; ++m) _Pragma("unroll") for (int k = 0; k < 2; ++k) dst[m][k] = *(const LAS bf16x8*)(lds + PG8_SA(b, h) + aoff + m * 2048 + k * 1024); } while (0)
; #define PG8_LDB(dst, b, h) do { _Pragma("unroll") for (int n = 0; n < 2; ++n) _Pragma("unroll") for (int k = 0; k < 2; ++k) dst[n][k] = *(const LAS bf16x8*)(lds + PG8_SB(b, h) + boff + n * 2048 + k * 1024); } while (0)
; #define PG8_BAR __builtin_amdgcn_s_barrier()
; template <class Epi, bool ALIGN_EPI = PG8_ALIGN, bool SP2 = PG8_SP2>
; __device__ __forceinline__ void gemm_phase(LAS uchar* lds, const Gemm g, const StaticOrder& S, const Epi& E) {
;     ...
;         for (int t = tb; t < tb + tblk; t += 2) {
;             const bool last = (t == nt - 2);
;             const char* a1 = cA + (size_t)(t + 1) * kstep;
;             const char* a2 = last ? nA : cA + (size_t)(t + 2) * kstep; const char* b2 = last ? nB : cB + (size_t)(t + 2) * kstep;
;             const char* a3 = a2 + kstep; const char* b3 = b2 + kstep;
;             if constexpr (SP2) {
;             PG8_LDB(B0, 0, 0); PG8_LDB(B1, 0, 1); PG8_SCHED; PG8_LDA(At, 0, 0); PG8_STAGE(PG8_SA(1, 1), a1 + hstepA, voffA);
;             PG8_WAIT_V(8); PG8_WAIT_L(0); PG8_BAR; PG8_MMA(0, 0, At, B0); PG8_MMA(0, 1, At, B1); PG8_BAR; PG8_SCHED;
;             PG8_LDA(At, 0, 1); PG8_STAGE(PG8_SB(0, 0), b2, voffB); PG8_STAGE(PG8_SB(0, 1), b2 + hstepB, voffB); PG8_STAGE(PG8_SA(0, 0), a2, voffA);
;             PG8_WAIT_V(8); PG8_WAIT_L(0); PG8_BAR; PG8_MMA(1, 0, At, B0); PG8_MMA(1, 1, At, B1); PG8_BAR; PG8_SCHED;
;             PG8_LDB(B0, 1, 0); PG8_LDB(B1, 1, 1); PG8_SCHED; PG8_LDA(At, 1, 0); PG8_STAGE(PG8_SA(0, 1), a2 + hstepA, voffA);
;             PG8_WAIT_V(8); PG8_WAIT_L(0); PG8_BAR; PG8_MMA(0, 0, At, B0); PG8_MMA(0, 1, At, B1); PG8_BAR; PG8_SCHED;
;             PG8_LDA(At, 1, 1); PG8_STAGE(PG8_SB(1, 0), b3, voffB); PG8_STAGE(PG8_SB(1, 1), b3 + hstepB, voffB); PG8_STAGE(PG8_SA(1, 0), a3, voffA);
;             PG8_WAIT_V(8); PG8_WAIT_L(0); PG8_BAR; PG8_MMA(1, 0, At, B0); PG8_MMA(1, 1, At, B1); PG8_BAR; PG8_SCHED;
	s_setprio 0
	s_add_i32 s39, 0, 0x18000
	s_add_i32 s40, 0, 0x1c000
	v_add_u32_e32 v174, s39, v139
	v_add_u32_e32 v192, s40, v139
	ds_read_b128 v[160:163], v174
	ds_read_b128 v[164:167], v174 offset:1024
	ds_read_b128 v[168:171], v174 offset:2048
	ds_read_b128 v[174:177], v174 offset:3072
	ds_read_b128 v[178:181], v192
	ds_read_b128 v[184:187], v192 offset:1024
	ds_read_b128 v[188:191], v192 offset:2048
	ds_read_b128 v[192:195], v192 offset:3072
	s_add_u32 s12, s18, 0x44000
	s_addc_u32 s13, s19, 0
	s_mov_b32 m0, s25
	v_lshl_add_u64 v[236:237], s[12:13], 0, v[152:153]
	ds_read_b128 v[196:199], v173 offset:32768
	ds_read_b128 v[200:203], v173 offset:33792
	ds_read_b128 v[204:207], v173 offset:34816
	ds_read_b128 v[208:211], v173 offset:35840
	ds_read_b128 v[212:215], v173 offset:36864
	ds_read_b128 v[216:219], v173 offset:37888
	ds_read_b128 v[220:223], v173 offset:38912
	ds_read_b128 v[224:227], v173 offset:39936
	global_load_lds_dwordx4 v[236:237], off
	s_mov_b32 m0, s26
	v_lshl_add_u64 v[236:237], s[12:13], 0, v[132:133]
	global_load_lds_dwordx4 v[236:237], off
	s_waitcnt vmcnt(8)
	s_waitcnt lgkmcnt(0)
	s_setprio 1
	s_barrier
	v_mfma_f32_16x16x32_bf16 v[126:129], v[160:163], v[196:199], v[126:129]
	v_mfma_f32_16x16x32_bf16 v[122:125], v[168:171], v[196:199], v[122:125]
	v_mfma_f32_16x16x32_bf16 v[118:121], v[160:163], v[204:207], v[118:121]
	v_mfma_f32_16x16x32_bf16 v[110:113], v[168:171], v[204:207], v[110:113]
	v_mfma_f32_16x16x32_bf16 v[102:105], v[160:163], v[212:215], v[102:105]
	v_mfma_f32_16x16x32_bf16 v[94:97], v[168:171], v[212:215], v[94:97]
	v_mfma_f32_16x16x32_bf16 v[86:89], v[160:163], v[220:223], v[86:89]
	v_mfma_f32_16x16x32_bf16 v[78:81], v[168:171], v[220:223], v[78:81]
	v_mfma_f32_16x16x32_bf16 v[126:129], v[164:167], v[200:203], v[126:129]
	v_mfma_f32_16x16x32_bf16 v[122:125], v[174:177], v[200:203], v[122:125]
	v_mfma_f32_16x16x32_bf16 v[118:121], v[164:167], v[208:211], v[118:121]
	v_mfma_f32_16x16x32_bf16 v[110:113], v[174:177], v[208:211], v[110:113]
	v_mfma_f32_16x16x32_bf16 v[102:105], v[164:167], v[216:219], v[102:105]
	v_mfma_f32_16x16x32_bf16 v[94:97], v[174:177], v[216:219], v[94:97]
	v_mfma_f32_16x16x32_bf16 v[86:89], v[164:167], v[224:227], v[86:89]
	v_mfma_f32_16x16x32_bf16 v[78:81], v[174:177], v[224:227], v[78:81]
	v_mfma_f32_16x16x32_bf16 v[114:117], v[178:181], v[196:199], v[114:117]
	v_mfma_f32_16x16x32_bf16 v[106:109], v[188:191], v[196:199], v[106:109]
	v_mfma_f32_16x16x32_bf16 v[98:101], v[178:181], v[204:207], v[98:101]
	v_mfma_f32_16x16x32_bf16 v[90:93], v[188:191], v[204:207], v[90:93]
	v_mfma_f32_16x16x32_bf16 v[82:85], v[178:181], v[212:215], v[82:85]
	v_mfma_f32_16x16x32_bf16 v[74:77], v[188:191], v[212:215], v[74:77]
	v_mfma_f32_16x16x32_bf16 v[70:73], v[178:181], v[220:223], v[70:73]
	v_mfma_f32_16x16x32_bf16 v[66:69], v[188:191], v[220:223], v[66:69]
	v_mfma_f32_16x16x32_bf16 v[114:117], v[184:187], v[200:203], v[114:117]
	v_mfma_f32_16x16x32_bf16 v[106:109], v[192:195], v[200:203], v[106:109]
	v_mfma_f32_16x16x32_bf16 v[98:101], v[184:187], v[208:211], v[98:101]
	v_mfma_f32_16x16x32_bf16 v[90:93], v[192:195], v[208:211], v[90:93]
	v_mfma_f32_16x16x32_bf16 v[82:85], v[184:187], v[216:219], v[82:85]
	v_mfma_f32_16x16x32_bf16 v[74:77], v[192:195], v[216:219], v[74:77]
	v_mfma_f32_16x16x32_bf16 v[70:73], v[184:187], v[224:227], v[70:73]
	v_mfma_f32_16x16x32_bf16 v[66:69], v[192:195], v[224:227], v[66:69]
	s_barrier
; #define PG8_STAGE(bufoff, gbase, voff) do { _Pragma("unroll") for (int _i = 0; _i < 2; ++_i) \
;         __builtin_amdgcn_global_load_lds((const unsigned*)((const char*)(gbase) + (voff)[_i]), (LAS unsigned*)(lds + (bufoff) + ldsw + _i * 8192), 16, 0, 0); } while (0)
; #define PG8_LDA(dst, b, h) do { _Pragma("unroll") for (int m = 0; m < 4; ++m) _Pragma("unroll") for (int k = 0; k < 2; ++k) dst[m][k] = *(const LAS bf16x8*)(lds + PG8_SA(b, h) + aoff + m * 2048 + k * 1024); } while (0)
; #define PG8_LDB(dst, b, h) do { _Pragma("unroll") for (int n = 0; n < 2; ++n) _Pragma("unroll") for (int k = 0; k < 2; ++k) dst[n][k] = *(const LAS bf16x8*)(lds + PG8_SB(b, h) + boff + n * 2048 + k * 1024); } while (0)
; template <class Epi, bool ALIGN_EPI = PG8_ALIGN, bool SP2 = PG8_SP2>
; __device__ __forceinline__ void gemm_phase(LAS uchar* lds, const Gemm g, const StaticOrder& S, const Epi& E) {
;     ...
;         for (int t = tb; t < tb + tblk; t += 2) {
;             const bool last = (t == nt - 2);
;             const char* a1 = cA + (size_t)(t + 1) * kstep;
;             const char* a2 = last ? nA : cA + (size_t)(t + 2) * kstep; const char* b2 = last ? nB : cB + (size_t)(t + 2) * kstep;
;             const char* a3 = a2 + kstep; const char* b3 = b2 + kstep;
;             if constexpr (SP2) {
;             PG8_LDB(B0, 0, 0); PG8_LDB(B1, 0, 1); PG8_SCHED; PG8_LDA(At, 0, 0); PG8_STAGE(PG8_SA(1, 1), a1 + hstepA, voffA);
;             PG8_WAIT_V(8); PG8_WAIT_L(0); PG8_BAR; PG8_MMA(0, 0, At, B0); PG8_MMA(0, 1, At, B1); PG8_BAR; PG8_SCHED;
;             PG8_LDA(At, 0, 1); PG8_STAGE(PG8_SB(0, 0), b2, voffB); PG8_STAGE(PG8_SB(0, 1), b2 + hstepB, voffB); PG8_STAGE(PG8_SA(0, 0), a2, voffA);
;             PG8_WAIT_V(8); PG8_WAIT_L(0); PG8_BAR; PG8_MMA(1, 0, At, B0); PG8_MMA(1, 1, At, B1); PG8_BAR; PG8_SCHED;
;             PG8_LDB(B0, 1, 0); PG8_LDB(B1, 1, 1); PG8_SCHED; PG8_LDA(At, 1, 0); PG8_STAGE(PG8_SA(0, 1), a2 + hstepA, voffA);
;             PG8_WAIT_V(8); PG8_WAIT_L(0); PG8_BAR; PG8_MMA(0, 0, At, B0); PG8_MMA(0, 1, At, B1); PG8_BAR; PG8_SCHED;
;             PG8_LDA(At, 1, 1); PG8_STAGE(PG8_SB(1, 0), b3, voffB); PG8_STAGE(PG8_SB(1, 1), b3 + hstepB, voffB); PG8_STAGE(PG8_SA(1, 0), a3, voffA);
;             PG8_WAIT_V(8); PG8_WAIT_L(0); PG8_BAR; PG8_MMA(1, 0, At, B0); PG8_MMA(1, 1, At, B1); PG8_BAR; PG8_SCHED;
;     ...
;         if constexpr (ALIGN_EPI) { if (wr == 0) PG8_BAR; }
	s_setprio 0
	s_add_i32 s12, s39, s21
	v_lshl_add_u64 v[228:229], v[228:229], 0, s[84:85]
	s_mov_b32 m0, s12
	ds_read_b128 v[196:199], v173 offset:49152
	ds_read_b128 v[200:203], v173 offset:50176
	ds_read_b128 v[204:207], v173 offset:51200
	ds_read_b128 v[208:211], v173 offset:52224
	ds_read_b128 v[212:215], v173 offset:53248
	ds_read_b128 v[216:219], v173 offset:54272
	ds_read_b128 v[220:223], v173 offset:55296
	ds_read_b128 v[224:227], v173 offset:56320
	global_load_lds_dwordx4 v[228:229], off
	s_add_i32 m0, s12, 0x2000
	s_add_u32 s12, s16, 0x44080
	v_lshl_add_u64 v[228:229], v[230:231], 0, s[84:85]
	s_addc_u32 s13, s17, 0
	s_add_i32 s16, s40, s21
	global_load_lds_dwordx4 v[228:229], off
	s_mov_b32 m0, s16
	v_lshl_add_u64 v[228:229], s[12:13], 0, v[134:135]
	global_load_lds_dwordx4 v[228:229], off
	s_add_i32 m0, s16, 0x2000
	v_lshl_add_u64 v[228:229], s[12:13], 0, v[130:131]
	global_load_lds_dwordx4 v[228:229], off
	s_mov_b32 m0, s27
	v_lshl_add_u64 v[228:229], v[232:233], 0, s[84:85]
	global_load_lds_dwordx4 v[228:229], off
	s_mov_b32 m0, s28
	v_lshl_add_u64 v[228:229], v[234:235], 0, s[84:85]
	global_load_lds_dwordx4 v[228:229], off
	s_waitcnt vmcnt(8)
	s_waitcnt lgkmcnt(0)
	s_setprio 1
	s_barrier
	v_mfma_f32_16x16x32_bf16 v[62:65], v[160:163], v[196:199], v[62:65]
	v_mfma_f32_16x16x32_bf16 v[58:61], v[168:171], v[196:199], v[58:61]
	v_mfma_f32_16x16x32_bf16 v[54:57], v[160:163], v[204:207], v[54:57]
	v_mfma_f32_16x16x32_bf16 v[46:49], v[168:171], v[204:207], v[46:49]
	v_mfma_f32_16x16x32_bf16 v[38:41], v[160:163], v[212:215], v[38:41]
	v_mfma_f32_16x16x32_bf16 v[30:33], v[168:171], v[212:215], v[30:33]
	v_mfma_f32_16x16x32_bf16 v[22:25], v[160:163], v[220:223], v[22:25]
	v_mfma_f32_16x16x32_bf16 v[14:17], v[168:171], v[220:223], v[14:17]
	v_mfma_f32_16x16x32_bf16 v[62:65], v[164:167], v[200:203], v[62:65]
	v_mfma_f32_16x16x32_bf16 v[58:61], v[174:177], v[200:203], v[58:61]
	v_mfma_f32_16x16x32_bf16 v[54:57], v[164:167], v[208:211], v[54:57]
	v_mfma_f32_16x16x32_bf16 v[46:49], v[174:177], v[208:211], v[46:49]
	v_mfma_f32_16x16x32_bf16 v[38:41], v[164:167], v[216:219], v[38:41]
	v_mfma_f32_16x16x32_bf16 v[30:33], v[174:177], v[216:219], v[30:33]
	v_mfma_f32_16x16x32_bf16 v[22:25], v[164:167], v[224:227], v[22:25]
	v_mfma_f32_16x16x32_bf16 v[14:17], v[174:177], v[224:227], v[14:17]
	v_mfma_f32_16x16x32_bf16 v[50:53], v[178:181], v[196:199], v[50:53]
	v_mfma_f32_16x16x32_bf16 v[42:45], v[188:191], v[196:199], v[42:45]
	v_mfma_f32_16x16x32_bf16 v[34:37], v[178:181], v[204:207], v[34:37]
	v_mfma_f32_16x16x32_bf16 v[26:29], v[188:191], v[204:207], v[26:29]
	v_mfma_f32_16x16x32_bf16 v[18:21], v[178:181], v[212:215], v[18:21]
	v_mfma_f32_16x16x32_bf16 v[10:13], v[188:191], v[212:215], v[10:13]
	v_mfma_f32_16x16x32_bf16 v[6:9], v[178:181], v[220:223], v[6:9]
	v_mfma_f32_16x16x32_bf16 v[2:5], v[188:191], v[220:223], v[2:5]
	v_mfma_f32_16x16x32_bf16 v[50:53], v[184:187], v[200:203], v[50:53]
	v_mfma_f32_16x16x32_bf16 v[42:45], v[192:195], v[200:203], v[42:45]
	v_mfma_f32_16x16x32_bf16 v[34:37], v[184:187], v[208:211], v[34:37]
	v_mfma_f32_16x16x32_bf16 v[26:29], v[192:195], v[208:211], v[26:29]
	v_mfma_f32_16x16x32_bf16 v[18:21], v[184:187], v[216:219], v[18:21]
	v_mfma_f32_16x16x32_bf16 v[10:13], v[192:195], v[216:219], v[10:13]
	v_mfma_f32_16x16x32_bf16 v[6:9], v[184:187], v[224:227], v[6:9]
	v_mfma_f32_16x16x32_bf16 v[2:5], v[192:195], v[224:227], v[2:5]
	s_barrier
	s_setprio 0
	s_add_i32 s38, s38, 2
	s_add_u32 s36, s36, 0x100
	s_addc_u32 s37, s37, 0
	s_cmp_gt_u32 s38, 13
	s_mov_b64 s[12:13], s[14:15]
	s_cbranch_scc0 .LBB0_669
	s_and_b64 vcc, exec, s[8:9]
	s_cbranch_vccz .LBB0_672
	s_barrier

; #define PG8_STAGE(bufoff, gbase, voff) do { _Pragma("unroll") for (int _i = 0; _i < 2; ++_i) \
;         __builtin_amdgcn_global_load_lds((const unsigned*)((const char*)(gbase) + (voff)[_i]), (LAS unsigned*)(lds + (bufoff) + ldsw + _i * 8192), 16, 0, 0); } while (0)
; #define PG8_LDA(dst, b, h) do { _Pragma("unroll") for (int m = 0; m < 4; ++m) _Pragma("unroll") for (int k = 0; k < 2; ++k) dst[m][k] = *(const LAS bf16x8*)(lds + PG8_SA(b, h) + aoff + m * 2048 + k * 1024); } while (0)
; #define PG8_LDB(dst, b, h) do { _Pragma("unroll") for (int n = 0; n < 2; ++n) _Pragma("unroll") for (int k = 0; k < 2; ++k) dst[n][k] = *(const LAS bf16x8*)(lds + PG8_SB(b, h) + boff + n * 2048 + k * 1024); } while (0)
; #define PG8_BAR __builtin_amdgcn_s_barrier()
; template <class Epi, bool ALIGN_EPI = PG8_ALIGN, bool SP2 = PG8_SP2>
; __device__ __forceinline__ void gemm_phase(LAS uchar* lds, const Gemm g, const StaticOrder& S, const Epi& E) {
;     ...
;         for (int t = tb; t < tb + tblk; t += 2) {
;             const bool last = (t == nt - 2);
;             const char* a1 = cA + (size_t)(t + 1) * kstep;
;             const char* a2 = last ? nA : cA + (size_t)(t + 2) * kstep; const char* b2 = last ? nB : cB + (size_t)(t + 2) * kstep;
;             const char* a3 = a2 + kstep; const char* b3 = b2 + kstep;
;             if constexpr (SP2) {
;             PG8_LDB(B0, 0, 0); PG8_LDB(B1, 0, 1); PG8_SCHED; PG8_LDA(At, 0, 0); PG8_STAGE(PG8_SA(1, 1), a1 + hstepA, voffA);
;             PG8_WAIT_V(8); PG8_WAIT_L(0); PG8_BAR; PG8_MMA(0, 0, At, B0); PG8_MMA(0, 1, At, B1); PG8_BAR; PG8_SCHED;
;             PG8_LDA(At, 0, 1); PG8_STAGE(PG8_SB(0, 0), b2, voffB); PG8_STAGE(PG8_SB(0, 1), b2 + hstepB, voffB); PG8_STAGE(PG8_SA(0, 0), a2, voffA);
;             PG8_WAIT_V(8); PG8_WAIT_L(0); PG8_BAR; PG8_MMA(1, 0, At, B0); PG8_MMA(1, 1, At, B1); PG8_BAR; PG8_SCHED;
;             PG8_LDB(B0, 1, 0); PG8_LDB(B1, 1, 1); PG8_SCHED; PG8_LDA(At, 1, 0); PG8_STAGE(PG8_SA(0, 1), a2 + hstepA, voffA);
;             PG8_WAIT_V(8); PG8_WAIT_L(0); PG8_BAR; PG8_MMA(0, 0, At, B0); PG8_MMA(0, 1, At, B1); PG8_BAR; PG8_SCHED;
;             PG8_LDA(At, 1, 1); PG8_STAGE(PG8_SB(1, 0), b3, voffB); PG8_STAGE(PG8_SB(1, 1), b3 + hstepB, voffB); PG8_STAGE(PG8_SA(1, 0), a3, voffA);
;             PG8_WAIT_V(8); PG8_WAIT_L(0); PG8_BAR; PG8_MMA(1, 0, At, B0); PG8_MMA(1, 1, At, B1); PG8_BAR; PG8_SCHED;
.LBB0_836:
	s_add_u32 s36, s14, 0x100
	s_addc_u32 s37, s15, 0
	s_mov_b32 s38, -2
	s_add_u32 s14, s12, 0x100
	s_addc_u32 s15, s13, 0
	s_add_i32 s39, 0, 0x10000
	s_cmp_eq_u32 s38, 12
	s_cselect_b32 s19, s5, s15
	s_cselect_b32 s18, s4, s14
	s_cselect_b32 s17, s11, s37
	s_cselect_b32 s16, s10, s36
	s_add_i32 s40, 0, 0x14000
	v_add_u32_e32 v174, s39, v139
	v_add_u32_e32 v192, s40, v139
	ds_read_b128 v[160:163], v174
	ds_read_b128 v[166:169], v174 offset:1024
	ds_read_b128 v[170:173], v174 offset:2048
	ds_read_b128 v[174:177], v174 offset:3072
	ds_read_b128 v[178:181], v192
	ds_read_b128 v[184:187], v192 offset:1024
	ds_read_b128 v[188:191], v192 offset:2048
	ds_read_b128 v[192:195], v192 offset:3072
	v_lshl_add_u64 v[228:229], s[12:13], 0, v[156:157]
	s_add_i32 m0, s23, 0xc000
	ds_read_b128 v[196:199], v165
	ds_read_b128 v[200:203], v165 offset:1024
	ds_read_b128 v[204:207], v165 offset:2048
	ds_read_b128 v[208:211], v165 offset:3072
	ds_read_b128 v[212:215], v165 offset:4096
	ds_read_b128 v[216:219], v165 offset:5120
	ds_read_b128 v[220:223], v165 offset:6144
	ds_read_b128 v[224:227], v165 offset:7168
	global_load_lds_dwordx4 v[228:229], off
	s_add_i32 m0, s23, 0xe000
	v_lshl_add_u64 v[228:229], s[12:13], 0, v[158:159]
	global_load_lds_dwordx4 v[228:229], off
	s_waitcnt vmcnt(8)
	s_waitcnt lgkmcnt(0)
	s_setprio 1
	s_barrier
	v_mfma_f32_16x16x32_bf16 v[126:129], v[160:163], v[196:199], 0
	v_mfma_f32_16x16x32_bf16 v[122:125], v[170:173], v[196:199], 0
	v_mfma_f32_16x16x32_bf16 v[118:121], v[160:163], v[204:207], 0
	v_mfma_f32_16x16x32_bf16 v[110:113], v[170:173], v[204:207], 0
	v_mfma_f32_16x16x32_bf16 v[102:105], v[160:163], v[212:215], 0
	v_mfma_f32_16x16x32_bf16 v[94:97], v[170:173], v[212:215], 0
	v_mfma_f32_16x16x32_bf16 v[86:89], v[160:163], v[220:223], 0
	v_mfma_f32_16x16x32_bf16 v[78:81], v[170:173], v[220:223], 0
	v_mfma_f32_16x16x32_bf16 v[126:129], v[166:169], v[200:203], v[126:129]
	v_mfma_f32_16x16x32_bf16 v[122:125], v[174:177], v[200:203], v[122:125]
	v_mfma_f32_16x16x32_bf16 v[118:121], v[166:169], v[208:211], v[118:121]
	v_mfma_f32_16x16x32_bf16 v[110:113], v[174:177], v[208:211], v[110:113]
	v_mfma_f32_16x16x32_bf16 v[102:105], v[166:169], v[216:219], v[102:105]
	v_mfma_f32_16x16x32_bf16 v[94:97], v[174:177], v[216:219], v[94:97]
	v_mfma_f32_16x16x32_bf16 v[86:89], v[166:169], v[224:227], v[86:89]
	v_mfma_f32_16x16x32_bf16 v[78:81], v[174:177], v[224:227], v[78:81]
	v_mfma_f32_16x16x32_bf16 v[114:117], v[178:181], v[196:199], 0
	v_mfma_f32_16x16x32_bf16 v[106:109], v[188:191], v[196:199], 0
	v_mfma_f32_16x16x32_bf16 v[98:101], v[178:181], v[204:207], 0
	v_mfma_f32_16x16x32_bf16 v[90:93], v[188:191], v[204:207], 0
	v_mfma_f32_16x16x32_bf16 v[82:85], v[178:181], v[212:215], 0
	v_mfma_f32_16x16x32_bf16 v[74:77], v[188:191], v[212:215], 0
	v_mfma_f32_16x16x32_bf16 v[70:73], v[178:181], v[220:223], 0
	v_mfma_f32_16x16x32_bf16 v[66:69], v[188:191], v[220:223], 0
	v_mfma_f32_16x16x32_bf16 v[114:117], v[184:187], v[200:203], v[114:117]
	v_mfma_f32_16x16x32_bf16 v[106:109], v[192:195], v[200:203], v[106:109]
	v_mfma_f32_16x16x32_bf16 v[98:101], v[184:187], v[208:211], v[98:101]
	v_mfma_f32_16x16x32_bf16 v[90:93], v[192:195], v[208:211], v[90:93]
	v_mfma_f32_16x16x32_bf16 v[82:85], v[184:187], v[216:219], v[82:85]
	v_mfma_f32_16x16x32_bf16 v[74:77], v[192:195], v[216:219], v[74:77]
	v_mfma_f32_16x16x32_bf16 v[70:73], v[184:187], v[224:227], v[70:73]
	v_mfma_f32_16x16x32_bf16 v[66:69], v[192:195], v[224:227], v[66:69]
	s_barrier
	s_setprio 0
	s_add_i32 s12, s39, s22
	v_lshl_add_u64 v[228:229], s[16:17], 0, v[132:133]
	s_mov_b32 m0, s12
	ds_read_b128 v[196:199], v165 offset:16384
	ds_read_b128 v[200:203], v165 offset:17408
	ds_read_b128 v[204:207], v165 offset:18432
	ds_read_b128 v[208:211], v165 offset:19456
	ds_read_b128 v[212:215], v165 offset:20480
	ds_read_b128 v[216:219], v165 offset:21504
	ds_read_b128 v[220:223], v165 offset:22528
	ds_read_b128 v[224:227], v165 offset:23552
	global_load_lds_dwordx4 v[228:229], off
	s_add_i32 m0, s12, 0x2000
	s_add_u32 s12, s16, 0x44000
	v_lshl_add_u64 v[230:231], s[16:17], 0, v[152:153]
	s_addc_u32 s13, s17, 0
	s_add_i32 s39, s40, s22
	global_load_lds_dwordx4 v[230:231], off
	v_lshl_add_u64 v[232:233], s[12:13], 0, v[132:133]
	s_mov_b32 m0, s39
	global_load_lds_dwordx4 v[232:233], off
	s_add_i32 m0, s39, 0x2000
	v_lshl_add_u64 v[232:233], s[12:13], 0, v[152:153]
	global_load_lds_dwordx4 v[232:233], off
	s_mov_b32 m0, s23
	v_lshl_add_u64 v[232:233], s[18:19], 0, v[130:131]
	global_load_lds_dwordx4 v[232:233], off
	s_mov_b32 m0, s24
	v_lshl_add_u64 v[234:235], s[18:19], 0, v[134:135]
	global_load_lds_dwordx4 v[234:235], off
	s_waitcnt vmcnt(8)
	s_waitcnt lgkmcnt(0)
	s_setprio 1
	s_barrier
; #define PG8_STAGE(bufoff, gbase, voff) do { _Pragma("unroll") for (int _i = 0; _i < 2; ++_i) \
;         __builtin_amdgcn_global_load_lds((const unsigned*)((const char*)(gbase) + (voff)[_i]), (LAS unsigned*)(lds + (bufoff) + ldsw + _i * 8192), 16, 0, 0); } while (0)
; #define PG8_LDA(dst, b, h) do { _Pragma("unroll") for (int m = 0; m < 4; ++m) _Pragma("unroll") for (int k = 0; k < 2; ++k) dst[m][k] = *(const LAS bf16x8*)(lds + PG8_SA(b, h) + aoff + m * 2048 + k * 1024); } while (0)
; #define PG8_LDB(dst, b, h) do { _Pragma("unroll") for (int n = 0; n < 2; ++n) _Pragma("unroll") for (int k = 0; k < 2; ++k) dst[n][k] = *(const LAS bf16x8*)(lds + PG8_SB(b, h) + boff + n * 2048 + k * 1024); } while (0)
; #define PG8_BAR __builtin_amdgcn_s_barrier()
; template <class Epi, bool ALIGN_EPI = PG8_ALIGN, bool SP2 = PG8_SP2>
; __device__ __forceinline__ void gemm_phase(LAS uchar* lds, const Gemm g, const StaticOrder& S, const Epi& E) {
;     ...
;         for (int t = tb; t < tb + tblk; t += 2) {
;             const bool last = (t == nt - 2);
;             const char* a1 = cA + (size_t)(t + 1) * kstep;
;             const char* a2 = last ? nA : cA + (size_t)(t + 2) * kstep; const char* b2 = last ? nB : cB + (size_t)(t + 2) * kstep;
;             const char* a3 = a2 + kstep; const char* b3 = b2 + kstep;
;             if constexpr (SP2) {
;             PG8_LDB(B0, 0, 0); PG8_LDB(B1, 0, 1); PG8_SCHED; PG8_LDA(At, 0, 0); PG8_STAGE(PG8_SA(1, 1), a1 + hstepA, voffA);
;             PG8_WAIT_V(8); PG8_WAIT_L(0); PG8_BAR; PG8_MMA(0, 0, At, B0); PG8_MMA(0, 1, At, B1); PG8_BAR; PG8_SCHED;
;             PG8_LDA(At, 0, 1); PG8_STAGE(PG8_SB(0, 0), b2, voffB); PG8_STAGE(PG8_SB(0, 1), b2 + hstepB, voffB); PG8_STAGE(PG8_SA(0, 0), a2, voffA);
;             PG8_WAIT_V(8); PG8_WAIT_L(0); PG8_BAR; PG8_MMA(1, 0, At, B0); PG8_MMA(1, 1, At, B1); PG8_BAR; PG8_SCHED;
;             PG8_LDB(B0, 1, 0); PG8_LDB(B1, 1, 1); PG8_SCHED; PG8_LDA(At, 1, 0); PG8_STAGE(PG8_SA(0, 1), a2 + hstepA, voffA);
;             PG8_WAIT_V(8); PG8_WAIT_L(0); PG8_BAR; PG8_MMA(0, 0, At, B0); PG8_MMA(0, 1, At, B1); PG8_BAR; PG8_SCHED;
;             PG8_LDA(At, 1, 1); PG8_STAGE(PG8_SB(1, 0), b3, voffB); PG8_STAGE(PG8_SB(1, 1), b3 + hstepB, voffB); PG8_STAGE(PG8_SA(1, 0), a3, voffA);
;             PG8_WAIT_V(8); PG8_WAIT_L(0); PG8_BAR; PG8_MMA(1, 0, At, B0); PG8_MMA(1, 1, At, B1); PG8_BAR; PG8_SCHED;
	v_mfma_f32_16x16x32_bf16 v[62:65], v[160:163], v[196:199], 0
	v_mfma_f32_16x16x32_bf16 v[58:61], v[170:173], v[196:199], 0
	v_mfma_f32_16x16x32_bf16 v[54:57], v[160:163], v[204:207], 0
	v_mfma_f32_16x16x32_bf16 v[46:49], v[170:173], v[204:207], 0
	v_mfma_f32_16x16x32_bf16 v[38:41], v[160:163], v[212:215], 0
	v_mfma_f32_16x16x32_bf16 v[30:33], v[170:173], v[212:215], 0
	v_mfma_f32_16x16x32_bf16 v[22:25], v[160:163], v[220:223], 0
	v_mfma_f32_16x16x32_bf16 v[14:17], v[170:173], v[220:223], 0
	v_mfma_f32_16x16x32_bf16 v[62:65], v[166:169], v[200:203], v[62:65]
	v_mfma_f32_16x16x32_bf16 v[58:61], v[174:177], v[200:203], v[58:61]
	v_mfma_f32_16x16x32_bf16 v[54:57], v[166:169], v[208:211], v[54:57]
	v_mfma_f32_16x16x32_bf16 v[46:49], v[174:177], v[208:211], v[46:49]
	v_mfma_f32_16x16x32_bf16 v[38:41], v[166:169], v[216:219], v[38:41]
	v_mfma_f32_16x16x32_bf16 v[30:33], v[174:177], v[216:219], v[30:33]
	v_mfma_f32_16x16x32_bf16 v[22:25], v[166:169], v[224:227], v[22:25]
	v_mfma_f32_16x16x32_bf16 v[14:17], v[174:177], v[224:227], v[14:17]
	v_mfma_f32_16x16x32_bf16 v[50:53], v[178:181], v[196:199], 0
	v_mfma_f32_16x16x32_bf16 v[42:45], v[188:191], v[196:199], 0
	v_mfma_f32_16x16x32_bf16 v[34:37], v[178:181], v[204:207], 0
	v_mfma_f32_16x16x32_bf16 v[26:29], v[188:191], v[204:207], 0
	v_mfma_f32_16x16x32_bf16 v[18:21], v[178:181], v[212:215], 0
	v_mfma_f32_16x16x32_bf16 v[10:13], v[188:191], v[212:215], 0
	v_mfma_f32_16x16x32_bf16 v[6:9], v[178:181], v[220:223], 0
	v_mfma_f32_16x16x32_bf16 v[2:5], v[188:191], v[220:223], 0
	v_mfma_f32_16x16x32_bf16 v[50:53], v[184:187], v[200:203], v[50:53]
	v_mfma_f32_16x16x32_bf16 v[42:45], v[192:195], v[200:203], v[42:45]
	v_mfma_f32_16x16x32_bf16 v[34:37], v[184:187], v[208:211], v[34:37]
	v_mfma_f32_16x16x32_bf16 v[26:29], v[192:195], v[208:211], v[26:29]
	v_mfma_f32_16x16x32_bf16 v[18:21], v[184:187], v[216:219], v[18:21]
	v_mfma_f32_16x16x32_bf16 v[10:13], v[192:195], v[216:219], v[10:13]
	v_mfma_f32_16x16x32_bf16 v[6:9], v[184:187], v[224:227], v[6:9]
	v_mfma_f32_16x16x32_bf16 v[2:5], v[192:195], v[224:227], v[2:5]
	s_barrier
	s_setprio 0
	s_add_i32 s39, 0, 0x18000
	s_add_i32 s40, 0, 0x1c000
	v_add_u32_e32 v174, s39, v139
	v_add_u32_e32 v192, s40, v139
	ds_read_b128 v[160:163], v174
	ds_read_b128 v[166:169], v174 offset:1024
	ds_read_b128 v[170:173], v174 offset:2048
	ds_read_b128 v[174:177], v174 offset:3072
	ds_read_b128 v[178:181], v192
	ds_read_b128 v[184:187], v192 offset:1024
	ds_read_b128 v[188:191], v192 offset:2048
	ds_read_b128 v[192:195], v192 offset:3072
	s_add_u32 s12, s18, 0x44000
	s_addc_u32 s13, s19, 0
	s_mov_b32 m0, s25
	v_lshl_add_u64 v[236:237], s[12:13], 0, v[130:131]
	ds_read_b128 v[196:199], v165 offset:32768
	ds_read_b128 v[200:203], v165 offset:33792
	ds_read_b128 v[204:207], v165 offset:34816
	ds_read_b128 v[208:211], v165 offset:35840
	ds_read_b128 v[212:215], v165 offset:36864
	ds_read_b128 v[216:219], v165 offset:37888
	ds_read_b128 v[220:223], v165 offset:38912
	ds_read_b128 v[224:227], v165 offset:39936
	global_load_lds_dwordx4 v[236:237], off
	s_mov_b32 m0, s26
	v_lshl_add_u64 v[236:237], s[12:13], 0, v[134:135]
	global_load_lds_dwordx4 v[236:237], off
	s_waitcnt vmcnt(8)
	s_waitcnt lgkmcnt(0)
	s_setprio 1
	s_barrier
	v_mfma_f32_16x16x32_bf16 v[126:129], v[160:163], v[196:199], v[126:129]
	v_mfma_f32_16x16x32_bf16 v[122:125], v[170:173], v[196:199], v[122:125]
	v_mfma_f32_16x16x32_bf16 v[118:121], v[160:163], v[204:207], v[118:121]
	v_mfma_f32_16x16x32_bf16 v[110:113], v[170:173], v[204:207], v[110:113]
	v_mfma_f32_16x16x32_bf16 v[102:105], v[160:163], v[212:215], v[102:105]
	v_mfma_f32_16x16x32_bf16 v[94:97], v[170:173], v[212:215], v[94:97]
	v_mfma_f32_16x16x32_bf16 v[86:89], v[160:163], v[220:223], v[86:89]
	v_mfma_f32_16x16x32_bf16 v[78:81], v[170:173], v[220:223], v[78:81]
	v_mfma_f32_16x16x32_bf16 v[126:129], v[166:169], v[200:203], v[126:129]
	v_mfma_f32_16x16x32_bf16 v[122:125], v[174:177], v[200:203], v[122:125]
	v_mfma_f32_16x16x32_bf16 v[118:121], v[166:169], v[208:211], v[118:121]
	v_mfma_f32_16x16x32_bf16 v[110:113], v[174:177], v[208:211], v[110:113]
	v_mfma_f32_16x16x32_bf16 v[102:105], v[166:169], v[216:219], v[102:105]
	v_mfma_f32_16x16x32_bf16 v[94:97], v[174:177], v[216:219], v[94:97]
	v_mfma_f32_16x16x32_bf16 v[86:89], v[166:169], v[224:227], v[86:89]
	v_mfma_f32_16x16x32_bf16 v[78:81], v[174:177], v[224:227], v[78:81]
	v_mfma_f32_16x16x32_bf16 v[114:117], v[178:181], v[196:199], v[114:117]
	v_mfma_f32_16x16x32_bf16 v[106:109], v[188:191], v[196:199], v[106:109]
	v_mfma_f32_16x16x32_bf16 v[98:101], v[178:181], v[204:207], v[98:101]
	v_mfma_f32_16x16x32_bf16 v[90:93], v[188:191], v[204:207], v[90:93]
	v_mfma_f32_16x16x32_bf16 v[82:85], v[178:181], v[212:215], v[82:85]
	v_mfma_f32_16x16x32_bf16 v[74:77], v[188:191], v[212:215], v[74:77]
	v_mfma_f32_16x16x32_bf16 v[70:73], v[178:181], v[220:223], v[70:73]
	v_mfma_f32_16x16x32_bf16 v[66:69], v[188:191], v[220:223], v[66:69]
	v_mfma_f32_16x16x32_bf16 v[114:117], v[184:187], v[200:203], v[114:117]
	v_mfma_f32_16x16x32_bf16 v[106:109], v[192:195], v[200:203], v[106:109]
	v_mfma_f32_16x16x32_bf16 v[98:101], v[184:187], v[208:211], v[98:101]
	v_mfma_f32_16x16x32_bf16 v[90:93], v[192:195], v[208:211], v[90:93]
	v_mfma_f32_16x16x32_bf16 v[82:85], v[184:187], v[216:219], v[82:85]
	v_mfma_f32_16x16x32_bf16 v[74:77], v[192:195], v[216:219], v[74:77]
	v_mfma_f32_16x16x32_bf16 v[70:73], v[184:187], v[224:227], v[70:73]
	v_mfma_f32_16x16x32_bf16 v[66:69], v[192:195], v[224:227], v[66:69]
	s_barrier
; #define PG8_STAGE(bufoff, gbase, voff) do { _Pragma("unroll") for (int _i = 0; _i < 2; ++_i) \
;         __builtin_amdgcn_global_load_lds((const unsigned*)((const char*)(gbase) + (voff)[_i]), (LAS unsigned*)(lds + (bufoff) + ldsw + _i * 8192), 16, 0, 0); } while (0)
; #define PG8_LDA(dst, b, h) do { _Pragma("unroll") for (int m = 0; m < 4; ++m) _Pragma("unroll") for (int k = 0; k < 2; ++k) dst[m][k] = *(const LAS bf16x8*)(lds + PG8_SA(b, h) + aoff + m * 2048 + k * 1024); } while (0)
; #define PG8_LDB(dst, b, h) do { _Pragma("unroll") for (int n = 0; n < 2; ++n) _Pragma("unroll") for (int k = 0; k < 2; ++k) dst[n][k] = *(const LAS bf16x8*)(lds + PG8_SB(b, h) + boff + n * 2048 + k * 1024); } while (0)
; #define PG8_BAR __builtin_amdgcn_s_barrier()
; template <class Epi, bool ALIGN_EPI = PG8_ALIGN, bool SP2 = PG8_SP2>
; __device__ __forceinline__ void gemm_phase(LAS uchar* lds, const Gemm g, const StaticOrder& S, const Epi& E) {
;     ...
;         for (int t = tb; t < tb + tblk; t += 2) {
;             const bool last = (t == nt - 2);
;             const char* a1 = cA + (size_t)(t + 1) * kstep;
;             const char* a2 = last ? nA : cA + (size_t)(t + 2) * kstep; const char* b2 = last ? nB : cB + (size_t)(t + 2) * kstep;
;             const char* a3 = a2 + kstep; const char* b3 = b2 + kstep;
;             if constexpr (SP2) {
;             PG8_LDB(B0, 0, 0); PG8_LDB(B1, 0, 1); PG8_SCHED; PG8_LDA(At, 0, 0); PG8_STAGE(PG8_SA(1, 1), a1 + hstepA, voffA);
;             PG8_WAIT_V(8); PG8_WAIT_L(0); PG8_BAR; PG8_MMA(0, 0, At, B0); PG8_MMA(0, 1, At, B1); PG8_BAR; PG8_SCHED;
;             PG8_LDA(At, 0, 1); PG8_STAGE(PG8_SB(0, 0), b2, voffB); PG8_STAGE(PG8_SB(0, 1), b2 + hstepB, voffB); PG8_STAGE(PG8_SA(0, 0), a2, voffA);
;             PG8_WAIT_V(8); PG8_WAIT_L(0); PG8_BAR; PG8_MMA(1, 0, At, B0); PG8_MMA(1, 1, At, B1); PG8_BAR; PG8_SCHED;
;             PG8_LDB(B0, 1, 0); PG8_LDB(B1, 1, 1); PG8_SCHED; PG8_LDA(At, 1, 0); PG8_STAGE(PG8_SA(0, 1), a2 + hstepA, voffA);
;             PG8_WAIT_V(8); PG8_WAIT_L(0); PG8_BAR; PG8_MMA(0, 0, At, B0); PG8_MMA(0, 1, At, B1); PG8_BAR; PG8_SCHED;
;             PG8_LDA(At, 1, 1); PG8_STAGE(PG8_SB(1, 0), b3, voffB); PG8_STAGE(PG8_SB(1, 1), b3 + hstepB, voffB); PG8_STAGE(PG8_SA(1, 0), a3, voffA);
;             PG8_WAIT_V(8); PG8_WAIT_L(0); PG8_BAR; PG8_MMA(1, 0, At, B0); PG8_MMA(1, 1, At, B1); PG8_BAR; PG8_SCHED;
	s_setprio 0
	s_add_i32 s12, s39, s22
	v_lshl_add_u64 v[228:229], v[228:229], 0, s[84:85]
	s_mov_b32 m0, s12
	ds_read_b128 v[196:199], v165 offset:49152
	ds_read_b128 v[200:203], v165 offset:50176
	ds_read_b128 v[204:207], v165 offset:51200
	ds_read_b128 v[208:211], v165 offset:52224
	ds_read_b128 v[212:215], v165 offset:53248
	ds_read_b128 v[216:219], v165 offset:54272
	ds_read_b128 v[220:223], v165 offset:55296
	ds_read_b128 v[224:227], v165 offset:56320
	global_load_lds_dwordx4 v[228:229], off
	s_add_i32 m0, s12, 0x2000
	s_add_u32 s12, s16, 0x44080
	v_lshl_add_u64 v[228:229], v[230:231], 0, s[84:85]
	s_addc_u32 s13, s17, 0
	s_add_i32 s16, s40, s22
	global_load_lds_dwordx4 v[228:229], off
	s_mov_b32 m0, s16
	v_lshl_add_u64 v[228:229], s[12:13], 0, v[132:133]
	global_load_lds_dwordx4 v[228:229], off
	s_add_i32 m0, s16, 0x2000
	v_lshl_add_u64 v[228:229], s[12:13], 0, v[152:153]
	global_load_lds_dwordx4 v[228:229], off
	s_mov_b32 m0, s27
	v_lshl_add_u64 v[228:229], v[232:233], 0, s[84:85]
	global_load_lds_dwordx4 v[228:229], off
	s_mov_b32 m0, s28
	v_lshl_add_u64 v[228:229], v[234:235], 0, s[84:85]
	global_load_lds_dwordx4 v[228:229], off
	s_waitcnt vmcnt(8)
	s_waitcnt lgkmcnt(0)
	s_setprio 1
	s_barrier
	v_mfma_f32_16x16x32_bf16 v[62:65], v[160:163], v[196:199], v[62:65]
	v_mfma_f32_16x16x32_bf16 v[58:61], v[170:173], v[196:199], v[58:61]
	v_mfma_f32_16x16x32_bf16 v[54:57], v[160:163], v[204:207], v[54:57]
	v_mfma_f32_16x16x32_bf16 v[46:49], v[170:173], v[204:207], v[46:49]
	v_mfma_f32_16x16x32_bf16 v[38:41], v[160:163], v[212:215], v[38:41]
	v_mfma_f32_16x16x32_bf16 v[30:33], v[170:173], v[212:215], v[30:33]
	v_mfma_f32_16x16x32_bf16 v[22:25], v[160:163], v[220:223], v[22:25]
	v_mfma_f32_16x16x32_bf16 v[14:17], v[170:173], v[220:223], v[14:17]
	v_mfma_f32_16x16x32_bf16 v[62:65], v[166:169], v[200:203], v[62:65]
	v_mfma_f32_16x16x32_bf16 v[58:61], v[174:177], v[200:203], v[58:61]
	v_mfma_f32_16x16x32_bf16 v[54:57], v[166:169], v[208:211], v[54:57]
	v_mfma_f32_16x16x32_bf16 v[46:49], v[174:177], v[208:211], v[46:49]
	v_mfma_f32_16x16x32_bf16 v[38:41], v[166:169], v[216:219], v[38:41]
	v_mfma_f32_16x16x32_bf16 v[30:33], v[174:177], v[216:219], v[30:33]
	v_mfma_f32_16x16x32_bf16 v[22:25], v[166:169], v[224:227], v[22:25]
	v_mfma_f32_16x16x32_bf16 v[14:17], v[174:177], v[224:227], v[14:17]
	v_mfma_f32_16x16x32_bf16 v[50:53], v[178:181], v[196:199], v[50:53]
	v_mfma_f32_16x16x32_bf16 v[42:45], v[188:191], v[196:199], v[42:45]
	v_mfma_f32_16x16x32_bf16 v[34:37], v[178:181], v[204:207], v[34:37]
	v_mfma_f32_16x16x32_bf16 v[26:29], v[188:191], v[204:207], v[26:29]
	v_mfma_f32_16x16x32_bf16 v[18:21], v[178:181], v[212:215], v[18:21]
	v_mfma_f32_16x16x32_bf16 v[10:13], v[188:191], v[212:215], v[10:13]
	v_mfma_f32_16x16x32_bf16 v[6:9], v[178:181], v[220:223], v[6:9]
	v_mfma_f32_16x16x32_bf16 v[2:5], v[188:191], v[220:223], v[2:5]
	v_mfma_f32_16x16x32_bf16 v[50:53], v[184:187], v[200:203], v[50:53]
	v_mfma_f32_16x16x32_bf16 v[42:45], v[192:195], v[200:203], v[42:45]
	v_mfma_f32_16x16x32_bf16 v[34:37], v[184:187], v[208:211], v[34:37]
	v_mfma_f32_16x16x32_bf16 v[26:29], v[192:195], v[208:211], v[26:29]
	v_mfma_f32_16x16x32_bf16 v[18:21], v[184:187], v[216:219], v[18:21]
	v_mfma_f32_16x16x32_bf16 v[10:13], v[192:195], v[216:219], v[10:13]
	v_mfma_f32_16x16x32_bf16 v[6:9], v[184:187], v[224:227], v[6:9]
	v_mfma_f32_16x16x32_bf16 v[2:5], v[192:195], v[224:227], v[2:5]
	s_barrier
	s_setprio 0
	s_add_i32 s38, s38, 2
	s_add_u32 s36, s36, 0x100
	s_addc_u32 s37, s37, 0
	s_cmp_gt_u32 s38, 13
	s_mov_b64 s[12:13], s[14:15]
.LBB0_837:
	s_add_u32 s14, s12, 0x100
	s_addc_u32 s15, s13, 0
	s_add_i32 s39, 0, 0x10000
	s_cmp_eq_u32 s38, 12
	s_cselect_b32 s19, s5, s15
	s_cselect_b32 s18, s4, s14
	s_cselect_b32 s17, s11, s37
	s_cselect_b32 s16, s10, s36
	s_add_i32 s40, 0, 0x14000
	v_add_u32_e32 v174, s39, v139
	v_add_u32_e32 v192, s40, v139
	ds_read_b128 v[160:163], v174
	ds_read_b128 v[166:169], v174 offset:1024
	ds_read_b128 v[170:173], v174 offset:2048
	ds_read_b128 v[174:177], v174 offset:3072
	ds_read_b128 v[178:181], v192
	ds_read_b128 v[184:187], v192 offset:1024
	ds_read_b128 v[188:191], v192 offset:2048
	ds_read_b128 v[192:195], v192 offset:3072
	v_lshl_add_u64 v[228:229], s[12:13], 0, v[156:157]
	s_add_i32 m0, s23, 0xc000
	ds_read_b128 v[196:199], v165
	ds_read_b128 v[200:203], v165 offset:1024
	ds_read_b128 v[204:207], v165 offset:2048
	ds_read_b128 v[208:211], v165 offset:3072
	ds_read_b128 v[212:215], v165 offset:4096
	ds_read_b128 v[216:219], v165 offset:5120
	ds_read_b128 v[220:223], v165 offset:6144
	ds_read_b128 v[224:227], v165 offset:7168
	global_load_lds_dwordx4 v[228:229], off
	s_add_i32 m0, s23, 0xe000
	v_lshl_add_u64 v[228:229], s[12:13], 0, v[158:159]
	global_load_lds_dwordx4 v[228:229], off
	s_waitcnt vmcnt(8)
	s_waitcnt lgkmcnt(0)
	s_setprio 1
	s_barrier
; #define PG8_STAGE(bufoff, gbase, voff) do { _Pragma("unroll") for (int _i = 0; _i < 2; ++_i) \
;         __builtin_amdgcn_global_load_lds((const unsigned*)((const char*)(gbase) + (voff)[_i]), (LAS unsigned*)(lds + (bufoff) + ldsw + _i * 8192), 16, 0, 0); } while (0)
; #define PG8_LDA(dst, b, h) do { _Pragma("unroll") for (int m = 0; m < 4; ++m) _Pragma("unroll") for (int k = 0; k < 2; ++k) dst[m][k] = *(const LAS bf16x8*)(lds + PG8_SA(b, h) + aoff + m * 2048 + k * 1024); } while (0)
; #define PG8_LDB(dst, b, h) do { _Pragma("unroll") for (int n = 0; n < 2; ++n) _Pragma("unroll") for (int k = 0; k < 2; ++k) dst[n][k] = *(const LAS bf16x8*)(lds + PG8_SB(b, h) + boff + n * 2048 + k * 1024); } while (0)
; #define PG8_BAR __builtin_amdgcn_s_barrier()
; template <class Epi, bool ALIGN_EPI = PG8_ALIGN, bool SP2 = PG8_SP2>
; __device__ __forceinline__ void gemm_phase(LAS uchar* lds, const Gemm g, const StaticOrder& S, const Epi& E) {
;     ...
;         for (int t = tb; t < tb + tblk; t += 2) {
;             const bool last = (t == nt - 2);
;             const char* a1 = cA + (size_t)(t + 1) * kstep;
;             const char* a2 = last ? nA : cA + (size_t)(t + 2) * kstep; const char* b2 = last ? nB : cB + (size_t)(t + 2) * kstep;
;             const char* a3 = a2 + kstep; const char* b3 = b2 + kstep;
;             if constexpr (SP2) {
;             PG8_LDB(B0, 0, 0); PG8_LDB(B1, 0, 1); PG8_SCHED; PG8_LDA(At, 0, 0); PG8_STAGE(PG8_SA(1, 1), a1 + hstepA, voffA);
;             PG8_WAIT_V(8); PG8_WAIT_L(0); PG8_BAR; PG8_MMA(0, 0, At, B0); PG8_MMA(0, 1, At, B1); PG8_BAR; PG8_SCHED;
;             PG8_LDA(At, 0, 1); PG8_STAGE(PG8_SB(0, 0), b2, voffB); PG8_STAGE(PG8_SB(0, 1), b2 + hstepB, voffB); PG8_STAGE(PG8_SA(0, 0), a2, voffA);
;             PG8_WAIT_V(8); PG8_WAIT_L(0); PG8_BAR; PG8_MMA(1, 0, At, B0); PG8_MMA(1, 1, At, B1); PG8_BAR; PG8_SCHED;
;             PG8_LDB(B0, 1, 0); PG8_LDB(B1, 1, 1); PG8_SCHED; PG8_LDA(At, 1, 0); PG8_STAGE(PG8_SA(0, 1), a2 + hstepA, voffA);
;             PG8_WAIT_V(8); PG8_WAIT_L(0); PG8_BAR; PG8_MMA(0, 0, At, B0); PG8_MMA(0, 1, At, B1); PG8_BAR; PG8_SCHED;
;             PG8_LDA(At, 1, 1); PG8_STAGE(PG8_SB(1, 0), b3, voffB); PG8_STAGE(PG8_SB(1, 1), b3 + hstepB, voffB); PG8_STAGE(PG8_SA(1, 0), a3, voffA);
;             PG8_WAIT_V(8); PG8_WAIT_L(0); PG8_BAR; PG8_MMA(1, 0, At, B0); PG8_MMA(1, 1, At, B1); PG8_BAR; PG8_SCHED;
	v_mfma_f32_16x16x32_bf16 v[126:129], v[160:163], v[196:199], v[126:129]
	v_mfma_f32_16x16x32_bf16 v[122:125], v[170:173], v[196:199], v[122:125]
	v_mfma_f32_16x16x32_bf16 v[118:121], v[160:163], v[204:207], v[118:121]
	v_mfma_f32_16x16x32_bf16 v[110:113], v[170:173], v[204:207], v[110:113]
	v_mfma_f32_16x16x32_bf16 v[102:105], v[160:163], v[212:215], v[102:105]
	v_mfma_f32_16x16x32_bf16 v[94:97], v[170:173], v[212:215], v[94:97]
	v_mfma_f32_16x16x32_bf16 v[86:89], v[160:163], v[220:223], v[86:89]
	v_mfma_f32_16x16x32_bf16 v[78:81], v[170:173], v[220:223], v[78:81]
	v_mfma_f32_16x16x32_bf16 v[126:129], v[166:169], v[200:203], v[126:129]
	v_mfma_f32_16x16x32_bf16 v[122:125], v[174:177], v[200:203], v[122:125]
	v_mfma_f32_16x16x32_bf16 v[118:121], v[166:169], v[208:211], v[118:121]
	v_mfma_f32_16x16x32_bf16 v[110:113], v[174:177], v[208:211], v[110:113]
	v_mfma_f32_16x16x32_bf16 v[102:105], v[166:169], v[216:219], v[102:105]
	v_mfma_f32_16x16x32_bf16 v[94:97], v[174:177], v[216:219], v[94:97]
	v_mfma_f32_16x16x32_bf16 v[86:89], v[166:169], v[224:227], v[86:89]
	v_mfma_f32_16x16x32_bf16 v[78:81], v[174:177], v[224:227], v[78:81]
	v_mfma_f32_16x16x32_bf16 v[114:117], v[178:181], v[196:199], v[114:117]
	v_mfma_f32_16x16x32_bf16 v[106:109], v[188:191], v[196:199], v[106:109]
	v_mfma_f32_16x16x32_bf16 v[98:101], v[178:181], v[204:207], v[98:101]
	v_mfma_f32_16x16x32_bf16 v[90:93], v[188:191], v[204:207], v[90:93]
	v_mfma_f32_16x16x32_bf16 v[82:85], v[178:181], v[212:215], v[82:85]
	v_mfma_f32_16x16x32_bf16 v[74:77], v[188:191], v[212:215], v[74:77]
	v_mfma_f32_16x16x32_bf16 v[70:73], v[178:181], v[220:223], v[70:73]
	v_mfma_f32_16x16x32_bf16 v[66:69], v[188:191], v[220:223], v[66:69]
	v_mfma_f32_16x16x32_bf16 v[114:117], v[184:187], v[200:203], v[114:117]
	v_mfma_f32_16x16x32_bf16 v[106:109], v[192:195], v[200:203], v[106:109]
	v_mfma_f32_16x16x32_bf16 v[98:101], v[184:187], v[208:211], v[98:101]
	v_mfma_f32_16x16x32_bf16 v[90:93], v[192:195], v[208:211], v[90:93]
	v_mfma_f32_16x16x32_bf16 v[82:85], v[184:187], v[216:219], v[82:85]
	v_mfma_f32_16x16x32_bf16 v[74:77], v[192:195], v[216:219], v[74:77]
	v_mfma_f32_16x16x32_bf16 v[70:73], v[184:187], v[224:227], v[70:73]
	v_mfma_f32_16x16x32_bf16 v[66:69], v[192:195], v[224:227], v[66:69]
	s_barrier
	s_setprio 0
	s_add_i32 s12, s39, s22
	v_lshl_add_u64 v[228:229], s[16:17], 0, v[132:133]
	s_mov_b32 m0, s12
	ds_read_b128 v[196:199], v165 offset:16384
	ds_read_b128 v[200:203], v165 offset:17408
	ds_read_b128 v[204:207], v165 offset:18432
	ds_read_b128 v[208:211], v165 offset:19456
	ds_read_b128 v[212:215], v165 offset:20480
	ds_read_b128 v[216:219], v165 offset:21504
	ds_read_b128 v[220:223], v165 offset:22528
	ds_read_b128 v[224:227], v165 offset:23552
	global_load_lds_dwordx4 v[228:229], off
	s_add_i32 m0, s12, 0x2000
	s_add_u32 s12, s16, 0x44000
	v_lshl_add_u64 v[230:231], s[16:17], 0, v[152:153]
	s_addc_u32 s13, s17, 0
	s_add_i32 s39, s40, s22
	global_load_lds_dwordx4 v[230:231], off
	v_lshl_add_u64 v[232:233], s[12:13], 0, v[132:133]
	s_mov_b32 m0, s39
	global_load_lds_dwordx4 v[232:233], off
	s_add_i32 m0, s39, 0x2000
	v_lshl_add_u64 v[232:233], s[12:13], 0, v[152:153]
	global_load_lds_dwordx4 v[232:233], off
	s_mov_b32 m0, s23
	v_lshl_add_u64 v[232:233], s[18:19], 0, v[130:131]
	global_load_lds_dwordx4 v[232:233], off
	s_mov_b32 m0, s24
	v_lshl_add_u64 v[234:235], s[18:19], 0, v[134:135]
	global_load_lds_dwordx4 v[234:235], off
	s_waitcnt vmcnt(8)
	s_waitcnt lgkmcnt(0)
	s_setprio 1
	s_barrier
	v_mfma_f32_16x16x32_bf16 v[62:65], v[160:163], v[196:199], v[62:65]
	v_mfma_f32_16x16x32_bf16 v[58:61], v[170:173], v[196:199], v[58:61]
	v_mfma_f32_16x16x32_bf16 v[54:57], v[160:163], v[204:207], v[54:57]
	v_mfma_f32_16x16x32_bf16 v[46:49], v[170:173], v[204:207], v[46:49]
	v_mfma_f32_16x16x32_bf16 v[38:41], v[160:163], v[212:215], v[38:41]
	v_mfma_f32_16x16x32_bf16 v[30:33], v[170:173], v[212:215], v[30:33]
	v_mfma_f32_16x16x32_bf16 v[22:25], v[160:163], v[220:223], v[22:25]
	v_mfma_f32_16x16x32_bf16 v[14:17], v[170:173], v[220:223], v[14:17]
	v_mfma_f32_16x16x32_bf16 v[62:65], v[166:169], v[200:203], v[62:65]
	v_mfma_f32_16x16x32_bf16 v[58:61], v[174:177], v[200:203], v[58:61]
	v_mfma_f32_16x16x32_bf16 v[54:57], v[166:169], v[208:211], v[54:57]
	v_mfma_f32_16x16x32_bf16 v[46:49], v[174:177], v[208:211], v[46:49]
	v_mfma_f32_16x16x32_bf16 v[38:41], v[166:169], v[216:219], v[38:41]
	v_mfma_f32_16x16x32_bf16 v[30:33], v[174:177], v[216:219], v[30:33]
	v_mfma_f32_16x16x32_bf16 v[22:25], v[166:169], v[224:227], v[22:25]
	v_mfma_f32_16x16x32_bf16 v[14:17], v[174:177], v[224:227], v[14:17]
	v_mfma_f32_16x16x32_bf16 v[50:53], v[178:181], v[196:199], v[50:53]
	v_mfma_f32_16x16x32_bf16 v[42:45], v[188:191], v[196:199], v[42:45]
	v_mfma_f32_16x16x32_bf16 v[34:37], v[178:181], v[204:207], v[34:37]
	v_mfma_f32_16x16x32_bf16 v[26:29], v[188:191], v[204:207], v[26:29]
	v_mfma_f32_16x16x32_bf16 v[18:21], v[178:181], v[212:215], v[18:21]
	v_mfma_f32_16x16x32_bf16 v[10:13], v[188:191], v[212:215], v[10:13]
	v_mfma_f32_16x16x32_bf16 v[6:9], v[178:181], v[220:223], v[6:9]
	v_mfma_f32_16x16x32_bf16 v[2:5], v[188:191], v[220:223], v[2:5]
	v_mfma_f32_16x16x32_bf16 v[50:53], v[184:187], v[200:203], v[50:53]
	v_mfma_f32_16x16x32_bf16 v[42:45], v[192:195], v[200:203], v[42:45]
	v_mfma_f32_16x16x32_bf16 v[34:37], v[184:187], v[208:211], v[34:37]
	v_mfma_f32_16x16x32_bf16 v[26:29], v[192:195], v[208:211], v[26:29]
	v_mfma_f32_16x16x32_bf16 v[18:21], v[184:187], v[216:219], v[18:21]
	v_mfma_f32_16x16x32_bf16 v[10:13], v[192:195], v[216:219], v[10:13]
	v_mfma_f32_16x16x32_bf16 v[6:9], v[184:187], v[224:227], v[6:9]
	v_mfma_f32_16x16x32_bf16 v[2:5], v[192:195], v[224:227], v[2:5]
	s_barrier
; #define PG8_STAGE(bufoff, gbase, voff) do { _Pragma("unroll") for (int _i = 0; _i < 2; ++_i) \
;         __builtin_amdgcn_global_load_lds((const unsigned*)((const char*)(gbase) + (voff)[_i]), (LAS unsigned*)(lds + (bufoff) + ldsw + _i * 8192), 16, 0, 0); } while (0)
; #define PG8_LDA(dst, b, h) do { _Pragma("unroll") for (int m = 0; m < 4; ++m) _Pragma("unroll") for (int k = 0; k < 2; ++k) dst[m][k] = *(const LAS bf16x8*)(lds + PG8_SA(b, h) + aoff + m * 2048 + k * 1024); } while (0)
; #define PG8_LDB(dst, b, h) do { _Pragma("unroll") for (int n = 0; n < 2; ++n) _Pragma("unroll") for (int k = 0; k < 2; ++k) dst[n][k] = *(const LAS bf16x8*)(lds + PG8_SB(b, h) + boff + n * 2048 + k * 1024); } while (0)
; #define PG8_BAR __builtin_amdgcn_s_barrier()
; template <class Epi, bool ALIGN_EPI = PG8_ALIGN, bool SP2 = PG8_SP2>
; __device__ __forceinline__ void gemm_phase(LAS uchar* lds, const Gemm g, const StaticOrder& S, const Epi& E) {
;     ...
;         for (int t = tb; t < tb + tblk; t += 2) {
;             const bool last = (t == nt - 2);
;             const char* a1 = cA + (size_t)(t + 1) * kstep;
;             const char* a2 = last ? nA : cA + (size_t)(t + 2) * kstep; const char* b2 = last ? nB : cB + (size_t)(t + 2) * kstep;
;             const char* a3 = a2 + kstep; const char* b3 = b2 + kstep;
;             if constexpr (SP2) {
;             PG8_LDB(B0, 0, 0); PG8_LDB(B1, 0, 1); PG8_SCHED; PG8_LDA(At, 0, 0); PG8_STAGE(PG8_SA(1, 1), a1 + hstepA, voffA);
;             PG8_WAIT_V(8); PG8_WAIT_L(0); PG8_BAR; PG8_MMA(0, 0, At, B0); PG8_MMA(0, 1, At, B1); PG8_BAR; PG8_SCHED;
;             PG8_LDA(At, 0, 1); PG8_STAGE(PG8_SB(0, 0), b2, voffB); PG8_STAGE(PG8_SB(0, 1), b2 + hstepB, voffB); PG8_STAGE(PG8_SA(0, 0), a2, voffA);
;             PG8_WAIT_V(8); PG8_WAIT_L(0); PG8_BAR; PG8_MMA(1, 0, At, B0); PG8_MMA(1, 1, At, B1); PG8_BAR; PG8_SCHED;
;             PG8_LDB(B0, 1, 0); PG8_LDB(B1, 1, 1); PG8_SCHED; PG8_LDA(At, 1, 0); PG8_STAGE(PG8_SA(0, 1), a2 + hstepA, voffA);
;             PG8_WAIT_V(8); PG8_WAIT_L(0); PG8_BAR; PG8_MMA(0, 0, At, B0); PG8_MMA(0, 1, At, B1); PG8_BAR; PG8_SCHED;
;             PG8_LDA(At, 1, 1); PG8_STAGE(PG8_SB(1, 0), b3, voffB); PG8_STAGE(PG8_SB(1, 1), b3 + hstepB, voffB); PG8_STAGE(PG8_SA(1, 0), a3, voffA);
;             PG8_WAIT_V(8); PG8_WAIT_L(0); PG8_BAR; PG8_MMA(1, 0, At, B0); PG8_MMA(1, 1, At, B1); PG8_BAR; PG8_SCHED;
	s_setprio 0
	s_add_i32 s39, 0, 0x18000
	s_add_i32 s40, 0, 0x1c000
	v_add_u32_e32 v174, s39, v139
	v_add_u32_e32 v192, s40, v139
	ds_read_b128 v[160:163], v174
	ds_read_b128 v[166:169], v174 offset:1024
	ds_read_b128 v[170:173], v174 offset:2048
	ds_read_b128 v[174:177], v174 offset:3072
	ds_read_b128 v[178:181], v192
	ds_read_b128 v[184:187], v192 offset:1024
	ds_read_b128 v[188:191], v192 offset:2048
	ds_read_b128 v[192:195], v192 offset:3072
	s_add_u32 s12, s18, 0x44000
	s_addc_u32 s13, s19, 0
	s_mov_b32 m0, s25
	v_lshl_add_u64 v[236:237], s[12:13], 0, v[130:131]
	ds_read_b128 v[196:199], v165 offset:32768
	ds_read_b128 v[200:203], v165 offset:33792
	ds_read_b128 v[204:207], v165 offset:34816
	ds_read_b128 v[208:211], v165 offset:35840
	ds_read_b128 v[212:215], v165 offset:36864
	ds_read_b128 v[216:219], v165 offset:37888
	ds_read_b128 v[220:223], v165 offset:38912
	ds_read_b128 v[224:227], v165 offset:39936
	global_load_lds_dwordx4 v[236:237], off
	s_mov_b32 m0, s26
	v_lshl_add_u64 v[236:237], s[12:13], 0, v[134:135]
	global_load_lds_dwordx4 v[236:237], off
	s_waitcnt vmcnt(8)
	s_waitcnt lgkmcnt(0)
	s_setprio 1
	s_barrier
	v_mfma_f32_16x16x32_bf16 v[126:129], v[160:163], v[196:199], v[126:129]
	v_mfma_f32_16x16x32_bf16 v[122:125], v[170:173], v[196:199], v[122:125]
	v_mfma_f32_16x16x32_bf16 v[118:121], v[160:163], v[204:207], v[118:121]
	v_mfma_f32_16x16x32_bf16 v[110:113], v[170:173], v[204:207], v[110:113]
	v_mfma_f32_16x16x32_bf16 v[102:105], v[160:163], v[212:215], v[102:105]
	v_mfma_f32_16x16x32_bf16 v[94:97], v[170:173], v[212:215], v[94:97]
	v_mfma_f32_16x16x32_bf16 v[86:89], v[160:163], v[220:223], v[86:89]
	v_mfma_f32_16x16x32_bf16 v[78:81], v[170:173], v[220:223], v[78:81]
	v_mfma_f32_16x16x32_bf16 v[126:129], v[166:169], v[200:203], v[126:129]
	v_mfma_f32_16x16x32_bf16 v[122:125], v[174:177], v[200:203], v[122:125]
	v_mfma_f32_16x16x32_bf16 v[118:121], v[166:169], v[208:211], v[118:121]
	v_mfma_f32_16x16x32_bf16 v[110:113], v[174:177], v[208:211], v[110:113]
	v_mfma_f32_16x16x32_bf16 v[102:105], v[166:169], v[216:219], v[102:105]
	v_mfma_f32_16x16x32_bf16 v[94:97], v[174:177], v[216:219], v[94:97]
	v_mfma_f32_16x16x32_bf16 v[86:89], v[166:169], v[224:227], v[86:89]
	v_mfma_f32_16x16x32_bf16 v[78:81], v[174:177], v[224:227], v[78:81]
	v_mfma_f32_16x16x32_bf16 v[114:117], v[178:181], v[196:199], v[114:117]
	v_mfma_f32_16x16x32_bf16 v[106:109], v[188:191], v[196:199], v[106:109]
	v_mfma_f32_16x16x32_bf16 v[98:101], v[178:181], v[204:207], v[98:101]
	v_mfma_f32_16x16x32_bf16 v[90:93], v[188:191], v[204:207], v[90:93]
	v_mfma_f32_16x16x32_bf16 v[82:85], v[178:181], v[212:215], v[82:85]
	v_mfma_f32_16x16x32_bf16 v[74:77], v[188:191], v[212:215], v[74:77]
	v_mfma_f32_16x16x32_bf16 v[70:73], v[178:181], v[220:223], v[70:73]
	v_mfma_f32_16x16x32_bf16 v[66:69], v[188:191], v[220:223], v[66:69]
	v_mfma_f32_16x16x32_bf16 v[114:117], v[184:187], v[200:203], v[114:117]
	v_mfma_f32_16x16x32_bf16 v[106:109], v[192:195], v[200:203], v[106:109]
	v_mfma_f32_16x16x32_bf16 v[98:101], v[184:187], v[208:211], v[98:101]
	v_mfma_f32_16x16x32_bf16 v[90:93], v[192:195], v[208:211], v[90:93]
	v_mfma_f32_16x16x32_bf16 v[82:85], v[184:187], v[216:219], v[82:85]
	v_mfma_f32_16x16x32_bf16 v[74:77], v[192:195], v[216:219], v[74:77]
	v_mfma_f32_16x16x32_bf16 v[70:73], v[184:187], v[224:227], v[70:73]
	v_mfma_f32_16x16x32_bf16 v[66:69], v[192:195], v[224:227], v[66:69]
	s_barrier
; #define PG8_STAGE(bufoff, gbase, voff) do { _Pragma("unroll") for (int _i = 0; _i < 2; ++_i) \
;         __builtin_amdgcn_global_load_lds((const unsigned*)((const char*)(gbase) + (voff)[_i]), (LAS unsigned*)(lds + (bufoff) + ldsw + _i * 8192), 16, 0, 0); } while (0)
; #define PG8_LDA(dst, b, h) do { _Pragma("unroll") for (int m = 0; m < 4; ++m) _Pragma("unroll") for (int k = 0; k < 2; ++k) dst[m][k] = *(const LAS bf16x8*)(lds + PG8_SA(b, h) + aoff + m * 2048 + k * 1024); } while (0)
; #define PG8_LDB(dst, b, h) do { _Pragma("unroll") for (int n = 0; n < 2; ++n) _Pragma("unroll") for (int k = 0; k < 2; ++k) dst[n][k] = *(const LAS bf16x8*)(lds + PG8_SB(b, h) + boff + n * 2048 + k * 1024); } while (0)
; template <class Epi, bool ALIGN_EPI = PG8_ALIGN, bool SP2 = PG8_SP2>
; __device__ __forceinline__ void gemm_phase(LAS uchar* lds, const Gemm g, const StaticOrder& S, const Epi& E) {
;     ...
;         for (int t = tb; t < tb + tblk; t += 2) {
;             const bool last = (t == nt - 2);
;             const char* a1 = cA + (size_t)(t + 1) * kstep;
;             const char* a2 = last ? nA : cA + (size_t)(t + 2) * kstep; const char* b2 = last ? nB : cB + (size_t)(t + 2) * kstep;
;             const char* a3 = a2 + kstep; const char* b3 = b2 + kstep;
;             if constexpr (SP2) {
;             PG8_LDB(B0, 0, 0); PG8_LDB(B1, 0, 1); PG8_SCHED; PG8_LDA(At, 0, 0); PG8_STAGE(PG8_SA(1, 1), a1 + hstepA, voffA);
;             PG8_WAIT_V(8); PG8_WAIT_L(0); PG8_BAR; PG8_MMA(0, 0, At, B0); PG8_MMA(0, 1, At, B1); PG8_BAR; PG8_SCHED;
;             PG8_LDA(At, 0, 1); PG8_STAGE(PG8_SB(0, 0), b2, voffB); PG8_STAGE(PG8_SB(0, 1), b2 + hstepB, voffB); PG8_STAGE(PG8_SA(0, 0), a2, voffA);
;             PG8_WAIT_V(8); PG8_WAIT_L(0); PG8_BAR; PG8_MMA(1, 0, At, B0); PG8_MMA(1, 1, At, B1); PG8_BAR; PG8_SCHED;
;             PG8_LDB(B0, 1, 0); PG8_LDB(B1, 1, 1); PG8_SCHED; PG8_LDA(At, 1, 0); PG8_STAGE(PG8_SA(0, 1), a2 + hstepA, voffA);
;             PG8_WAIT_V(8); PG8_WAIT_L(0); PG8_BAR; PG8_MMA(0, 0, At, B0); PG8_MMA(0, 1, At, B1); PG8_BAR; PG8_SCHED;
;             PG8_LDA(At, 1, 1); PG8_STAGE(PG8_SB(1, 0), b3, voffB); PG8_STAGE(PG8_SB(1, 1), b3 + hstepB, voffB); PG8_STAGE(PG8_SA(1, 0), a3, voffA);
;             PG8_WAIT_V(8); PG8_WAIT_L(0); PG8_BAR; PG8_MMA(1, 0, At, B0); PG8_MMA(1, 1, At, B1); PG8_BAR; PG8_SCHED;
;     ...
;         if constexpr (ALIGN_EPI) { if (wr == 0) PG8_BAR; }
	s_setprio 0
	s_add_i32 s12, s39, s22
	v_lshl_add_u64 v[228:229], v[228:229], 0, s[84:85]
	s_mov_b32 m0, s12
	ds_read_b128 v[196:199], v165 offset:49152
	ds_read_b128 v[200:203], v165 offset:50176
	ds_read_b128 v[204:207], v165 offset:51200
	ds_read_b128 v[208:211], v165 offset:52224
	ds_read_b128 v[212:215], v165 offset:53248
	ds_read_b128 v[216:219], v165 offset:54272
	ds_read_b128 v[220:223], v165 offset:55296
	ds_read_b128 v[224:227], v165 offset:56320
	global_load_lds_dwordx4 v[228:229], off
	s_add_i32 m0, s12, 0x2000
	s_add_u32 s12, s16, 0x44080
	v_lshl_add_u64 v[228:229], v[230:231], 0, s[84:85]
	s_addc_u32 s13, s17, 0
	s_add_i32 s16, s40, s22
	global_load_lds_dwordx4 v[228:229], off
	s_mov_b32 m0, s16
	v_lshl_add_u64 v[228:229], s[12:13], 0, v[132:133]
	global_load_lds_dwordx4 v[228:229], off
	s_add_i32 m0, s16, 0x2000
	v_lshl_add_u64 v[228:229], s[12:13], 0, v[152:153]
	global_load_lds_dwordx4 v[228:229], off
	s_mov_b32 m0, s27
	v_lshl_add_u64 v[228:229], v[232:233], 0, s[84:85]
	global_load_lds_dwordx4 v[228:229], off
	s_mov_b32 m0, s28
	v_lshl_add_u64 v[228:229], v[234:235], 0, s[84:85]
	global_load_lds_dwordx4 v[228:229], off
	s_waitcnt vmcnt(8)
	s_waitcnt lgkmcnt(0)
	s_setprio 1
	s_barrier
	v_mfma_f32_16x16x32_bf16 v[62:65], v[160:163], v[196:199], v[62:65]
	v_mfma_f32_16x16x32_bf16 v[58:61], v[170:173], v[196:199], v[58:61]
	v_mfma_f32_16x16x32_bf16 v[54:57], v[160:163], v[204:207], v[54:57]
	v_mfma_f32_16x16x32_bf16 v[46:49], v[170:173], v[204:207], v[46:49]
	v_mfma_f32_16x16x32_bf16 v[38:41], v[160:163], v[212:215], v[38:41]
	v_mfma_f32_16x16x32_bf16 v[30:33], v[170:173], v[212:215], v[30:33]
	v_mfma_f32_16x16x32_bf16 v[22:25], v[160:163], v[220:223], v[22:25]
	v_mfma_f32_16x16x32_bf16 v[14:17], v[170:173], v[220:223], v[14:17]
	v_mfma_f32_16x16x32_bf16 v[62:65], v[166:169], v[200:203], v[62:65]
	v_mfma_f32_16x16x32_bf16 v[58:61], v[174:177], v[200:203], v[58:61]
	v_mfma_f32_16x16x32_bf16 v[54:57], v[166:169], v[208:211], v[54:57]
	v_mfma_f32_16x16x32_bf16 v[46:49], v[174:177], v[208:211], v[46:49]
	v_mfma_f32_16x16x32_bf16 v[38:41], v[166:169], v[216:219], v[38:41]
	v_mfma_f32_16x16x32_bf16 v[30:33], v[174:177], v[216:219], v[30:33]
	v_mfma_f32_16x16x32_bf16 v[22:25], v[166:169], v[224:227], v[22:25]
	v_mfma_f32_16x16x32_bf16 v[14:17], v[174:177], v[224:227], v[14:17]
	v_mfma_f32_16x16x32_bf16 v[50:53], v[178:181], v[196:199], v[50:53]
	v_mfma_f32_16x16x32_bf16 v[42:45], v[188:191], v[196:199], v[42:45]
	v_mfma_f32_16x16x32_bf16 v[34:37], v[178:181], v[204:207], v[34:37]
	v_mfma_f32_16x16x32_bf16 v[26:29], v[188:191], v[204:207], v[26:29]
	v_mfma_f32_16x16x32_bf16 v[18:21], v[178:181], v[212:215], v[18:21]
	v_mfma_f32_16x16x32_bf16 v[10:13], v[188:191], v[212:215], v[10:13]
	v_mfma_f32_16x16x32_bf16 v[6:9], v[178:181], v[220:223], v[6:9]
	v_mfma_f32_16x16x32_bf16 v[2:5], v[188:191], v[220:223], v[2:5]
	v_mfma_f32_16x16x32_bf16 v[50:53], v[184:187], v[200:203], v[50:53]
	v_mfma_f32_16x16x32_bf16 v[42:45], v[192:195], v[200:203], v[42:45]
	v_mfma_f32_16x16x32_bf16 v[34:37], v[184:187], v[208:211], v[34:37]
	v_mfma_f32_16x16x32_bf16 v[26:29], v[192:195], v[208:211], v[26:29]
	v_mfma_f32_16x16x32_bf16 v[18:21], v[184:187], v[216:219], v[18:21]
	v_mfma_f32_16x16x32_bf16 v[10:13], v[192:195], v[216:219], v[10:13]
	v_mfma_f32_16x16x32_bf16 v[6:9], v[184:187], v[224:227], v[6:9]
	v_mfma_f32_16x16x32_bf16 v[2:5], v[192:195], v[224:227], v[2:5]
	s_barrier
	s_setprio 0
	s_add_i32 s38, s38, 2
	s_add_u32 s36, s36, 0x100
	s_addc_u32 s37, s37, 0
	s_cmp_gt_u32 s38, 13
	s_mov_b64 s[12:13], s[14:15]
	s_cbranch_scc0 .LBB0_837
	s_and_b64 vcc, exec, s[8:9]
	s_cbranch_vccz .LBB0_840
	s_barrier

; #define PG8_STAGE(bufoff, gbase, voff) do { _Pragma("unroll") for (int _i = 0; _i < 2; ++_i) \
;         __builtin_amdgcn_global_load_lds((const unsigned*)((const char*)(gbase) + (voff)[_i]), (LAS unsigned*)(lds + (bufoff) + ldsw + _i * 8192), 16, 0, 0); } while (0)
; #define PG8_LDA(dst, b, h) do { _Pragma("unroll") for (int m = 0; m < 4; ++m) _Pragma("unroll") for (int k = 0; k < 2; ++k) dst[m][k] = *(const LAS bf16x8*)(lds + PG8_SA(b, h) + aoff + m * 2048 + k * 1024); } while (0)
; #define PG8_LDB(dst, b, h) do { _Pragma("unroll") for (int n = 0; n < 2; ++n) _Pragma("unroll") for (int k = 0; k < 2; ++k) dst[n][k] = *(const LAS bf16x8*)(lds + PG8_SB(b, h) + boff + n * 2048 + k * 1024); } while (0)
; #define PG8_SCHED __builtin_amdgcn_sched_barrier(0)
; template <class Epi, bool ALIGN_EPI = PG8_ALIGN, bool SP2 = PG8_SP2>
; __device__ __forceinline__ void gemm_phase(LAS uchar* lds, const Gemm g, const StaticOrder& S, const Epi& E) {
;     ...
;         for (int t = tb; t < tb + tblk; t += 2) {
;             const bool last = (t == nt - 2);
;             const char* a1 = cA + (size_t)(t + 1) * kstep;
;             const char* a2 = last ? nA : cA + (size_t)(t + 2) * kstep; const char* b2 = last ? nB : cB + (size_t)(t + 2) * kstep;
;             const char* a3 = a2 + kstep; const char* b3 = b2 + kstep;
;             if constexpr (SP2) {
;             PG8_LDB(B0, 0, 0); PG8_LDB(B1, 0, 1); PG8_SCHED; PG8_LDA(At, 0, 0); PG8_STAGE(PG8_SA(1, 1), a1 + hstepA, voffA);
.LBB0_1049:
	s_add_u32 s36, s14, 0x100
	s_addc_u32 s37, s15, 0
	s_mov_b32 s38, -2
	s_add_u32 s14, s12, 0x100
	s_addc_u32 s15, s13, 0
	s_add_i32 s39, 0, 0x10000
	s_cmp_eq_u32 s38, 12
	s_cselect_b32 s19, s1, s15
	s_cselect_b32 s18, s0, s14
	v_add_u32_e32 v144, s39, v139
	s_cselect_b32 s17, s11, s37
	s_cselect_b32 s16, s10, s36
	s_add_i32 s40, 0, 0x14000
	ds_read_b128 v[164:167], v144
	ds_read_b128 v[168:171], v144 offset:1024
	ds_read_b128 v[172:175], v144 offset:2048
	ds_read_b128 v[176:179], v144 offset:3072
	v_add_u32_e32 v144, s40, v139
	ds_read_b128 v[184:187], v144
	ds_read_b128 v[188:191], v144 offset:1024
	ds_read_b128 v[192:195], v144 offset:2048
	ds_read_b128 v[196:199], v144 offset:3072
	v_lshl_add_u64 v[160:161], s[12:13], 0, v[156:157]
	s_add_i32 m0, s23, 0xc000
	ds_read_b128 v[200:203], v163
	ds_read_b128 v[204:207], v163 offset:1024
	ds_read_b128 v[208:211], v163 offset:2048
	ds_read_b128 v[212:215], v163 offset:3072
	ds_read_b128 v[216:219], v163 offset:4096
	ds_read_b128 v[220:223], v163 offset:5120
	ds_read_b128 v[224:227], v163 offset:6144
	ds_read_b128 v[228:231], v163 offset:7168
	global_load_lds_dwordx4 v[160:161], off
	s_add_i32 m0, s23, 0xe000
	v_lshl_add_u64 v[160:161], s[12:13], 0, v[158:159]
	global_load_lds_dwordx4 v[160:161], off
	s_cmp_lt_u32 s29, 2
	s_cbranch_scc1 .Lrw_std_1050_0_pl
	s_waitcnt vmcnt(16)
	s_branch .Lrw_done_1050_0_pl

; #define PG8_STAGE(bufoff, gbase, voff) do { _Pragma("unroll") for (int _i = 0; _i < 2; ++_i) \
;         __builtin_amdgcn_global_load_lds((const unsigned*)((const char*)(gbase) + (voff)[_i]), (LAS unsigned*)(lds + (bufoff) + ldsw + _i * 8192), 16, 0, 0); } while (0)
; #define PG8_LDA(dst, b, h) do { _Pragma("unroll") for (int m = 0; m < 4; ++m) _Pragma("unroll") for (int k = 0; k < 2; ++k) dst[m][k] = *(const LAS bf16x8*)(lds + PG8_SA(b, h) + aoff + m * 2048 + k * 1024); } while (0)
; #define PG8_LDB(dst, b, h) do { _Pragma("unroll") for (int n = 0; n < 2; ++n) _Pragma("unroll") for (int k = 0; k < 2; ++k) dst[n][k] = *(const LAS bf16x8*)(lds + PG8_SB(b, h) + boff + n * 2048 + k * 1024); } while (0)
; #define PG8_MMA(ai, bj, At, Bt) do { __builtin_amdgcn_s_setprio(1); _Pragma("unroll") for (int m = 0; m < 4; ++m) _Pragma("unroll") for (int n = 0; n < 2; ++n) _Pragma("unroll") for (int k = 0; k < 2; ++k) \
;         acc[ai][bj][m][n] = __builtin_amdgcn_mfma_f32_16x16x32_bf16(Bt[n][k], At[m][k], acc[ai][bj][m][n], 0, 0, 0); __builtin_amdgcn_s_setprio(0); } while (0)
; #define PG8_WAIT_V(n) asm volatile("s_waitcnt vmcnt(" #n ")" ::: "memory")
; #define PG8_WAIT_L(n) asm volatile("s_waitcnt lgkmcnt(" #n ")" ::: "memory")
; #define PG8_BAR __builtin_amdgcn_s_barrier()
; #define PG8_SCHED __builtin_amdgcn_sched_barrier(0)
; template <class Epi, bool ALIGN_EPI = PG8_ALIGN, bool SP2 = PG8_SP2>
; __device__ __forceinline__ void gemm_phase(LAS uchar* lds, const Gemm g, const StaticOrder& S, const Epi& E) {
;     ...
;             PG8_LDB(B0, 0, 0); PG8_LDB(B1, 0, 1); PG8_SCHED; PG8_LDA(At, 0, 0); PG8_STAGE(PG8_SA(1, 1), a1 + hstepA, voffA);
;             PG8_WAIT_V(8); PG8_WAIT_L(0); PG8_BAR; PG8_MMA(0, 0, At, B0); PG8_MMA(0, 1, At, B1); PG8_BAR; PG8_SCHED;
;             PG8_LDA(At, 0, 1); PG8_STAGE(PG8_SB(0, 0), b2, voffB); PG8_STAGE(PG8_SB(0, 1), b2 + hstepB, voffB); PG8_STAGE(PG8_SA(0, 0), a2, voffA);
.Lrw_done_1050_0_pl:
	s_waitcnt lgkmcnt(0)
	s_setprio 1
	s_barrier
	v_mfma_f32_16x16x32_bf16 v[126:129], v[164:167], v[200:203], 0
	v_mfma_f32_16x16x32_bf16 v[118:121], v[172:175], v[200:203], 0
	v_mfma_f32_16x16x32_bf16 v[110:113], v[164:167], v[208:211], 0
	v_mfma_f32_16x16x32_bf16 v[102:105], v[172:175], v[208:211], 0
	v_mfma_f32_16x16x32_bf16 v[94:97], v[164:167], v[216:219], 0
	v_mfma_f32_16x16x32_bf16 v[86:89], v[172:175], v[216:219], 0
	v_mfma_f32_16x16x32_bf16 v[78:81], v[164:167], v[224:227], 0
	v_mfma_f32_16x16x32_bf16 v[70:73], v[172:175], v[224:227], 0
	v_mfma_f32_16x16x32_bf16 v[126:129], v[168:171], v[204:207], v[126:129]
	v_mfma_f32_16x16x32_bf16 v[118:121], v[176:179], v[204:207], v[118:121]
	v_mfma_f32_16x16x32_bf16 v[110:113], v[168:171], v[212:215], v[110:113]
	v_mfma_f32_16x16x32_bf16 v[102:105], v[176:179], v[212:215], v[102:105]
	v_mfma_f32_16x16x32_bf16 v[94:97], v[168:171], v[220:223], v[94:97]
	v_mfma_f32_16x16x32_bf16 v[86:89], v[176:179], v[220:223], v[86:89]
	v_mfma_f32_16x16x32_bf16 v[78:81], v[168:171], v[228:231], v[78:81]
	v_mfma_f32_16x16x32_bf16 v[70:73], v[176:179], v[228:231], v[70:73]
	v_mfma_f32_16x16x32_bf16 v[122:125], v[184:187], v[200:203], 0
	v_mfma_f32_16x16x32_bf16 v[114:117], v[192:195], v[200:203], 0
	v_mfma_f32_16x16x32_bf16 v[106:109], v[184:187], v[208:211], 0
	v_mfma_f32_16x16x32_bf16 v[98:101], v[192:195], v[208:211], 0
	v_mfma_f32_16x16x32_bf16 v[90:93], v[184:187], v[216:219], 0
	v_mfma_f32_16x16x32_bf16 v[82:85], v[192:195], v[216:219], 0
	v_mfma_f32_16x16x32_bf16 v[74:77], v[184:187], v[224:227], 0
	v_mfma_f32_16x16x32_bf16 v[66:69], v[192:195], v[224:227], 0
	v_mfma_f32_16x16x32_bf16 v[122:125], v[188:191], v[204:207], v[122:125]
	v_mfma_f32_16x16x32_bf16 v[114:117], v[196:199], v[204:207], v[114:117]
	v_mfma_f32_16x16x32_bf16 v[106:109], v[188:191], v[212:215], v[106:109]
	v_mfma_f32_16x16x32_bf16 v[98:101], v[196:199], v[212:215], v[98:101]
	v_mfma_f32_16x16x32_bf16 v[90:93], v[188:191], v[220:223], v[90:93]
	v_mfma_f32_16x16x32_bf16 v[82:85], v[196:199], v[220:223], v[82:85]
	v_mfma_f32_16x16x32_bf16 v[74:77], v[188:191], v[228:231], v[74:77]
	v_mfma_f32_16x16x32_bf16 v[66:69], v[196:199], v[228:231], v[66:69]
	s_barrier
	s_setprio 0
	s_add_i32 s12, s39, s21
	v_lshl_add_u64 v[160:161], s[16:17], 0, v[134:135]
	s_mov_b32 m0, s12
	ds_read_b128 v[200:203], v163 offset:16384
	ds_read_b128 v[204:207], v163 offset:17408
	ds_read_b128 v[208:211], v163 offset:18432
	ds_read_b128 v[212:215], v163 offset:19456
	ds_read_b128 v[216:219], v163 offset:20480
	ds_read_b128 v[220:223], v163 offset:21504
	ds_read_b128 v[224:227], v163 offset:22528
	ds_read_b128 v[228:231], v163 offset:23552
	global_load_lds_dwordx4 v[160:161], off
	s_add_i32 m0, s12, 0x2000
	s_add_u32 s12, s16, 0x44000
	v_lshl_add_u64 v[180:181], s[16:17], 0, v[130:131]
	s_addc_u32 s13, s17, 0
	s_add_i32 s39, s40, s21
	global_load_lds_dwordx4 v[180:181], off
	v_lshl_add_u64 v[232:233], s[12:13], 0, v[134:135]
	s_mov_b32 m0, s39
	global_load_lds_dwordx4 v[232:233], off
	s_add_i32 m0, s39, 0x2000
	v_lshl_add_u64 v[232:233], s[12:13], 0, v[130:131]
	global_load_lds_dwordx4 v[232:233], off
	s_mov_b32 m0, s23
	v_lshl_add_u64 v[232:233], s[18:19], 0, v[154:155]
	global_load_lds_dwordx4 v[232:233], off
	s_mov_b32 m0, s24
	v_lshl_add_u64 v[234:235], s[18:19], 0, v[132:133]
	global_load_lds_dwordx4 v[234:235], off
	s_cmp_lt_u32 s29, 2
	s_cbranch_scc1 .Lrw_std_1050_1_pl
	s_waitcnt vmcnt(16)
	s_branch .Lrw_done_1050_1_pl

; #define PG8_STAGE(bufoff, gbase, voff) do { _Pragma("unroll") for (int _i = 0; _i < 2; ++_i) \
;         __builtin_amdgcn_global_load_lds((const unsigned*)((const char*)(gbase) + (voff)[_i]), (LAS unsigned*)(lds + (bufoff) + ldsw + _i * 8192), 16, 0, 0); } while (0)
; #define PG8_LDA(dst, b, h) do { _Pragma("unroll") for (int m = 0; m < 4; ++m) _Pragma("unroll") for (int k = 0; k < 2; ++k) dst[m][k] = *(const LAS bf16x8*)(lds + PG8_SA(b, h) + aoff + m * 2048 + k * 1024); } while (0)
; #define PG8_LDB(dst, b, h) do { _Pragma("unroll") for (int n = 0; n < 2; ++n) _Pragma("unroll") for (int k = 0; k < 2; ++k) dst[n][k] = *(const LAS bf16x8*)(lds + PG8_SB(b, h) + boff + n * 2048 + k * 1024); } while (0)
; #define PG8_MMA(ai, bj, At, Bt) do { __builtin_amdgcn_s_setprio(1); _Pragma("unroll") for (int m = 0; m < 4; ++m) _Pragma("unroll") for (int n = 0; n < 2; ++n) _Pragma("unroll") for (int k = 0; k < 2; ++k) \
;         acc[ai][bj][m][n] = __builtin_amdgcn_mfma_f32_16x16x32_bf16(Bt[n][k], At[m][k], acc[ai][bj][m][n], 0, 0, 0); __builtin_amdgcn_s_setprio(0); } while (0)
; #define PG8_WAIT_V(n) asm volatile("s_waitcnt vmcnt(" #n ")" ::: "memory")
; #define PG8_WAIT_L(n) asm volatile("s_waitcnt lgkmcnt(" #n ")" ::: "memory")
; #define PG8_BAR __builtin_amdgcn_s_barrier()
; #define PG8_SCHED __builtin_amdgcn_sched_barrier(0)
; template <class Epi, bool ALIGN_EPI = PG8_ALIGN, bool SP2 = PG8_SP2>
; __device__ __forceinline__ void gemm_phase(LAS uchar* lds, const Gemm g, const StaticOrder& S, const Epi& E) {
;     ...
;             PG8_LDA(At, 0, 1); PG8_STAGE(PG8_SB(0, 0), b2, voffB); PG8_STAGE(PG8_SB(0, 1), b2 + hstepB, voffB); PG8_STAGE(PG8_SA(0, 0), a2, voffA);
;             PG8_WAIT_V(8); PG8_WAIT_L(0); PG8_BAR; PG8_MMA(1, 0, At, B0); PG8_MMA(1, 1, At, B1); PG8_BAR; PG8_SCHED;
;             PG8_LDB(B0, 1, 0); PG8_LDB(B1, 1, 1); PG8_SCHED; PG8_LDA(At, 1, 0); PG8_STAGE(PG8_SA(0, 1), a2 + hstepA, voffA);
;             PG8_WAIT_V(8); PG8_WAIT_L(0); PG8_BAR; PG8_MMA(0, 0, At, B0); PG8_MMA(0, 1, At, B1); PG8_BAR; PG8_SCHED;
.Lrw_done_1050_1_pl:
	s_waitcnt lgkmcnt(0)
	s_setprio 1
	s_barrier
	v_mfma_f32_16x16x32_bf16 v[62:65], v[164:167], v[200:203], 0
	v_mfma_f32_16x16x32_bf16 v[54:57], v[172:175], v[200:203], 0
	v_mfma_f32_16x16x32_bf16 v[46:49], v[164:167], v[208:211], 0
	v_mfma_f32_16x16x32_bf16 v[38:41], v[172:175], v[208:211], 0
	v_mfma_f32_16x16x32_bf16 v[30:33], v[164:167], v[216:219], 0
	v_mfma_f32_16x16x32_bf16 v[22:25], v[172:175], v[216:219], 0
	v_mfma_f32_16x16x32_bf16 v[14:17], v[164:167], v[224:227], 0
	v_mfma_f32_16x16x32_bf16 v[6:9], v[172:175], v[224:227], 0
	v_mfma_f32_16x16x32_bf16 v[62:65], v[168:171], v[204:207], v[62:65]
	v_mfma_f32_16x16x32_bf16 v[54:57], v[176:179], v[204:207], v[54:57]
	v_mfma_f32_16x16x32_bf16 v[46:49], v[168:171], v[212:215], v[46:49]
	v_mfma_f32_16x16x32_bf16 v[38:41], v[176:179], v[212:215], v[38:41]
	v_mfma_f32_16x16x32_bf16 v[30:33], v[168:171], v[220:223], v[30:33]
	v_mfma_f32_16x16x32_bf16 v[22:25], v[176:179], v[220:223], v[22:25]
	v_mfma_f32_16x16x32_bf16 v[14:17], v[168:171], v[228:231], v[14:17]
	v_mfma_f32_16x16x32_bf16 v[6:9], v[176:179], v[228:231], v[6:9]
	v_mfma_f32_16x16x32_bf16 v[58:61], v[184:187], v[200:203], 0
	v_mfma_f32_16x16x32_bf16 v[50:53], v[192:195], v[200:203], 0
	v_mfma_f32_16x16x32_bf16 v[42:45], v[184:187], v[208:211], 0
	v_mfma_f32_16x16x32_bf16 v[34:37], v[192:195], v[208:211], 0
	v_mfma_f32_16x16x32_bf16 v[26:29], v[184:187], v[216:219], 0
	v_mfma_f32_16x16x32_bf16 v[18:21], v[192:195], v[216:219], 0
	v_mfma_f32_16x16x32_bf16 v[10:13], v[184:187], v[224:227], 0
	v_mfma_f32_16x16x32_bf16 v[2:5], v[192:195], v[224:227], 0
	v_mfma_f32_16x16x32_bf16 v[58:61], v[188:191], v[204:207], v[58:61]
	v_mfma_f32_16x16x32_bf16 v[50:53], v[196:199], v[204:207], v[50:53]
	v_mfma_f32_16x16x32_bf16 v[42:45], v[188:191], v[212:215], v[42:45]
	v_mfma_f32_16x16x32_bf16 v[34:37], v[196:199], v[212:215], v[34:37]
	v_mfma_f32_16x16x32_bf16 v[26:29], v[188:191], v[220:223], v[26:29]
	v_mfma_f32_16x16x32_bf16 v[18:21], v[196:199], v[220:223], v[18:21]
	v_mfma_f32_16x16x32_bf16 v[10:13], v[188:191], v[228:231], v[10:13]
	v_mfma_f32_16x16x32_bf16 v[2:5], v[196:199], v[228:231], v[2:5]
	s_barrier
	s_setprio 0
	s_add_i32 s39, 0, 0x18000
	v_add_u32_e32 v144, s39, v139
	s_add_i32 s40, 0, 0x1c000
	ds_read_b128 v[164:167], v144
	ds_read_b128 v[168:171], v144 offset:1024
	ds_read_b128 v[172:175], v144 offset:2048
	ds_read_b128 v[176:179], v144 offset:3072
	v_add_u32_e32 v144, s40, v139
	ds_read_b128 v[184:187], v144
	ds_read_b128 v[188:191], v144 offset:1024
	ds_read_b128 v[192:195], v144 offset:2048
	ds_read_b128 v[196:199], v144 offset:3072
	s_add_u32 s12, s18, 0x44000
	s_addc_u32 s13, s19, 0
	s_mov_b32 m0, s25
	v_lshl_add_u64 v[236:237], s[12:13], 0, v[154:155]
	ds_read_b128 v[200:203], v163 offset:32768
	ds_read_b128 v[204:207], v163 offset:33792
	ds_read_b128 v[208:211], v163 offset:34816
	ds_read_b128 v[212:215], v163 offset:35840
	ds_read_b128 v[216:219], v163 offset:36864
	ds_read_b128 v[220:223], v163 offset:37888
	ds_read_b128 v[224:227], v163 offset:38912
	ds_read_b128 v[228:231], v163 offset:39936
	global_load_lds_dwordx4 v[236:237], off
	s_mov_b32 m0, s26
	v_lshl_add_u64 v[236:237], s[12:13], 0, v[132:133]
	global_load_lds_dwordx4 v[236:237], off
	s_waitcnt vmcnt(8)
	s_waitcnt lgkmcnt(0)
	s_setprio 1
	s_barrier
	v_mfma_f32_16x16x32_bf16 v[126:129], v[164:167], v[200:203], v[126:129]
	v_mfma_f32_16x16x32_bf16 v[118:121], v[172:175], v[200:203], v[118:121]
	v_mfma_f32_16x16x32_bf16 v[110:113], v[164:167], v[208:211], v[110:113]
	v_mfma_f32_16x16x32_bf16 v[102:105], v[172:175], v[208:211], v[102:105]
	v_mfma_f32_16x16x32_bf16 v[94:97], v[164:167], v[216:219], v[94:97]
	v_mfma_f32_16x16x32_bf16 v[86:89], v[172:175], v[216:219], v[86:89]
	v_mfma_f32_16x16x32_bf16 v[78:81], v[164:167], v[224:227], v[78:81]
	v_mfma_f32_16x16x32_bf16 v[70:73], v[172:175], v[224:227], v[70:73]
	v_mfma_f32_16x16x32_bf16 v[126:129], v[168:171], v[204:207], v[126:129]
	v_mfma_f32_16x16x32_bf16 v[118:121], v[176:179], v[204:207], v[118:121]
	v_mfma_f32_16x16x32_bf16 v[110:113], v[168:171], v[212:215], v[110:113]
	v_mfma_f32_16x16x32_bf16 v[102:105], v[176:179], v[212:215], v[102:105]
	v_mfma_f32_16x16x32_bf16 v[94:97], v[168:171], v[220:223], v[94:97]
	v_mfma_f32_16x16x32_bf16 v[86:89], v[176:179], v[220:223], v[86:89]
	v_mfma_f32_16x16x32_bf16 v[78:81], v[168:171], v[228:231], v[78:81]
	v_mfma_f32_16x16x32_bf16 v[70:73], v[176:179], v[228:231], v[70:73]
	v_mfma_f32_16x16x32_bf16 v[122:125], v[184:187], v[200:203], v[122:125]
	v_mfma_f32_16x16x32_bf16 v[114:117], v[192:195], v[200:203], v[114:117]
	v_mfma_f32_16x16x32_bf16 v[106:109], v[184:187], v[208:211], v[106:109]
	v_mfma_f32_16x16x32_bf16 v[98:101], v[192:195], v[208:211], v[98:101]
	v_mfma_f32_16x16x32_bf16 v[90:93], v[184:187], v[216:219], v[90:93]
	v_mfma_f32_16x16x32_bf16 v[82:85], v[192:195], v[216:219], v[82:85]
	v_mfma_f32_16x16x32_bf16 v[74:77], v[184:187], v[224:227], v[74:77]
	v_mfma_f32_16x16x32_bf16 v[66:69], v[192:195], v[224:227], v[66:69]
	v_mfma_f32_16x16x32_bf16 v[122:125], v[188:191], v[204:207], v[122:125]
	v_mfma_f32_16x16x32_bf16 v[114:117], v[196:199], v[204:207], v[114:117]
	v_mfma_f32_16x16x32_bf16 v[106:109], v[188:191], v[212:215], v[106:109]
	v_mfma_f32_16x16x32_bf16 v[98:101], v[196:199], v[212:215], v[98:101]
	v_mfma_f32_16x16x32_bf16 v[90:93], v[188:191], v[220:223], v[90:93]
	v_mfma_f32_16x16x32_bf16 v[82:85], v[196:199], v[220:223], v[82:85]
	v_mfma_f32_16x16x32_bf16 v[74:77], v[188:191], v[228:231], v[74:77]
	v_mfma_f32_16x16x32_bf16 v[66:69], v[196:199], v[228:231], v[66:69]
	s_barrier
; #define PG8_STAGE(bufoff, gbase, voff) do { _Pragma("unroll") for (int _i = 0; _i < 2; ++_i) \
;         __builtin_amdgcn_global_load_lds((const unsigned*)((const char*)(gbase) + (voff)[_i]), (LAS unsigned*)(lds + (bufoff) + ldsw + _i * 8192), 16, 0, 0); } while (0)
; #define PG8_LDA(dst, b, h) do { _Pragma("unroll") for (int m = 0; m < 4; ++m) _Pragma("unroll") for (int k = 0; k < 2; ++k) dst[m][k] = *(const LAS bf16x8*)(lds + PG8_SA(b, h) + aoff + m * 2048 + k * 1024); } while (0)
; #define PG8_LDB(dst, b, h) do { _Pragma("unroll") for (int n = 0; n < 2; ++n) _Pragma("unroll") for (int k = 0; k < 2; ++k) dst[n][k] = *(const LAS bf16x8*)(lds + PG8_SB(b, h) + boff + n * 2048 + k * 1024); } while (0)
; #define PG8_BAR __builtin_amdgcn_s_barrier()
; template <class Epi, bool ALIGN_EPI = PG8_ALIGN, bool SP2 = PG8_SP2>
; __device__ __forceinline__ void gemm_phase(LAS uchar* lds, const Gemm g, const StaticOrder& S, const Epi& E) {
;     ...
;         for (int t = tb; t < tb + tblk; t += 2) {
;             const bool last = (t == nt - 2);
;             const char* a1 = cA + (size_t)(t + 1) * kstep;
;             const char* a2 = last ? nA : cA + (size_t)(t + 2) * kstep; const char* b2 = last ? nB : cB + (size_t)(t + 2) * kstep;
;             const char* a3 = a2 + kstep; const char* b3 = b2 + kstep;
;             if constexpr (SP2) {
;             PG8_LDB(B0, 0, 0); PG8_LDB(B1, 0, 1); PG8_SCHED; PG8_LDA(At, 0, 0); PG8_STAGE(PG8_SA(1, 1), a1 + hstepA, voffA);
;             PG8_WAIT_V(8); PG8_WAIT_L(0); PG8_BAR; PG8_MMA(0, 0, At, B0); PG8_MMA(0, 1, At, B1); PG8_BAR; PG8_SCHED;
;             PG8_LDA(At, 0, 1); PG8_STAGE(PG8_SB(0, 0), b2, voffB); PG8_STAGE(PG8_SB(0, 1), b2 + hstepB, voffB); PG8_STAGE(PG8_SA(0, 0), a2, voffA);
;             PG8_WAIT_V(8); PG8_WAIT_L(0); PG8_BAR; PG8_MMA(1, 0, At, B0); PG8_MMA(1, 1, At, B1); PG8_BAR; PG8_SCHED;
;             PG8_LDB(B0, 1, 0); PG8_LDB(B1, 1, 1); PG8_SCHED; PG8_LDA(At, 1, 0); PG8_STAGE(PG8_SA(0, 1), a2 + hstepA, voffA);
;             PG8_WAIT_V(8); PG8_WAIT_L(0); PG8_BAR; PG8_MMA(0, 0, At, B0); PG8_MMA(0, 1, At, B1); PG8_BAR; PG8_SCHED;
;             PG8_LDA(At, 1, 1); PG8_STAGE(PG8_SB(1, 0), b3, voffB); PG8_STAGE(PG8_SB(1, 1), b3 + hstepB, voffB); PG8_STAGE(PG8_SA(1, 0), a3, voffA);
;             PG8_WAIT_V(8); PG8_WAIT_L(0); PG8_BAR; PG8_MMA(1, 0, At, B0); PG8_MMA(1, 1, At, B1); PG8_BAR; PG8_SCHED;
	s_setprio 0
	s_add_i32 s12, s39, s21
	v_lshl_add_u64 v[160:161], v[160:161], 0, s[84:85]
	s_mov_b32 m0, s12
	ds_read_b128 v[200:203], v163 offset:49152
	ds_read_b128 v[204:207], v163 offset:50176
	ds_read_b128 v[208:211], v163 offset:51200
	ds_read_b128 v[212:215], v163 offset:52224
	ds_read_b128 v[216:219], v163 offset:53248
	ds_read_b128 v[220:223], v163 offset:54272
	ds_read_b128 v[224:227], v163 offset:55296
	ds_read_b128 v[228:231], v163 offset:56320
	global_load_lds_dwordx4 v[160:161], off
	s_add_i32 m0, s12, 0x2000
	s_add_u32 s12, s16, 0x44080
	v_lshl_add_u64 v[160:161], v[180:181], 0, s[84:85]
	s_addc_u32 s13, s17, 0
	s_add_i32 s16, s40, s21
	global_load_lds_dwordx4 v[160:161], off
	s_mov_b32 m0, s16
	v_lshl_add_u64 v[160:161], s[12:13], 0, v[134:135]
	global_load_lds_dwordx4 v[160:161], off
	s_add_i32 m0, s16, 0x2000
	v_lshl_add_u64 v[160:161], s[12:13], 0, v[130:131]
	global_load_lds_dwordx4 v[160:161], off
	s_mov_b32 m0, s27
	v_lshl_add_u64 v[160:161], v[232:233], 0, s[84:85]
	global_load_lds_dwordx4 v[160:161], off
	s_mov_b32 m0, s28
	v_lshl_add_u64 v[160:161], v[234:235], 0, s[84:85]
	global_load_lds_dwordx4 v[160:161], off
	s_waitcnt vmcnt(8)
	s_waitcnt lgkmcnt(0)
	s_setprio 1
	s_barrier
	v_mfma_f32_16x16x32_bf16 v[62:65], v[164:167], v[200:203], v[62:65]
	v_mfma_f32_16x16x32_bf16 v[54:57], v[172:175], v[200:203], v[54:57]
	v_mfma_f32_16x16x32_bf16 v[46:49], v[164:167], v[208:211], v[46:49]
	v_mfma_f32_16x16x32_bf16 v[38:41], v[172:175], v[208:211], v[38:41]
	v_mfma_f32_16x16x32_bf16 v[30:33], v[164:167], v[216:219], v[30:33]
	v_mfma_f32_16x16x32_bf16 v[22:25], v[172:175], v[216:219], v[22:25]
	v_mfma_f32_16x16x32_bf16 v[14:17], v[164:167], v[224:227], v[14:17]
	v_mfma_f32_16x16x32_bf16 v[6:9], v[172:175], v[224:227], v[6:9]
	v_mfma_f32_16x16x32_bf16 v[62:65], v[168:171], v[204:207], v[62:65]
	v_mfma_f32_16x16x32_bf16 v[54:57], v[176:179], v[204:207], v[54:57]
	v_mfma_f32_16x16x32_bf16 v[46:49], v[168:171], v[212:215], v[46:49]
	v_mfma_f32_16x16x32_bf16 v[38:41], v[176:179], v[212:215], v[38:41]
	v_mfma_f32_16x16x32_bf16 v[30:33], v[168:171], v[220:223], v[30:33]
	v_mfma_f32_16x16x32_bf16 v[22:25], v[176:179], v[220:223], v[22:25]
	v_mfma_f32_16x16x32_bf16 v[14:17], v[168:171], v[228:231], v[14:17]
	v_mfma_f32_16x16x32_bf16 v[6:9], v[176:179], v[228:231], v[6:9]
	v_mfma_f32_16x16x32_bf16 v[58:61], v[184:187], v[200:203], v[58:61]
	v_mfma_f32_16x16x32_bf16 v[50:53], v[192:195], v[200:203], v[50:53]
	v_mfma_f32_16x16x32_bf16 v[42:45], v[184:187], v[208:211], v[42:45]
	v_mfma_f32_16x16x32_bf16 v[34:37], v[192:195], v[208:211], v[34:37]
	v_mfma_f32_16x16x32_bf16 v[26:29], v[184:187], v[216:219], v[26:29]
	v_mfma_f32_16x16x32_bf16 v[18:21], v[192:195], v[216:219], v[18:21]
	v_mfma_f32_16x16x32_bf16 v[10:13], v[184:187], v[224:227], v[10:13]
	v_mfma_f32_16x16x32_bf16 v[2:5], v[192:195], v[224:227], v[2:5]
	v_mfma_f32_16x16x32_bf16 v[58:61], v[188:191], v[204:207], v[58:61]
	v_mfma_f32_16x16x32_bf16 v[50:53], v[196:199], v[204:207], v[50:53]
	v_mfma_f32_16x16x32_bf16 v[42:45], v[188:191], v[212:215], v[42:45]
	v_mfma_f32_16x16x32_bf16 v[34:37], v[196:199], v[212:215], v[34:37]
	v_mfma_f32_16x16x32_bf16 v[26:29], v[188:191], v[220:223], v[26:29]
	v_mfma_f32_16x16x32_bf16 v[18:21], v[196:199], v[220:223], v[18:21]
	v_mfma_f32_16x16x32_bf16 v[10:13], v[188:191], v[228:231], v[10:13]
	v_mfma_f32_16x16x32_bf16 v[2:5], v[196:199], v[228:231], v[2:5]
	s_barrier
	s_setprio 0
	s_add_i32 s38, s38, 2
	s_add_u32 s36, s36, 0x100
	s_addc_u32 s37, s37, 0
	s_cmp_gt_u32 s38, 13
	s_mov_b64 s[12:13], s[14:15]
.LBB0_1050:
	s_add_u32 s14, s12, 0x100
	s_addc_u32 s15, s13, 0
	s_add_i32 s39, 0, 0x10000
	s_cmp_eq_u32 s38, 12
	s_cselect_b32 s19, s1, s15
	s_cselect_b32 s18, s0, s14
	v_add_u32_e32 v144, s39, v139
	s_cselect_b32 s17, s11, s37
	s_cselect_b32 s16, s10, s36
	s_add_i32 s40, 0, 0x14000
	ds_read_b128 v[164:167], v144
	ds_read_b128 v[168:171], v144 offset:1024
	ds_read_b128 v[172:175], v144 offset:2048
	ds_read_b128 v[176:179], v144 offset:3072
	v_add_u32_e32 v144, s40, v139
	ds_read_b128 v[184:187], v144
	ds_read_b128 v[188:191], v144 offset:1024
	ds_read_b128 v[192:195], v144 offset:2048
	ds_read_b128 v[196:199], v144 offset:3072
	v_lshl_add_u64 v[160:161], s[12:13], 0, v[156:157]
	s_add_i32 m0, s23, 0xc000
	ds_read_b128 v[200:203], v163
	ds_read_b128 v[204:207], v163 offset:1024
	ds_read_b128 v[208:211], v163 offset:2048
	ds_read_b128 v[212:215], v163 offset:3072
	ds_read_b128 v[216:219], v163 offset:4096
	ds_read_b128 v[220:223], v163 offset:5120
	ds_read_b128 v[224:227], v163 offset:6144
	ds_read_b128 v[228:231], v163 offset:7168
	global_load_lds_dwordx4 v[160:161], off
	s_add_i32 m0, s23, 0xe000
	v_lshl_add_u64 v[160:161], s[12:13], 0, v[158:159]
	global_load_lds_dwordx4 v[160:161], off
	s_waitcnt vmcnt(8)
	s_waitcnt lgkmcnt(0)
	s_setprio 1
	s_barrier
; #define PG8_STAGE(bufoff, gbase, voff) do { _Pragma("unroll") for (int _i = 0; _i < 2; ++_i) \
;         __builtin_amdgcn_global_load_lds((const unsigned*)((const char*)(gbase) + (voff)[_i]), (LAS unsigned*)(lds + (bufoff) + ldsw + _i * 8192), 16, 0, 0); } while (0)
; #define PG8_LDA(dst, b, h) do { _Pragma("unroll") for (int m = 0; m < 4; ++m) _Pragma("unroll") for (int k = 0; k < 2; ++k) dst[m][k] = *(const LAS bf16x8*)(lds + PG8_SA(b, h) + aoff + m * 2048 + k * 1024); } while (0)
; #define PG8_LDB(dst, b, h) do { _Pragma("unroll") for (int n = 0; n < 2; ++n) _Pragma("unroll") for (int k = 0; k < 2; ++k) dst[n][k] = *(const LAS bf16x8*)(lds + PG8_SB(b, h) + boff + n * 2048 + k * 1024); } while (0)
; #define PG8_BAR __builtin_amdgcn_s_barrier()
; template <class Epi, bool ALIGN_EPI = PG8_ALIGN, bool SP2 = PG8_SP2>
; __device__ __forceinline__ void gemm_phase(LAS uchar* lds, const Gemm g, const StaticOrder& S, const Epi& E) {
;     ...
;         for (int t = tb; t < tb + tblk; t += 2) {
;             const bool last = (t == nt - 2);
;             const char* a1 = cA + (size_t)(t + 1) * kstep;
;             const char* a2 = last ? nA : cA + (size_t)(t + 2) * kstep; const char* b2 = last ? nB : cB + (size_t)(t + 2) * kstep;
;             const char* a3 = a2 + kstep; const char* b3 = b2 + kstep;
;             if constexpr (SP2) {
;             PG8_LDB(B0, 0, 0); PG8_LDB(B1, 0, 1); PG8_SCHED; PG8_LDA(At, 0, 0); PG8_STAGE(PG8_SA(1, 1), a1 + hstepA, voffA);
;             PG8_WAIT_V(8); PG8_WAIT_L(0); PG8_BAR; PG8_MMA(0, 0, At, B0); PG8_MMA(0, 1, At, B1); PG8_BAR; PG8_SCHED;
;             PG8_LDA(At, 0, 1); PG8_STAGE(PG8_SB(0, 0), b2, voffB); PG8_STAGE(PG8_SB(0, 1), b2 + hstepB, voffB); PG8_STAGE(PG8_SA(0, 0), a2, voffA);
;             PG8_WAIT_V(8); PG8_WAIT_L(0); PG8_BAR; PG8_MMA(1, 0, At, B0); PG8_MMA(1, 1, At, B1); PG8_BAR; PG8_SCHED;
;             PG8_LDB(B0, 1, 0); PG8_LDB(B1, 1, 1); PG8_SCHED; PG8_LDA(At, 1, 0); PG8_STAGE(PG8_SA(0, 1), a2 + hstepA, voffA);
;             PG8_WAIT_V(8); PG8_WAIT_L(0); PG8_BAR; PG8_MMA(0, 0, At, B0); PG8_MMA(0, 1, At, B1); PG8_BAR; PG8_SCHED;
;             PG8_LDA(At, 1, 1); PG8_STAGE(PG8_SB(1, 0), b3, voffB); PG8_STAGE(PG8_SB(1, 1), b3 + hstepB, voffB); PG8_STAGE(PG8_SA(1, 0), a3, voffA);
;             PG8_WAIT_V(8); PG8_WAIT_L(0); PG8_BAR; PG8_MMA(1, 0, At, B0); PG8_MMA(1, 1, At, B1); PG8_BAR; PG8_SCHED;
	v_mfma_f32_16x16x32_bf16 v[126:129], v[164:167], v[200:203], v[126:129]
	v_mfma_f32_16x16x32_bf16 v[118:121], v[172:175], v[200:203], v[118:121]
	v_mfma_f32_16x16x32_bf16 v[110:113], v[164:167], v[208:211], v[110:113]
	v_mfma_f32_16x16x32_bf16 v[102:105], v[172:175], v[208:211], v[102:105]
	v_mfma_f32_16x16x32_bf16 v[94:97], v[164:167], v[216:219], v[94:97]
	v_mfma_f32_16x16x32_bf16 v[86:89], v[172:175], v[216:219], v[86:89]
	v_mfma_f32_16x16x32_bf16 v[78:81], v[164:167], v[224:227], v[78:81]
	v_mfma_f32_16x16x32_bf16 v[70:73], v[172:175], v[224:227], v[70:73]
	v_mfma_f32_16x16x32_bf16 v[126:129], v[168:171], v[204:207], v[126:129]
	v_mfma_f32_16x16x32_bf16 v[118:121], v[176:179], v[204:207], v[118:121]
	v_mfma_f32_16x16x32_bf16 v[110:113], v[168:171], v[212:215], v[110:113]
	v_mfma_f32_16x16x32_bf16 v[102:105], v[176:179], v[212:215], v[102:105]
	v_mfma_f32_16x16x32_bf16 v[94:97], v[168:171], v[220:223], v[94:97]
	v_mfma_f32_16x16x32_bf16 v[86:89], v[176:179], v[220:223], v[86:89]
	v_mfma_f32_16x16x32_bf16 v[78:81], v[168:171], v[228:231], v[78:81]
	v_mfma_f32_16x16x32_bf16 v[70:73], v[176:179], v[228:231], v[70:73]
	v_mfma_f32_16x16x32_bf16 v[122:125], v[184:187], v[200:203], v[122:125]
	v_mfma_f32_16x16x32_bf16 v[114:117], v[192:195], v[200:203], v[114:117]
	v_mfma_f32_16x16x32_bf16 v[106:109], v[184:187], v[208:211], v[106:109]
	v_mfma_f32_16x16x32_bf16 v[98:101], v[192:195], v[208:211], v[98:101]
	v_mfma_f32_16x16x32_bf16 v[90:93], v[184:187], v[216:219], v[90:93]
	v_mfma_f32_16x16x32_bf16 v[82:85], v[192:195], v[216:219], v[82:85]
	v_mfma_f32_16x16x32_bf16 v[74:77], v[184:187], v[224:227], v[74:77]
	v_mfma_f32_16x16x32_bf16 v[66:69], v[192:195], v[224:227], v[66:69]
	v_mfma_f32_16x16x32_bf16 v[122:125], v[188:191], v[204:207], v[122:125]
	v_mfma_f32_16x16x32_bf16 v[114:117], v[196:199], v[204:207], v[114:117]
	v_mfma_f32_16x16x32_bf16 v[106:109], v[188:191], v[212:215], v[106:109]
	v_mfma_f32_16x16x32_bf16 v[98:101], v[196:199], v[212:215], v[98:101]
	v_mfma_f32_16x16x32_bf16 v[90:93], v[188:191], v[220:223], v[90:93]
	v_mfma_f32_16x16x32_bf16 v[82:85], v[196:199], v[220:223], v[82:85]
	v_mfma_f32_16x16x32_bf16 v[74:77], v[188:191], v[228:231], v[74:77]
	v_mfma_f32_16x16x32_bf16 v[66:69], v[196:199], v[228:231], v[66:69]
	s_barrier
	s_setprio 0
	s_add_i32 s12, s39, s21
	v_lshl_add_u64 v[160:161], s[16:17], 0, v[134:135]
	s_mov_b32 m0, s12
	ds_read_b128 v[200:203], v163 offset:16384
	ds_read_b128 v[204:207], v163 offset:17408
	ds_read_b128 v[208:211], v163 offset:18432
	ds_read_b128 v[212:215], v163 offset:19456
	ds_read_b128 v[216:219], v163 offset:20480
	ds_read_b128 v[220:223], v163 offset:21504
	ds_read_b128 v[224:227], v163 offset:22528
	ds_read_b128 v[228:231], v163 offset:23552
	global_load_lds_dwordx4 v[160:161], off
	s_add_i32 m0, s12, 0x2000
	s_add_u32 s12, s16, 0x44000
	v_lshl_add_u64 v[180:181], s[16:17], 0, v[130:131]
	s_addc_u32 s13, s17, 0
	s_add_i32 s39, s40, s21
	global_load_lds_dwordx4 v[180:181], off
	v_lshl_add_u64 v[232:233], s[12:13], 0, v[134:135]
	s_mov_b32 m0, s39
	global_load_lds_dwordx4 v[232:233], off
	s_add_i32 m0, s39, 0x2000
	v_lshl_add_u64 v[232:233], s[12:13], 0, v[130:131]
	global_load_lds_dwordx4 v[232:233], off
	s_mov_b32 m0, s23
	v_lshl_add_u64 v[232:233], s[18:19], 0, v[154:155]
	global_load_lds_dwordx4 v[232:233], off
	s_mov_b32 m0, s24
	v_lshl_add_u64 v[234:235], s[18:19], 0, v[132:133]
	global_load_lds_dwordx4 v[234:235], off
	s_waitcnt vmcnt(8)
	s_waitcnt lgkmcnt(0)
	s_setprio 1
	s_barrier
	v_mfma_f32_16x16x32_bf16 v[62:65], v[164:167], v[200:203], v[62:65]
	v_mfma_f32_16x16x32_bf16 v[54:57], v[172:175], v[200:203], v[54:57]
	v_mfma_f32_16x16x32_bf16 v[46:49], v[164:167], v[208:211], v[46:49]
	v_mfma_f32_16x16x32_bf16 v[38:41], v[172:175], v[208:211], v[38:41]
	v_mfma_f32_16x16x32_bf16 v[30:33], v[164:167], v[216:219], v[30:33]
	v_mfma_f32_16x16x32_bf16 v[22:25], v[172:175], v[216:219], v[22:25]
	v_mfma_f32_16x16x32_bf16 v[14:17], v[164:167], v[224:227], v[14:17]
	v_mfma_f32_16x16x32_bf16 v[6:9], v[172:175], v[224:227], v[6:9]
	v_mfma_f32_16x16x32_bf16 v[62:65], v[168:171], v[204:207], v[62:65]
	v_mfma_f32_16x16x32_bf16 v[54:57], v[176:179], v[204:207], v[54:57]
	v_mfma_f32_16x16x32_bf16 v[46:49], v[168:171], v[212:215], v[46:49]
	v_mfma_f32_16x16x32_bf16 v[38:41], v[176:179], v[212:215], v[38:41]
	v_mfma_f32_16x16x32_bf16 v[30:33], v[168:171], v[220:223], v[30:33]
	v_mfma_f32_16x16x32_bf16 v[22:25], v[176:179], v[220:223], v[22:25]
	v_mfma_f32_16x16x32_bf16 v[14:17], v[168:171], v[228:231], v[14:17]
	v_mfma_f32_16x16x32_bf16 v[6:9], v[176:179], v[228:231], v[6:9]
	v_mfma_f32_16x16x32_bf16 v[58:61], v[184:187], v[200:203], v[58:61]
	v_mfma_f32_16x16x32_bf16 v[50:53], v[192:195], v[200:203], v[50:53]
	v_mfma_f32_16x16x32_bf16 v[42:45], v[184:187], v[208:211], v[42:45]
	v_mfma_f32_16x16x32_bf16 v[34:37], v[192:195], v[208:211], v[34:37]
	v_mfma_f32_16x16x32_bf16 v[26:29], v[184:187], v[216:219], v[26:29]
	v_mfma_f32_16x16x32_bf16 v[18:21], v[192:195], v[216:219], v[18:21]
	v_mfma_f32_16x16x32_bf16 v[10:13], v[184:187], v[224:227], v[10:13]
	v_mfma_f32_16x16x32_bf16 v[2:5], v[192:195], v[224:227], v[2:5]
	v_mfma_f32_16x16x32_bf16 v[58:61], v[188:191], v[204:207], v[58:61]
	v_mfma_f32_16x16x32_bf16 v[50:53], v[196:199], v[204:207], v[50:53]
	v_mfma_f32_16x16x32_bf16 v[42:45], v[188:191], v[212:215], v[42:45]
	v_mfma_f32_16x16x32_bf16 v[34:37], v[196:199], v[212:215], v[34:37]
	v_mfma_f32_16x16x32_bf16 v[26:29], v[188:191], v[220:223], v[26:29]
	v_mfma_f32_16x16x32_bf16 v[18:21], v[196:199], v[220:223], v[18:21]
	v_mfma_f32_16x16x32_bf16 v[10:13], v[188:191], v[228:231], v[10:13]
	v_mfma_f32_16x16x32_bf16 v[2:5], v[196:199], v[228:231], v[2:5]
	s_barrier
; #define PG8_STAGE(bufoff, gbase, voff) do { _Pragma("unroll") for (int _i = 0; _i < 2; ++_i) \
;         __builtin_amdgcn_global_load_lds((const unsigned*)((const char*)(gbase) + (voff)[_i]), (LAS unsigned*)(lds + (bufoff) + ldsw + _i * 8192), 16, 0, 0); } while (0)
; #define PG8_LDA(dst, b, h) do { _Pragma("unroll") for (int m = 0; m < 4; ++m) _Pragma("unroll") for (int k = 0; k < 2; ++k) dst[m][k] = *(const LAS bf16x8*)(lds + PG8_SA(b, h) + aoff + m * 2048 + k * 1024); } while (0)
; #define PG8_LDB(dst, b, h) do { _Pragma("unroll") for (int n = 0; n < 2; ++n) _Pragma("unroll") for (int k = 0; k < 2; ++k) dst[n][k] = *(const LAS bf16x8*)(lds + PG8_SB(b, h) + boff + n * 2048 + k * 1024); } while (0)
; #define PG8_MMA(ai, bj, At, Bt) do { __builtin_amdgcn_s_setprio(1); _Pragma("unroll") for (int m = 0; m < 4; ++m) _Pragma("unroll") for (int n = 0; n < 2; ++n) _Pragma("unroll") for (int k = 0; k < 2; ++k) \
;         acc[ai][bj][m][n] = __builtin_amdgcn_mfma_f32_16x16x32_bf16(Bt[n][k], At[m][k], acc[ai][bj][m][n], 0, 0, 0); __builtin_amdgcn_s_setprio(0); } while (0)
; #define PG8_WAIT_V(n) asm volatile("s_waitcnt vmcnt(" #n ")" ::: "memory")
; #define PG8_WAIT_L(n) asm volatile("s_waitcnt lgkmcnt(" #n ")" ::: "memory")
; #define PG8_BAR __builtin_amdgcn_s_barrier()
; #define PG8_SCHED __builtin_amdgcn_sched_barrier(0)
; template <class Epi, bool ALIGN_EPI = PG8_ALIGN, bool SP2 = PG8_SP2>
; __device__ __forceinline__ void gemm_phase(LAS uchar* lds, const Gemm g, const StaticOrder& S, const Epi& E) {
;     ...
;             PG8_LDB(B0, 1, 0); PG8_LDB(B1, 1, 1); PG8_SCHED; PG8_LDA(At, 1, 0); PG8_STAGE(PG8_SA(0, 1), a2 + hstepA, voffA);
;             PG8_WAIT_V(8); PG8_WAIT_L(0); PG8_BAR; PG8_MMA(0, 0, At, B0); PG8_MMA(0, 1, At, B1); PG8_BAR; PG8_SCHED;
	s_setprio 0
	s_add_i32 s39, 0, 0x18000
	v_add_u32_e32 v144, s39, v139
	s_add_i32 s40, 0, 0x1c000
	ds_read_b128 v[164:167], v144
	ds_read_b128 v[168:171], v144 offset:1024
	ds_read_b128 v[172:175], v144 offset:2048
	ds_read_b128 v[176:179], v144 offset:3072
	v_add_u32_e32 v144, s40, v139
	ds_read_b128 v[184:187], v144
	ds_read_b128 v[188:191], v144 offset:1024
	ds_read_b128 v[192:195], v144 offset:2048
	ds_read_b128 v[196:199], v144 offset:3072
	s_add_u32 s12, s18, 0x44000
	s_addc_u32 s13, s19, 0
	s_mov_b32 m0, s25
	v_lshl_add_u64 v[236:237], s[12:13], 0, v[154:155]
	ds_read_b128 v[200:203], v163 offset:32768
	ds_read_b128 v[204:207], v163 offset:33792
	ds_read_b128 v[208:211], v163 offset:34816
	ds_read_b128 v[212:215], v163 offset:35840
	ds_read_b128 v[216:219], v163 offset:36864
	ds_read_b128 v[220:223], v163 offset:37888
	ds_read_b128 v[224:227], v163 offset:38912
	ds_read_b128 v[228:231], v163 offset:39936
	global_load_lds_dwordx4 v[236:237], off
	s_mov_b32 m0, s26
	v_lshl_add_u64 v[236:237], s[12:13], 0, v[132:133]
	global_load_lds_dwordx4 v[236:237], off
	s_waitcnt vmcnt(8)
	s_waitcnt lgkmcnt(0)
	s_setprio 1
	s_barrier
	v_mfma_f32_16x16x32_bf16 v[126:129], v[164:167], v[200:203], v[126:129]
	v_mfma_f32_16x16x32_bf16 v[118:121], v[172:175], v[200:203], v[118:121]
	v_mfma_f32_16x16x32_bf16 v[110:113], v[164:167], v[208:211], v[110:113]
	v_mfma_f32_16x16x32_bf16 v[102:105], v[172:175], v[208:211], v[102:105]
	v_mfma_f32_16x16x32_bf16 v[94:97], v[164:167], v[216:219], v[94:97]
	v_mfma_f32_16x16x32_bf16 v[86:89], v[172:175], v[216:219], v[86:89]
	v_mfma_f32_16x16x32_bf16 v[78:81], v[164:167], v[224:227], v[78:81]
	v_mfma_f32_16x16x32_bf16 v[70:73], v[172:175], v[224:227], v[70:73]
	v_mfma_f32_16x16x32_bf16 v[126:129], v[168:171], v[204:207], v[126:129]
	v_mfma_f32_16x16x32_bf16 v[118:121], v[176:179], v[204:207], v[118:121]
	v_mfma_f32_16x16x32_bf16 v[110:113], v[168:171], v[212:215], v[110:113]
	v_mfma_f32_16x16x32_bf16 v[102:105], v[176:179], v[212:215], v[102:105]
	v_mfma_f32_16x16x32_bf16 v[94:97], v[168:171], v[220:223], v[94:97]
	v_mfma_f32_16x16x32_bf16 v[86:89], v[176:179], v[220:223], v[86:89]
	v_mfma_f32_16x16x32_bf16 v[78:81], v[168:171], v[228:231], v[78:81]
	v_mfma_f32_16x16x32_bf16 v[70:73], v[176:179], v[228:231], v[70:73]
	v_mfma_f32_16x16x32_bf16 v[122:125], v[184:187], v[200:203], v[122:125]
	v_mfma_f32_16x16x32_bf16 v[114:117], v[192:195], v[200:203], v[114:117]
	v_mfma_f32_16x16x32_bf16 v[106:109], v[184:187], v[208:211], v[106:109]
	v_mfma_f32_16x16x32_bf16 v[98:101], v[192:195], v[208:211], v[98:101]
	v_mfma_f32_16x16x32_bf16 v[90:93], v[184:187], v[216:219], v[90:93]
	v_mfma_f32_16x16x32_bf16 v[82:85], v[192:195], v[216:219], v[82:85]
	v_mfma_f32_16x16x32_bf16 v[74:77], v[184:187], v[224:227], v[74:77]
	v_mfma_f32_16x16x32_bf16 v[66:69], v[192:195], v[224:227], v[66:69]
	v_mfma_f32_16x16x32_bf16 v[122:125], v[188:191], v[204:207], v[122:125]
	v_mfma_f32_16x16x32_bf16 v[114:117], v[196:199], v[204:207], v[114:117]
	v_mfma_f32_16x16x32_bf16 v[106:109], v[188:191], v[212:215], v[106:109]
	v_mfma_f32_16x16x32_bf16 v[98:101], v[196:199], v[212:215], v[98:101]
	v_mfma_f32_16x16x32_bf16 v[90:93], v[188:191], v[220:223], v[90:93]
	v_mfma_f32_16x16x32_bf16 v[82:85], v[196:199], v[220:223], v[82:85]
	v_mfma_f32_16x16x32_bf16 v[74:77], v[188:191], v[228:231], v[74:77]
	v_mfma_f32_16x16x32_bf16 v[66:69], v[196:199], v[228:231], v[66:69]
	s_barrier
; #define PG8_STAGE(bufoff, gbase, voff) do { _Pragma("unroll") for (int _i = 0; _i < 2; ++_i) \
;         __builtin_amdgcn_global_load_lds((const unsigned*)((const char*)(gbase) + (voff)[_i]), (LAS unsigned*)(lds + (bufoff) + ldsw + _i * 8192), 16, 0, 0); } while (0)
; #define PG8_LDA(dst, b, h) do { _Pragma("unroll") for (int m = 0; m < 4; ++m) _Pragma("unroll") for (int k = 0; k < 2; ++k) dst[m][k] = *(const LAS bf16x8*)(lds + PG8_SA(b, h) + aoff + m * 2048 + k * 1024); } while (0)
; #define PG8_LDB(dst, b, h) do { _Pragma("unroll") for (int n = 0; n < 2; ++n) _Pragma("unroll") for (int k = 0; k < 2; ++k) dst[n][k] = *(const LAS bf16x8*)(lds + PG8_SB(b, h) + boff + n * 2048 + k * 1024); } while (0)
; template <class Epi, bool ALIGN_EPI = PG8_ALIGN, bool SP2 = PG8_SP2>
; __device__ __forceinline__ void gemm_phase(LAS uchar* lds, const Gemm g, const StaticOrder& S, const Epi& E) {
;     ...
;         for (int t = tb; t < tb + tblk; t += 2) {
;             const bool last = (t == nt - 2);
;             const char* a1 = cA + (size_t)(t + 1) * kstep;
;             const char* a2 = last ? nA : cA + (size_t)(t + 2) * kstep; const char* b2 = last ? nB : cB + (size_t)(t + 2) * kstep;
;             const char* a3 = a2 + kstep; const char* b3 = b2 + kstep;
;             if constexpr (SP2) {
;             PG8_LDB(B0, 0, 0); PG8_LDB(B1, 0, 1); PG8_SCHED; PG8_LDA(At, 0, 0); PG8_STAGE(PG8_SA(1, 1), a1 + hstepA, voffA);
;             PG8_WAIT_V(8); PG8_WAIT_L(0); PG8_BAR; PG8_MMA(0, 0, At, B0); PG8_MMA(0, 1, At, B1); PG8_BAR; PG8_SCHED;
;             PG8_LDA(At, 0, 1); PG8_STAGE(PG8_SB(0, 0), b2, voffB); PG8_STAGE(PG8_SB(0, 1), b2 + hstepB, voffB); PG8_STAGE(PG8_SA(0, 0), a2, voffA);
;             PG8_WAIT_V(8); PG8_WAIT_L(0); PG8_BAR; PG8_MMA(1, 0, At, B0); PG8_MMA(1, 1, At, B1); PG8_BAR; PG8_SCHED;
;             PG8_LDB(B0, 1, 0); PG8_LDB(B1, 1, 1); PG8_SCHED; PG8_LDA(At, 1, 0); PG8_STAGE(PG8_SA(0, 1), a2 + hstepA, voffA);
;             PG8_WAIT_V(8); PG8_WAIT_L(0); PG8_BAR; PG8_MMA(0, 0, At, B0); PG8_MMA(0, 1, At, B1); PG8_BAR; PG8_SCHED;
;             PG8_LDA(At, 1, 1); PG8_STAGE(PG8_SB(1, 0), b3, voffB); PG8_STAGE(PG8_SB(1, 1), b3 + hstepB, voffB); PG8_STAGE(PG8_SA(1, 0), a3, voffA);
;             PG8_WAIT_V(8); PG8_WAIT_L(0); PG8_BAR; PG8_MMA(1, 0, At, B0); PG8_MMA(1, 1, At, B1); PG8_BAR; PG8_SCHED;
;     ...
;         if constexpr (ALIGN_EPI) { if (wr == 0) PG8_BAR; }
	s_setprio 0
	s_add_i32 s12, s39, s21
	v_lshl_add_u64 v[160:161], v[160:161], 0, s[84:85]
	s_mov_b32 m0, s12
	ds_read_b128 v[200:203], v163 offset:49152
	ds_read_b128 v[204:207], v163 offset:50176
	ds_read_b128 v[208:211], v163 offset:51200
	ds_read_b128 v[212:215], v163 offset:52224
	ds_read_b128 v[216:219], v163 offset:53248
	ds_read_b128 v[220:223], v163 offset:54272
	ds_read_b128 v[224:227], v163 offset:55296
	ds_read_b128 v[228:231], v163 offset:56320
	global_load_lds_dwordx4 v[160:161], off
	s_add_i32 m0, s12, 0x2000
	s_add_u32 s12, s16, 0x44080
	v_lshl_add_u64 v[160:161], v[180:181], 0, s[84:85]
	s_addc_u32 s13, s17, 0
	s_add_i32 s16, s40, s21
	global_load_lds_dwordx4 v[160:161], off
	s_mov_b32 m0, s16
	v_lshl_add_u64 v[160:161], s[12:13], 0, v[134:135]
	global_load_lds_dwordx4 v[160:161], off
	s_add_i32 m0, s16, 0x2000
	v_lshl_add_u64 v[160:161], s[12:13], 0, v[130:131]
	global_load_lds_dwordx4 v[160:161], off
	s_mov_b32 m0, s27
	v_lshl_add_u64 v[160:161], v[232:233], 0, s[84:85]
	global_load_lds_dwordx4 v[160:161], off
	s_mov_b32 m0, s28
	v_lshl_add_u64 v[160:161], v[234:235], 0, s[84:85]
	global_load_lds_dwordx4 v[160:161], off
	s_waitcnt vmcnt(8)
	s_waitcnt lgkmcnt(0)
	s_setprio 1
	s_barrier
	v_mfma_f32_16x16x32_bf16 v[62:65], v[164:167], v[200:203], v[62:65]
	v_mfma_f32_16x16x32_bf16 v[54:57], v[172:175], v[200:203], v[54:57]
	v_mfma_f32_16x16x32_bf16 v[46:49], v[164:167], v[208:211], v[46:49]
	v_mfma_f32_16x16x32_bf16 v[38:41], v[172:175], v[208:211], v[38:41]
	v_mfma_f32_16x16x32_bf16 v[30:33], v[164:167], v[216:219], v[30:33]
	v_mfma_f32_16x16x32_bf16 v[22:25], v[172:175], v[216:219], v[22:25]
	v_mfma_f32_16x16x32_bf16 v[14:17], v[164:167], v[224:227], v[14:17]
	v_mfma_f32_16x16x32_bf16 v[6:9], v[172:175], v[224:227], v[6:9]
	v_mfma_f32_16x16x32_bf16 v[62:65], v[168:171], v[204:207], v[62:65]
	v_mfma_f32_16x16x32_bf16 v[54:57], v[176:179], v[204:207], v[54:57]
	v_mfma_f32_16x16x32_bf16 v[46:49], v[168:171], v[212:215], v[46:49]
	v_mfma_f32_16x16x32_bf16 v[38:41], v[176:179], v[212:215], v[38:41]
	v_mfma_f32_16x16x32_bf16 v[30:33], v[168:171], v[220:223], v[30:33]
	v_mfma_f32_16x16x32_bf16 v[22:25], v[176:179], v[220:223], v[22:25]
	v_mfma_f32_16x16x32_bf16 v[14:17], v[168:171], v[228:231], v[14:17]
	v_mfma_f32_16x16x32_bf16 v[6:9], v[176:179], v[228:231], v[6:9]
	v_mfma_f32_16x16x32_bf16 v[58:61], v[184:187], v[200:203], v[58:61]
	v_mfma_f32_16x16x32_bf16 v[50:53], v[192:195], v[200:203], v[50:53]
	v_mfma_f32_16x16x32_bf16 v[42:45], v[184:187], v[208:211], v[42:45]
	v_mfma_f32_16x16x32_bf16 v[34:37], v[192:195], v[208:211], v[34:37]
	v_mfma_f32_16x16x32_bf16 v[26:29], v[184:187], v[216:219], v[26:29]
	v_mfma_f32_16x16x32_bf16 v[18:21], v[192:195], v[216:219], v[18:21]
	v_mfma_f32_16x16x32_bf16 v[10:13], v[184:187], v[224:227], v[10:13]
	v_mfma_f32_16x16x32_bf16 v[2:5], v[192:195], v[224:227], v[2:5]
	v_mfma_f32_16x16x32_bf16 v[58:61], v[188:191], v[204:207], v[58:61]
	v_mfma_f32_16x16x32_bf16 v[50:53], v[196:199], v[204:207], v[50:53]
	v_mfma_f32_16x16x32_bf16 v[42:45], v[188:191], v[212:215], v[42:45]
	v_mfma_f32_16x16x32_bf16 v[34:37], v[196:199], v[212:215], v[34:37]
	v_mfma_f32_16x16x32_bf16 v[26:29], v[188:191], v[220:223], v[26:29]
	v_mfma_f32_16x16x32_bf16 v[18:21], v[196:199], v[220:223], v[18:21]
	v_mfma_f32_16x16x32_bf16 v[10:13], v[188:191], v[228:231], v[10:13]
	v_mfma_f32_16x16x32_bf16 v[2:5], v[196:199], v[228:231], v[2:5]
	s_barrier
	s_setprio 0
	s_add_i32 s38, s38, 2
	s_add_u32 s36, s36, 0x100
	s_addc_u32 s37, s37, 0
	s_cmp_gt_u32 s38, 13
	s_mov_b64 s[12:13], s[14:15]
	s_cbranch_scc0 .LBB0_1050
	s_and_b64 vcc, exec, s[8:9]
	s_cbranch_vccz .LBB0_1053
	s_barrier

; #define PG8_STAGE(bufoff, gbase, voff) do { _Pragma("unroll") for (int _i = 0; _i < 2; ++_i) \
;         __builtin_amdgcn_global_load_lds((const unsigned*)((const char*)(gbase) + (voff)[_i]), (LAS unsigned*)(lds + (bufoff) + ldsw + _i * 8192), 16, 0, 0); } while (0)
; #define PG8_LDA(dst, b, h) do { _Pragma("unroll") for (int m = 0; m < 4; ++m) _Pragma("unroll") for (int k = 0; k < 2; ++k) dst[m][k] = *(const LAS bf16x8*)(lds + PG8_SA(b, h) + aoff + m * 2048 + k * 1024); } while (0)
; #define PG8_LDB(dst, b, h) do { _Pragma("unroll") for (int n = 0; n < 2; ++n) _Pragma("unroll") for (int k = 0; k < 2; ++k) dst[n][k] = *(const LAS bf16x8*)(lds + PG8_SB(b, h) + boff + n * 2048 + k * 1024); } while (0)
; #define PG8_MMA(ai, bj, At, Bt) do { __builtin_amdgcn_s_setprio(1); _Pragma("unroll") for (int m = 0; m < 4; ++m) _Pragma("unroll") for (int n = 0; n < 2; ++n) _Pragma("unroll") for (int k = 0; k < 2; ++k) \
;         acc[ai][bj][m][n] = __builtin_amdgcn_mfma_f32_16x16x32_bf16(Bt[n][k], At[m][k], acc[ai][bj][m][n], 0, 0, 0); __builtin_amdgcn_s_setprio(0); } while (0)
; #define PG8_WAIT_V(n) asm volatile("s_waitcnt vmcnt(" #n ")" ::: "memory")
; #define PG8_WAIT_L(n) asm volatile("s_waitcnt lgkmcnt(" #n ")" ::: "memory")
; #define PG8_BAR __builtin_amdgcn_s_barrier()
; #define PG8_SCHED __builtin_amdgcn_sched_barrier(0)
; template <class Epi, bool ALIGN_EPI = PG8_ALIGN, bool SP2 = PG8_SP2>
; __device__ __forceinline__ void gemm_phase(LAS uchar* lds, const Gemm g, const StaticOrder& S, const Epi& E) {
;     ...
;         for (int t = tb; t < tb + tblk; t += 2) {
;             const bool last = (t == nt - 2);
;             const char* a1 = cA + (size_t)(t + 1) * kstep;
;             const char* a2 = last ? nA : cA + (size_t)(t + 2) * kstep; const char* b2 = last ? nB : cB + (size_t)(t + 2) * kstep;
;             const char* a3 = a2 + kstep; const char* b3 = b2 + kstep;
;             if constexpr (SP2) {
;             PG8_LDB(B0, 0, 0); PG8_LDB(B1, 0, 1); PG8_SCHED; PG8_LDA(At, 0, 0); PG8_STAGE(PG8_SA(1, 1), a1 + hstepA, voffA);
;             PG8_WAIT_V(8); PG8_WAIT_L(0); PG8_BAR; PG8_MMA(0, 0, At, B0); PG8_MMA(0, 1, At, B1); PG8_BAR; PG8_SCHED;
;             PG8_LDA(At, 0, 1); PG8_STAGE(PG8_SB(0, 0), b2, voffB); PG8_STAGE(PG8_SB(0, 1), b2 + hstepB, voffB); PG8_STAGE(PG8_SA(0, 0), a2, voffA);
.LBB0_1142:
	s_add_u32 s38, s16, 0x100
	s_addc_u32 s39, s17, 0
	s_mov_b32 s40, -2
	s_add_u32 s16, s14, 0x100
	s_addc_u32 s17, s15, 0
	s_add_i32 s41, 0, 0x10000
	s_cmp_eq_u32 s40, 40
	s_cselect_b32 s21, s5, s17
	s_cselect_b32 s20, s4, s16
	v_add_u32_e32 v144, s41, v139
	s_cselect_b32 s19, s13, s39
	s_cselect_b32 s18, s12, s38
	s_add_i32 s42, 0, 0x14000
	ds_read_b128 v[160:163], v144
	ds_read_b128 v[166:169], v144 offset:1024
	ds_read_b128 v[170:173], v144 offset:2048
	ds_read_b128 v[174:177], v144 offset:3072
	v_add_u32_e32 v144, s42, v139
	ds_read_b128 v[178:181], v144
	ds_read_b128 v[184:187], v144 offset:1024
	ds_read_b128 v[188:191], v144 offset:2048
	ds_read_b128 v[192:195], v144 offset:3072
	v_lshl_add_u64 v[228:229], s[14:15], 0, v[156:157]
	s_add_i32 m0, s25, 0xc000
	ds_read_b128 v[196:199], v165
	ds_read_b128 v[200:203], v165 offset:1024
	ds_read_b128 v[204:207], v165 offset:2048
	ds_read_b128 v[208:211], v165 offset:3072
	ds_read_b128 v[212:215], v165 offset:4096
	ds_read_b128 v[216:219], v165 offset:5120
	ds_read_b128 v[220:223], v165 offset:6144
	ds_read_b128 v[224:227], v165 offset:7168
	global_load_lds_dwordx4 v[228:229], off
	s_add_i32 m0, s25, 0xe000
	v_lshl_add_u64 v[228:229], s[14:15], 0, v[158:159]
	global_load_lds_dwordx4 v[228:229], off
	s_waitcnt vmcnt(8)
	s_waitcnt lgkmcnt(0)
	s_setprio 1
	s_barrier
	v_mfma_f32_16x16x32_bf16 v[126:129], v[160:163], v[196:199], 0
	v_mfma_f32_16x16x32_bf16 v[122:125], v[170:173], v[196:199], 0
	v_mfma_f32_16x16x32_bf16 v[118:121], v[160:163], v[204:207], 0
	v_mfma_f32_16x16x32_bf16 v[110:113], v[170:173], v[204:207], 0
	v_mfma_f32_16x16x32_bf16 v[102:105], v[160:163], v[212:215], 0
	v_mfma_f32_16x16x32_bf16 v[94:97], v[170:173], v[212:215], 0
	v_mfma_f32_16x16x32_bf16 v[86:89], v[160:163], v[220:223], 0
	v_mfma_f32_16x16x32_bf16 v[78:81], v[170:173], v[220:223], 0
	v_mfma_f32_16x16x32_bf16 v[126:129], v[166:169], v[200:203], v[126:129]
	v_mfma_f32_16x16x32_bf16 v[122:125], v[174:177], v[200:203], v[122:125]
	v_mfma_f32_16x16x32_bf16 v[118:121], v[166:169], v[208:211], v[118:121]
	v_mfma_f32_16x16x32_bf16 v[110:113], v[174:177], v[208:211], v[110:113]
	v_mfma_f32_16x16x32_bf16 v[102:105], v[166:169], v[216:219], v[102:105]
	v_mfma_f32_16x16x32_bf16 v[94:97], v[174:177], v[216:219], v[94:97]
	v_mfma_f32_16x16x32_bf16 v[86:89], v[166:169], v[224:227], v[86:89]
	v_mfma_f32_16x16x32_bf16 v[78:81], v[174:177], v[224:227], v[78:81]
	v_mfma_f32_16x16x32_bf16 v[114:117], v[178:181], v[196:199], 0
	v_mfma_f32_16x16x32_bf16 v[106:109], v[188:191], v[196:199], 0
	v_mfma_f32_16x16x32_bf16 v[98:101], v[178:181], v[204:207], 0
	v_mfma_f32_16x16x32_bf16 v[90:93], v[188:191], v[204:207], 0
	v_mfma_f32_16x16x32_bf16 v[82:85], v[178:181], v[212:215], 0
	v_mfma_f32_16x16x32_bf16 v[74:77], v[188:191], v[212:215], 0
	v_mfma_f32_16x16x32_bf16 v[70:73], v[178:181], v[220:223], 0
	v_mfma_f32_16x16x32_bf16 v[66:69], v[188:191], v[220:223], 0
	v_mfma_f32_16x16x32_bf16 v[114:117], v[184:187], v[200:203], v[114:117]
	v_mfma_f32_16x16x32_bf16 v[106:109], v[192:195], v[200:203], v[106:109]
	v_mfma_f32_16x16x32_bf16 v[98:101], v[184:187], v[208:211], v[98:101]
	v_mfma_f32_16x16x32_bf16 v[90:93], v[192:195], v[208:211], v[90:93]
	v_mfma_f32_16x16x32_bf16 v[82:85], v[184:187], v[216:219], v[82:85]
	v_mfma_f32_16x16x32_bf16 v[74:77], v[192:195], v[216:219], v[74:77]
	v_mfma_f32_16x16x32_bf16 v[70:73], v[184:187], v[224:227], v[70:73]
	v_mfma_f32_16x16x32_bf16 v[66:69], v[192:195], v[224:227], v[66:69]
	s_barrier
	s_setprio 0
	s_add_i32 s14, s41, s24
	v_lshl_add_u64 v[228:229], s[18:19], 0, v[132:133]
	s_mov_b32 m0, s14
	ds_read_b128 v[196:199], v165 offset:16384
	ds_read_b128 v[200:203], v165 offset:17408
	ds_read_b128 v[204:207], v165 offset:18432
	ds_read_b128 v[208:211], v165 offset:19456
	ds_read_b128 v[212:215], v165 offset:20480
	ds_read_b128 v[216:219], v165 offset:21504
	ds_read_b128 v[220:223], v165 offset:22528
	ds_read_b128 v[224:227], v165 offset:23552
	global_load_lds_dwordx4 v[228:229], off
	s_add_i32 m0, s14, 0x2000
	s_add_u32 s14, s18, 0xb0000
	v_lshl_add_u64 v[230:231], s[18:19], 0, v[154:155]
	s_addc_u32 s15, s19, 0
	s_add_i32 s41, s42, s24
	global_load_lds_dwordx4 v[230:231], off
	v_lshl_add_u64 v[232:233], s[14:15], 0, v[132:133]
	s_mov_b32 m0, s41
	global_load_lds_dwordx4 v[232:233], off
	s_add_i32 m0, s41, 0x2000
	v_lshl_add_u64 v[232:233], s[14:15], 0, v[154:155]
	global_load_lds_dwordx4 v[232:233], off
	s_mov_b32 m0, s25
	v_lshl_add_u64 v[232:233], s[20:21], 0, v[130:131]
	global_load_lds_dwordx4 v[232:233], off
	s_mov_b32 m0, s26
	v_lshl_add_u64 v[234:235], s[20:21], 0, v[134:135]
	global_load_lds_dwordx4 v[234:235], off
	s_waitcnt vmcnt(8)
	s_waitcnt lgkmcnt(0)
	s_setprio 1
	s_barrier
; #define PG8_STAGE(bufoff, gbase, voff) do { _Pragma("unroll") for (int _i = 0; _i < 2; ++_i) \
;         __builtin_amdgcn_global_load_lds((const unsigned*)((const char*)(gbase) + (voff)[_i]), (LAS unsigned*)(lds + (bufoff) + ldsw + _i * 8192), 16, 0, 0); } while (0)
; #define PG8_LDA(dst, b, h) do { _Pragma("unroll") for (int m = 0; m < 4; ++m) _Pragma("unroll") for (int k = 0; k < 2; ++k) dst[m][k] = *(const LAS bf16x8*)(lds + PG8_SA(b, h) + aoff + m * 2048 + k * 1024); } while (0)
; #define PG8_LDB(dst, b, h) do { _Pragma("unroll") for (int n = 0; n < 2; ++n) _Pragma("unroll") for (int k = 0; k < 2; ++k) dst[n][k] = *(const LAS bf16x8*)(lds + PG8_SB(b, h) + boff + n * 2048 + k * 1024); } while (0)
; #define PG8_MMA(ai, bj, At, Bt) do { __builtin_amdgcn_s_setprio(1); _Pragma("unroll") for (int m = 0; m < 4; ++m) _Pragma("unroll") for (int n = 0; n < 2; ++n) _Pragma("unroll") for (int k = 0; k < 2; ++k) \
;         acc[ai][bj][m][n] = __builtin_amdgcn_mfma_f32_16x16x32_bf16(Bt[n][k], At[m][k], acc[ai][bj][m][n], 0, 0, 0); __builtin_amdgcn_s_setprio(0); } while (0)
; #define PG8_WAIT_V(n) asm volatile("s_waitcnt vmcnt(" #n ")" ::: "memory")
; #define PG8_WAIT_L(n) asm volatile("s_waitcnt lgkmcnt(" #n ")" ::: "memory")
; #define PG8_BAR __builtin_amdgcn_s_barrier()
; #define PG8_SCHED __builtin_amdgcn_sched_barrier(0)
; template <class Epi, bool ALIGN_EPI = PG8_ALIGN, bool SP2 = PG8_SP2>
; __device__ __forceinline__ void gemm_phase(LAS uchar* lds, const Gemm g, const StaticOrder& S, const Epi& E) {
;     ...
;             PG8_LDA(At, 0, 1); PG8_STAGE(PG8_SB(0, 0), b2, voffB); PG8_STAGE(PG8_SB(0, 1), b2 + hstepB, voffB); PG8_STAGE(PG8_SA(0, 0), a2, voffA);
;             PG8_WAIT_V(8); PG8_WAIT_L(0); PG8_BAR; PG8_MMA(1, 0, At, B0); PG8_MMA(1, 1, At, B1); PG8_BAR; PG8_SCHED;
;             PG8_LDB(B0, 1, 0); PG8_LDB(B1, 1, 1); PG8_SCHED; PG8_LDA(At, 1, 0); PG8_STAGE(PG8_SA(0, 1), a2 + hstepA, voffA);
;             PG8_WAIT_V(8); PG8_WAIT_L(0); PG8_BAR; PG8_MMA(0, 0, At, B0); PG8_MMA(0, 1, At, B1); PG8_BAR; PG8_SCHED;
	v_mfma_f32_16x16x32_bf16 v[62:65], v[160:163], v[196:199], 0
	v_mfma_f32_16x16x32_bf16 v[58:61], v[170:173], v[196:199], 0
	v_mfma_f32_16x16x32_bf16 v[54:57], v[160:163], v[204:207], 0
	v_mfma_f32_16x16x32_bf16 v[46:49], v[170:173], v[204:207], 0
	v_mfma_f32_16x16x32_bf16 v[38:41], v[160:163], v[212:215], 0
	v_mfma_f32_16x16x32_bf16 v[30:33], v[170:173], v[212:215], 0
	v_mfma_f32_16x16x32_bf16 v[22:25], v[160:163], v[220:223], 0
	v_mfma_f32_16x16x32_bf16 v[14:17], v[170:173], v[220:223], 0
	v_mfma_f32_16x16x32_bf16 v[62:65], v[166:169], v[200:203], v[62:65]
	v_mfma_f32_16x16x32_bf16 v[58:61], v[174:177], v[200:203], v[58:61]
	v_mfma_f32_16x16x32_bf16 v[54:57], v[166:169], v[208:211], v[54:57]
	v_mfma_f32_16x16x32_bf16 v[46:49], v[174:177], v[208:211], v[46:49]
	v_mfma_f32_16x16x32_bf16 v[38:41], v[166:169], v[216:219], v[38:41]
	v_mfma_f32_16x16x32_bf16 v[30:33], v[174:177], v[216:219], v[30:33]
	v_mfma_f32_16x16x32_bf16 v[22:25], v[166:169], v[224:227], v[22:25]
	v_mfma_f32_16x16x32_bf16 v[14:17], v[174:177], v[224:227], v[14:17]
	v_mfma_f32_16x16x32_bf16 v[50:53], v[178:181], v[196:199], 0
	v_mfma_f32_16x16x32_bf16 v[42:45], v[188:191], v[196:199], 0
	v_mfma_f32_16x16x32_bf16 v[34:37], v[178:181], v[204:207], 0
	v_mfma_f32_16x16x32_bf16 v[26:29], v[188:191], v[204:207], 0
	v_mfma_f32_16x16x32_bf16 v[18:21], v[178:181], v[212:215], 0
	v_mfma_f32_16x16x32_bf16 v[10:13], v[188:191], v[212:215], 0
	v_mfma_f32_16x16x32_bf16 v[6:9], v[178:181], v[220:223], 0
	v_mfma_f32_16x16x32_bf16 v[2:5], v[188:191], v[220:223], 0
	v_mfma_f32_16x16x32_bf16 v[50:53], v[184:187], v[200:203], v[50:53]
	v_mfma_f32_16x16x32_bf16 v[42:45], v[192:195], v[200:203], v[42:45]
	v_mfma_f32_16x16x32_bf16 v[34:37], v[184:187], v[208:211], v[34:37]
	v_mfma_f32_16x16x32_bf16 v[26:29], v[192:195], v[208:211], v[26:29]
	v_mfma_f32_16x16x32_bf16 v[18:21], v[184:187], v[216:219], v[18:21]
	v_mfma_f32_16x16x32_bf16 v[10:13], v[192:195], v[216:219], v[10:13]
	v_mfma_f32_16x16x32_bf16 v[6:9], v[184:187], v[224:227], v[6:9]
	v_mfma_f32_16x16x32_bf16 v[2:5], v[192:195], v[224:227], v[2:5]
	s_barrier
	s_setprio 0
	s_add_i32 s41, 0, 0x18000
	v_add_u32_e32 v144, s41, v139
	s_add_i32 s42, 0, 0x1c000
	ds_read_b128 v[160:163], v144
	ds_read_b128 v[166:169], v144 offset:1024
	ds_read_b128 v[170:173], v144 offset:2048
	ds_read_b128 v[174:177], v144 offset:3072
	v_add_u32_e32 v144, s42, v139
	ds_read_b128 v[178:181], v144
	ds_read_b128 v[184:187], v144 offset:1024
	ds_read_b128 v[188:191], v144 offset:2048
	ds_read_b128 v[192:195], v144 offset:3072
	s_add_u32 s14, s20, 0xb0000
	s_addc_u32 s15, s21, 0
	s_mov_b32 m0, s27
	v_lshl_add_u64 v[236:237], s[14:15], 0, v[130:131]
	ds_read_b128 v[196:199], v165 offset:32768
	ds_read_b128 v[200:203], v165 offset:33792
	ds_read_b128 v[204:207], v165 offset:34816
	ds_read_b128 v[208:211], v165 offset:35840
	ds_read_b128 v[212:215], v165 offset:36864
	ds_read_b128 v[216:219], v165 offset:37888
	ds_read_b128 v[220:223], v165 offset:38912
	ds_read_b128 v[224:227], v165 offset:39936
	global_load_lds_dwordx4 v[236:237], off
	s_mov_b32 m0, s28
	v_lshl_add_u64 v[236:237], s[14:15], 0, v[134:135]
	global_load_lds_dwordx4 v[236:237], off
	s_waitcnt vmcnt(8)
	s_waitcnt lgkmcnt(0)
	s_setprio 1
	s_barrier
	v_mfma_f32_16x16x32_bf16 v[126:129], v[160:163], v[196:199], v[126:129]
	v_mfma_f32_16x16x32_bf16 v[122:125], v[170:173], v[196:199], v[122:125]
	v_mfma_f32_16x16x32_bf16 v[118:121], v[160:163], v[204:207], v[118:121]
	v_mfma_f32_16x16x32_bf16 v[110:113], v[170:173], v[204:207], v[110:113]
	v_mfma_f32_16x16x32_bf16 v[102:105], v[160:163], v[212:215], v[102:105]
	v_mfma_f32_16x16x32_bf16 v[94:97], v[170:173], v[212:215], v[94:97]
	v_mfma_f32_16x16x32_bf16 v[86:89], v[160:163], v[220:223], v[86:89]
	v_mfma_f32_16x16x32_bf16 v[78:81], v[170:173], v[220:223], v[78:81]
	v_mfma_f32_16x16x32_bf16 v[126:129], v[166:169], v[200:203], v[126:129]
	v_mfma_f32_16x16x32_bf16 v[122:125], v[174:177], v[200:203], v[122:125]
	v_mfma_f32_16x16x32_bf16 v[118:121], v[166:169], v[208:211], v[118:121]
	v_mfma_f32_16x16x32_bf16 v[110:113], v[174:177], v[208:211], v[110:113]
	v_mfma_f32_16x16x32_bf16 v[102:105], v[166:169], v[216:219], v[102:105]
	v_mfma_f32_16x16x32_bf16 v[94:97], v[174:177], v[216:219], v[94:97]
	v_mfma_f32_16x16x32_bf16 v[86:89], v[166:169], v[224:227], v[86:89]
	v_mfma_f32_16x16x32_bf16 v[78:81], v[174:177], v[224:227], v[78:81]
	v_mfma_f32_16x16x32_bf16 v[114:117], v[178:181], v[196:199], v[114:117]
	v_mfma_f32_16x16x32_bf16 v[106:109], v[188:191], v[196:199], v[106:109]
	v_mfma_f32_16x16x32_bf16 v[98:101], v[178:181], v[204:207], v[98:101]
	v_mfma_f32_16x16x32_bf16 v[90:93], v[188:191], v[204:207], v[90:93]
	v_mfma_f32_16x16x32_bf16 v[82:85], v[178:181], v[212:215], v[82:85]
	v_mfma_f32_16x16x32_bf16 v[74:77], v[188:191], v[212:215], v[74:77]
	v_mfma_f32_16x16x32_bf16 v[70:73], v[178:181], v[220:223], v[70:73]
	v_mfma_f32_16x16x32_bf16 v[66:69], v[188:191], v[220:223], v[66:69]
	v_mfma_f32_16x16x32_bf16 v[114:117], v[184:187], v[200:203], v[114:117]
	v_mfma_f32_16x16x32_bf16 v[106:109], v[192:195], v[200:203], v[106:109]
	v_mfma_f32_16x16x32_bf16 v[98:101], v[184:187], v[208:211], v[98:101]
	v_mfma_f32_16x16x32_bf16 v[90:93], v[192:195], v[208:211], v[90:93]
	v_mfma_f32_16x16x32_bf16 v[82:85], v[184:187], v[216:219], v[82:85]
	v_mfma_f32_16x16x32_bf16 v[74:77], v[192:195], v[216:219], v[74:77]
	v_mfma_f32_16x16x32_bf16 v[70:73], v[184:187], v[224:227], v[70:73]
	v_mfma_f32_16x16x32_bf16 v[66:69], v[192:195], v[224:227], v[66:69]
	s_barrier
; #define PG8_STAGE(bufoff, gbase, voff) do { _Pragma("unroll") for (int _i = 0; _i < 2; ++_i) \
;         __builtin_amdgcn_global_load_lds((const unsigned*)((const char*)(gbase) + (voff)[_i]), (LAS unsigned*)(lds + (bufoff) + ldsw + _i * 8192), 16, 0, 0); } while (0)
; #define PG8_LDA(dst, b, h) do { _Pragma("unroll") for (int m = 0; m < 4; ++m) _Pragma("unroll") for (int k = 0; k < 2; ++k) dst[m][k] = *(const LAS bf16x8*)(lds + PG8_SA(b, h) + aoff + m * 2048 + k * 1024); } while (0)
; #define PG8_LDB(dst, b, h) do { _Pragma("unroll") for (int n = 0; n < 2; ++n) _Pragma("unroll") for (int k = 0; k < 2; ++k) dst[n][k] = *(const LAS bf16x8*)(lds + PG8_SB(b, h) + boff + n * 2048 + k * 1024); } while (0)
; #define PG8_BAR __builtin_amdgcn_s_barrier()
; template <class Epi, bool ALIGN_EPI = PG8_ALIGN, bool SP2 = PG8_SP2>
; __device__ __forceinline__ void gemm_phase(LAS uchar* lds, const Gemm g, const StaticOrder& S, const Epi& E) {
;     ...
;         for (int t = tb; t < tb + tblk; t += 2) {
;             const bool last = (t == nt - 2);
;             const char* a1 = cA + (size_t)(t + 1) * kstep;
;             const char* a2 = last ? nA : cA + (size_t)(t + 2) * kstep; const char* b2 = last ? nB : cB + (size_t)(t + 2) * kstep;
;             const char* a3 = a2 + kstep; const char* b3 = b2 + kstep;
;             if constexpr (SP2) {
;             PG8_LDB(B0, 0, 0); PG8_LDB(B1, 0, 1); PG8_SCHED; PG8_LDA(At, 0, 0); PG8_STAGE(PG8_SA(1, 1), a1 + hstepA, voffA);
;             PG8_WAIT_V(8); PG8_WAIT_L(0); PG8_BAR; PG8_MMA(0, 0, At, B0); PG8_MMA(0, 1, At, B1); PG8_BAR; PG8_SCHED;
;             PG8_LDA(At, 0, 1); PG8_STAGE(PG8_SB(0, 0), b2, voffB); PG8_STAGE(PG8_SB(0, 1), b2 + hstepB, voffB); PG8_STAGE(PG8_SA(0, 0), a2, voffA);
;             PG8_WAIT_V(8); PG8_WAIT_L(0); PG8_BAR; PG8_MMA(1, 0, At, B0); PG8_MMA(1, 1, At, B1); PG8_BAR; PG8_SCHED;
;             PG8_LDB(B0, 1, 0); PG8_LDB(B1, 1, 1); PG8_SCHED; PG8_LDA(At, 1, 0); PG8_STAGE(PG8_SA(0, 1), a2 + hstepA, voffA);
;             PG8_WAIT_V(8); PG8_WAIT_L(0); PG8_BAR; PG8_MMA(0, 0, At, B0); PG8_MMA(0, 1, At, B1); PG8_BAR; PG8_SCHED;
;             PG8_LDA(At, 1, 1); PG8_STAGE(PG8_SB(1, 0), b3, voffB); PG8_STAGE(PG8_SB(1, 1), b3 + hstepB, voffB); PG8_STAGE(PG8_SA(1, 0), a3, voffA);
;             PG8_WAIT_V(8); PG8_WAIT_L(0); PG8_BAR; PG8_MMA(1, 0, At, B0); PG8_MMA(1, 1, At, B1); PG8_BAR; PG8_SCHED;
	s_setprio 0
	s_add_i32 s14, s41, s24
	v_lshl_add_u64 v[228:229], v[228:229], 0, s[84:85]
	s_mov_b32 m0, s14
	ds_read_b128 v[196:199], v165 offset:49152
	ds_read_b128 v[200:203], v165 offset:50176
	ds_read_b128 v[204:207], v165 offset:51200
	ds_read_b128 v[208:211], v165 offset:52224
	ds_read_b128 v[212:215], v165 offset:53248
	ds_read_b128 v[216:219], v165 offset:54272
	ds_read_b128 v[220:223], v165 offset:55296
	ds_read_b128 v[224:227], v165 offset:56320
	global_load_lds_dwordx4 v[228:229], off
	s_add_i32 m0, s14, 0x2000
	s_add_u32 s14, s18, 0xb0080
	v_lshl_add_u64 v[228:229], v[230:231], 0, s[84:85]
	s_addc_u32 s15, s19, 0
	s_add_i32 s18, s42, s24
	global_load_lds_dwordx4 v[228:229], off
	s_mov_b32 m0, s18
	v_lshl_add_u64 v[228:229], s[14:15], 0, v[132:133]
	global_load_lds_dwordx4 v[228:229], off
	s_add_i32 m0, s18, 0x2000
	v_lshl_add_u64 v[228:229], s[14:15], 0, v[154:155]
	global_load_lds_dwordx4 v[228:229], off
	s_mov_b32 m0, s29
	v_lshl_add_u64 v[228:229], v[232:233], 0, s[84:85]
	global_load_lds_dwordx4 v[228:229], off
	s_mov_b32 m0, s30
	v_lshl_add_u64 v[228:229], v[234:235], 0, s[84:85]
	global_load_lds_dwordx4 v[228:229], off
	s_waitcnt vmcnt(8)
	s_waitcnt lgkmcnt(0)
	s_setprio 1
	s_barrier
	v_mfma_f32_16x16x32_bf16 v[62:65], v[160:163], v[196:199], v[62:65]
	v_mfma_f32_16x16x32_bf16 v[58:61], v[170:173], v[196:199], v[58:61]
	v_mfma_f32_16x16x32_bf16 v[54:57], v[160:163], v[204:207], v[54:57]
	v_mfma_f32_16x16x32_bf16 v[46:49], v[170:173], v[204:207], v[46:49]
	v_mfma_f32_16x16x32_bf16 v[38:41], v[160:163], v[212:215], v[38:41]
	v_mfma_f32_16x16x32_bf16 v[30:33], v[170:173], v[212:215], v[30:33]
	v_mfma_f32_16x16x32_bf16 v[22:25], v[160:163], v[220:223], v[22:25]
	v_mfma_f32_16x16x32_bf16 v[14:17], v[170:173], v[220:223], v[14:17]
	v_mfma_f32_16x16x32_bf16 v[62:65], v[166:169], v[200:203], v[62:65]
	v_mfma_f32_16x16x32_bf16 v[58:61], v[174:177], v[200:203], v[58:61]
	v_mfma_f32_16x16x32_bf16 v[54:57], v[166:169], v[208:211], v[54:57]
	v_mfma_f32_16x16x32_bf16 v[46:49], v[174:177], v[208:211], v[46:49]
	v_mfma_f32_16x16x32_bf16 v[38:41], v[166:169], v[216:219], v[38:41]
	v_mfma_f32_16x16x32_bf16 v[30:33], v[174:177], v[216:219], v[30:33]
	v_mfma_f32_16x16x32_bf16 v[22:25], v[166:169], v[224:227], v[22:25]
	v_mfma_f32_16x16x32_bf16 v[14:17], v[174:177], v[224:227], v[14:17]
	v_mfma_f32_16x16x32_bf16 v[50:53], v[178:181], v[196:199], v[50:53]
	v_mfma_f32_16x16x32_bf16 v[42:45], v[188:191], v[196:199], v[42:45]
	v_mfma_f32_16x16x32_bf16 v[34:37], v[178:181], v[204:207], v[34:37]
	v_mfma_f32_16x16x32_bf16 v[26:29], v[188:191], v[204:207], v[26:29]
	v_mfma_f32_16x16x32_bf16 v[18:21], v[178:181], v[212:215], v[18:21]
	v_mfma_f32_16x16x32_bf16 v[10:13], v[188:191], v[212:215], v[10:13]
	v_mfma_f32_16x16x32_bf16 v[6:9], v[178:181], v[220:223], v[6:9]
	v_mfma_f32_16x16x32_bf16 v[2:5], v[188:191], v[220:223], v[2:5]
	v_mfma_f32_16x16x32_bf16 v[50:53], v[184:187], v[200:203], v[50:53]
	v_mfma_f32_16x16x32_bf16 v[42:45], v[192:195], v[200:203], v[42:45]
	v_mfma_f32_16x16x32_bf16 v[34:37], v[184:187], v[208:211], v[34:37]
	v_mfma_f32_16x16x32_bf16 v[26:29], v[192:195], v[208:211], v[26:29]
	v_mfma_f32_16x16x32_bf16 v[18:21], v[184:187], v[216:219], v[18:21]
	v_mfma_f32_16x16x32_bf16 v[10:13], v[192:195], v[216:219], v[10:13]
	v_mfma_f32_16x16x32_bf16 v[6:9], v[184:187], v[224:227], v[6:9]
	v_mfma_f32_16x16x32_bf16 v[2:5], v[192:195], v[224:227], v[2:5]
	s_barrier
	s_setprio 0
	s_add_i32 s40, s40, 2
	s_add_u32 s38, s38, 0x100
	s_addc_u32 s39, s39, 0
	s_cmp_gt_u32 s40, 41
	s_mov_b64 s[14:15], s[16:17]
.LBB0_1143:
	s_add_u32 s16, s14, 0x100
	s_addc_u32 s17, s15, 0
	s_add_i32 s41, 0, 0x10000
	s_cmp_eq_u32 s40, 40
	s_cselect_b32 s21, s5, s17
	s_cselect_b32 s20, s4, s16
	v_add_u32_e32 v144, s41, v139
	s_cselect_b32 s19, s13, s39
	s_cselect_b32 s18, s12, s38
	s_add_i32 s42, 0, 0x14000
	ds_read_b128 v[160:163], v144
	ds_read_b128 v[166:169], v144 offset:1024
	ds_read_b128 v[170:173], v144 offset:2048
	ds_read_b128 v[174:177], v144 offset:3072
	v_add_u32_e32 v144, s42, v139
	ds_read_b128 v[178:181], v144
	ds_read_b128 v[184:187], v144 offset:1024
	ds_read_b128 v[188:191], v144 offset:2048
	ds_read_b128 v[192:195], v144 offset:3072
	v_lshl_add_u64 v[228:229], s[14:15], 0, v[156:157]
	s_add_i32 m0, s25, 0xc000
	ds_read_b128 v[196:199], v165
	ds_read_b128 v[200:203], v165 offset:1024
	ds_read_b128 v[204:207], v165 offset:2048
	ds_read_b128 v[208:211], v165 offset:3072
	ds_read_b128 v[212:215], v165 offset:4096
	ds_read_b128 v[216:219], v165 offset:5120
	ds_read_b128 v[220:223], v165 offset:6144
	ds_read_b128 v[224:227], v165 offset:7168
	global_load_lds_dwordx4 v[228:229], off
	s_add_i32 m0, s25, 0xe000
	v_lshl_add_u64 v[228:229], s[14:15], 0, v[158:159]
	global_load_lds_dwordx4 v[228:229], off
	s_waitcnt vmcnt(8)
	s_waitcnt lgkmcnt(0)
	s_setprio 1
	s_barrier
; #define PG8_STAGE(bufoff, gbase, voff) do { _Pragma("unroll") for (int _i = 0; _i < 2; ++_i) \
;         __builtin_amdgcn_global_load_lds((const unsigned*)((const char*)(gbase) + (voff)[_i]), (LAS unsigned*)(lds + (bufoff) + ldsw + _i * 8192), 16, 0, 0); } while (0)
; #define PG8_LDA(dst, b, h) do { _Pragma("unroll") for (int m = 0; m < 4; ++m) _Pragma("unroll") for (int k = 0; k < 2; ++k) dst[m][k] = *(const LAS bf16x8*)(lds + PG8_SA(b, h) + aoff + m * 2048 + k * 1024); } while (0)
; #define PG8_LDB(dst, b, h) do { _Pragma("unroll") for (int n = 0; n < 2; ++n) _Pragma("unroll") for (int k = 0; k < 2; ++k) dst[n][k] = *(const LAS bf16x8*)(lds + PG8_SB(b, h) + boff + n * 2048 + k * 1024); } while (0)
; #define PG8_BAR __builtin_amdgcn_s_barrier()
; template <class Epi, bool ALIGN_EPI = PG8_ALIGN, bool SP2 = PG8_SP2>
; __device__ __forceinline__ void gemm_phase(LAS uchar* lds, const Gemm g, const StaticOrder& S, const Epi& E) {
;     ...
;         for (int t = tb; t < tb + tblk; t += 2) {
;             const bool last = (t == nt - 2);
;             const char* a1 = cA + (size_t)(t + 1) * kstep;
;             const char* a2 = last ? nA : cA + (size_t)(t + 2) * kstep; const char* b2 = last ? nB : cB + (size_t)(t + 2) * kstep;
;             const char* a3 = a2 + kstep; const char* b3 = b2 + kstep;
;             if constexpr (SP2) {
;             PG8_LDB(B0, 0, 0); PG8_LDB(B1, 0, 1); PG8_SCHED; PG8_LDA(At, 0, 0); PG8_STAGE(PG8_SA(1, 1), a1 + hstepA, voffA);
;             PG8_WAIT_V(8); PG8_WAIT_L(0); PG8_BAR; PG8_MMA(0, 0, At, B0); PG8_MMA(0, 1, At, B1); PG8_BAR; PG8_SCHED;
;             PG8_LDA(At, 0, 1); PG8_STAGE(PG8_SB(0, 0), b2, voffB); PG8_STAGE(PG8_SB(0, 1), b2 + hstepB, voffB); PG8_STAGE(PG8_SA(0, 0), a2, voffA);
;             PG8_WAIT_V(8); PG8_WAIT_L(0); PG8_BAR; PG8_MMA(1, 0, At, B0); PG8_MMA(1, 1, At, B1); PG8_BAR; PG8_SCHED;
;             PG8_LDB(B0, 1, 0); PG8_LDB(B1, 1, 1); PG8_SCHED; PG8_LDA(At, 1, 0); PG8_STAGE(PG8_SA(0, 1), a2 + hstepA, voffA);
;             PG8_WAIT_V(8); PG8_WAIT_L(0); PG8_BAR; PG8_MMA(0, 0, At, B0); PG8_MMA(0, 1, At, B1); PG8_BAR; PG8_SCHED;
;             PG8_LDA(At, 1, 1); PG8_STAGE(PG8_SB(1, 0), b3, voffB); PG8_STAGE(PG8_SB(1, 1), b3 + hstepB, voffB); PG8_STAGE(PG8_SA(1, 0), a3, voffA);
;             PG8_WAIT_V(8); PG8_WAIT_L(0); PG8_BAR; PG8_MMA(1, 0, At, B0); PG8_MMA(1, 1, At, B1); PG8_BAR; PG8_SCHED;
	v_mfma_f32_16x16x32_bf16 v[126:129], v[160:163], v[196:199], v[126:129]
	v_mfma_f32_16x16x32_bf16 v[122:125], v[170:173], v[196:199], v[122:125]
	v_mfma_f32_16x16x32_bf16 v[118:121], v[160:163], v[204:207], v[118:121]
	v_mfma_f32_16x16x32_bf16 v[110:113], v[170:173], v[204:207], v[110:113]
	v_mfma_f32_16x16x32_bf16 v[102:105], v[160:163], v[212:215], v[102:105]
	v_mfma_f32_16x16x32_bf16 v[94:97], v[170:173], v[212:215], v[94:97]
	v_mfma_f32_16x16x32_bf16 v[86:89], v[160:163], v[220:223], v[86:89]
	v_mfma_f32_16x16x32_bf16 v[78:81], v[170:173], v[220:223], v[78:81]
	v_mfma_f32_16x16x32_bf16 v[126:129], v[166:169], v[200:203], v[126:129]
	v_mfma_f32_16x16x32_bf16 v[122:125], v[174:177], v[200:203], v[122:125]
	v_mfma_f32_16x16x32_bf16 v[118:121], v[166:169], v[208:211], v[118:121]
	v_mfma_f32_16x16x32_bf16 v[110:113], v[174:177], v[208:211], v[110:113]
	v_mfma_f32_16x16x32_bf16 v[102:105], v[166:169], v[216:219], v[102:105]
	v_mfma_f32_16x16x32_bf16 v[94:97], v[174:177], v[216:219], v[94:97]
	v_mfma_f32_16x16x32_bf16 v[86:89], v[166:169], v[224:227], v[86:89]
	v_mfma_f32_16x16x32_bf16 v[78:81], v[174:177], v[224:227], v[78:81]
	v_mfma_f32_16x16x32_bf16 v[114:117], v[178:181], v[196:199], v[114:117]
	v_mfma_f32_16x16x32_bf16 v[106:109], v[188:191], v[196:199], v[106:109]
	v_mfma_f32_16x16x32_bf16 v[98:101], v[178:181], v[204:207], v[98:101]
	v_mfma_f32_16x16x32_bf16 v[90:93], v[188:191], v[204:207], v[90:93]
	v_mfma_f32_16x16x32_bf16 v[82:85], v[178:181], v[212:215], v[82:85]
	v_mfma_f32_16x16x32_bf16 v[74:77], v[188:191], v[212:215], v[74:77]
	v_mfma_f32_16x16x32_bf16 v[70:73], v[178:181], v[220:223], v[70:73]
	v_mfma_f32_16x16x32_bf16 v[66:69], v[188:191], v[220:223], v[66:69]
	v_mfma_f32_16x16x32_bf16 v[114:117], v[184:187], v[200:203], v[114:117]
	v_mfma_f32_16x16x32_bf16 v[106:109], v[192:195], v[200:203], v[106:109]
	v_mfma_f32_16x16x32_bf16 v[98:101], v[184:187], v[208:211], v[98:101]
	v_mfma_f32_16x16x32_bf16 v[90:93], v[192:195], v[208:211], v[90:93]
	v_mfma_f32_16x16x32_bf16 v[82:85], v[184:187], v[216:219], v[82:85]
	v_mfma_f32_16x16x32_bf16 v[74:77], v[192:195], v[216:219], v[74:77]
	v_mfma_f32_16x16x32_bf16 v[70:73], v[184:187], v[224:227], v[70:73]
	v_mfma_f32_16x16x32_bf16 v[66:69], v[192:195], v[224:227], v[66:69]
	s_barrier
	s_setprio 0
	s_add_i32 s14, s41, s24
	v_lshl_add_u64 v[228:229], s[18:19], 0, v[132:133]
	s_mov_b32 m0, s14
	ds_read_b128 v[196:199], v165 offset:16384
	ds_read_b128 v[200:203], v165 offset:17408
	ds_read_b128 v[204:207], v165 offset:18432
	ds_read_b128 v[208:211], v165 offset:19456
	ds_read_b128 v[212:215], v165 offset:20480
	ds_read_b128 v[216:219], v165 offset:21504
	ds_read_b128 v[220:223], v165 offset:22528
	ds_read_b128 v[224:227], v165 offset:23552
	global_load_lds_dwordx4 v[228:229], off
	s_add_i32 m0, s14, 0x2000
	s_add_u32 s14, s18, 0xb0000
	v_lshl_add_u64 v[230:231], s[18:19], 0, v[154:155]
	s_addc_u32 s15, s19, 0
	s_add_i32 s41, s42, s24
	global_load_lds_dwordx4 v[230:231], off
	v_lshl_add_u64 v[232:233], s[14:15], 0, v[132:133]
	s_mov_b32 m0, s41
	global_load_lds_dwordx4 v[232:233], off
	s_add_i32 m0, s41, 0x2000
	v_lshl_add_u64 v[232:233], s[14:15], 0, v[154:155]
	global_load_lds_dwordx4 v[232:233], off
	s_mov_b32 m0, s25
	v_lshl_add_u64 v[232:233], s[20:21], 0, v[130:131]
	global_load_lds_dwordx4 v[232:233], off
	s_mov_b32 m0, s26
	v_lshl_add_u64 v[234:235], s[20:21], 0, v[134:135]
	global_load_lds_dwordx4 v[234:235], off
	s_waitcnt vmcnt(8)
	s_waitcnt lgkmcnt(0)
	s_setprio 1
	s_barrier
	v_mfma_f32_16x16x32_bf16 v[62:65], v[160:163], v[196:199], v[62:65]
	v_mfma_f32_16x16x32_bf16 v[58:61], v[170:173], v[196:199], v[58:61]
	v_mfma_f32_16x16x32_bf16 v[54:57], v[160:163], v[204:207], v[54:57]
	v_mfma_f32_16x16x32_bf16 v[46:49], v[170:173], v[204:207], v[46:49]
	v_mfma_f32_16x16x32_bf16 v[38:41], v[160:163], v[212:215], v[38:41]
	v_mfma_f32_16x16x32_bf16 v[30:33], v[170:173], v[212:215], v[30:33]
	v_mfma_f32_16x16x32_bf16 v[22:25], v[160:163], v[220:223], v[22:25]
	v_mfma_f32_16x16x32_bf16 v[14:17], v[170:173], v[220:223], v[14:17]
	v_mfma_f32_16x16x32_bf16 v[62:65], v[166:169], v[200:203], v[62:65]
	v_mfma_f32_16x16x32_bf16 v[58:61], v[174:177], v[200:203], v[58:61]
	v_mfma_f32_16x16x32_bf16 v[54:57], v[166:169], v[208:211], v[54:57]
	v_mfma_f32_16x16x32_bf16 v[46:49], v[174:177], v[208:211], v[46:49]
	v_mfma_f32_16x16x32_bf16 v[38:41], v[166:169], v[216:219], v[38:41]
	v_mfma_f32_16x16x32_bf16 v[30:33], v[174:177], v[216:219], v[30:33]
	v_mfma_f32_16x16x32_bf16 v[22:25], v[166:169], v[224:227], v[22:25]
	v_mfma_f32_16x16x32_bf16 v[14:17], v[174:177], v[224:227], v[14:17]
	v_mfma_f32_16x16x32_bf16 v[50:53], v[178:181], v[196:199], v[50:53]
	v_mfma_f32_16x16x32_bf16 v[42:45], v[188:191], v[196:199], v[42:45]
	v_mfma_f32_16x16x32_bf16 v[34:37], v[178:181], v[204:207], v[34:37]
	v_mfma_f32_16x16x32_bf16 v[26:29], v[188:191], v[204:207], v[26:29]
	v_mfma_f32_16x16x32_bf16 v[18:21], v[178:181], v[212:215], v[18:21]
	v_mfma_f32_16x16x32_bf16 v[10:13], v[188:191], v[212:215], v[10:13]
	v_mfma_f32_16x16x32_bf16 v[6:9], v[178:181], v[220:223], v[6:9]
	v_mfma_f32_16x16x32_bf16 v[2:5], v[188:191], v[220:223], v[2:5]
	v_mfma_f32_16x16x32_bf16 v[50:53], v[184:187], v[200:203], v[50:53]
	v_mfma_f32_16x16x32_bf16 v[42:45], v[192:195], v[200:203], v[42:45]
	v_mfma_f32_16x16x32_bf16 v[34:37], v[184:187], v[208:211], v[34:37]
	v_mfma_f32_16x16x32_bf16 v[26:29], v[192:195], v[208:211], v[26:29]
	v_mfma_f32_16x16x32_bf16 v[18:21], v[184:187], v[216:219], v[18:21]
	v_mfma_f32_16x16x32_bf16 v[10:13], v[192:195], v[216:219], v[10:13]
	v_mfma_f32_16x16x32_bf16 v[6:9], v[184:187], v[224:227], v[6:9]
	v_mfma_f32_16x16x32_bf16 v[2:5], v[192:195], v[224:227], v[2:5]
	s_barrier
; #define PG8_STAGE(bufoff, gbase, voff) do { _Pragma("unroll") for (int _i = 0; _i < 2; ++_i) \
;         __builtin_amdgcn_global_load_lds((const unsigned*)((const char*)(gbase) + (voff)[_i]), (LAS unsigned*)(lds + (bufoff) + ldsw + _i * 8192), 16, 0, 0); } while (0)
; #define PG8_LDA(dst, b, h) do { _Pragma("unroll") for (int m = 0; m < 4; ++m) _Pragma("unroll") for (int k = 0; k < 2; ++k) dst[m][k] = *(const LAS bf16x8*)(lds + PG8_SA(b, h) + aoff + m * 2048 + k * 1024); } while (0)
; #define PG8_LDB(dst, b, h) do { _Pragma("unroll") for (int n = 0; n < 2; ++n) _Pragma("unroll") for (int k = 0; k < 2; ++k) dst[n][k] = *(const LAS bf16x8*)(lds + PG8_SB(b, h) + boff + n * 2048 + k * 1024); } while (0)
; #define PG8_MMA(ai, bj, At, Bt) do { __builtin_amdgcn_s_setprio(1); _Pragma("unroll") for (int m = 0; m < 4; ++m) _Pragma("unroll") for (int n = 0; n < 2; ++n) _Pragma("unroll") for (int k = 0; k < 2; ++k) \
;         acc[ai][bj][m][n] = __builtin_amdgcn_mfma_f32_16x16x32_bf16(Bt[n][k], At[m][k], acc[ai][bj][m][n], 0, 0, 0); __builtin_amdgcn_s_setprio(0); } while (0)
; #define PG8_WAIT_V(n) asm volatile("s_waitcnt vmcnt(" #n ")" ::: "memory")
; #define PG8_WAIT_L(n) asm volatile("s_waitcnt lgkmcnt(" #n ")" ::: "memory")
; #define PG8_BAR __builtin_amdgcn_s_barrier()
; #define PG8_SCHED __builtin_amdgcn_sched_barrier(0)
; template <class Epi, bool ALIGN_EPI = PG8_ALIGN, bool SP2 = PG8_SP2>
; __device__ __forceinline__ void gemm_phase(LAS uchar* lds, const Gemm g, const StaticOrder& S, const Epi& E) {
;     ...
;             PG8_LDB(B0, 1, 0); PG8_LDB(B1, 1, 1); PG8_SCHED; PG8_LDA(At, 1, 0); PG8_STAGE(PG8_SA(0, 1), a2 + hstepA, voffA);
;             PG8_WAIT_V(8); PG8_WAIT_L(0); PG8_BAR; PG8_MMA(0, 0, At, B0); PG8_MMA(0, 1, At, B1); PG8_BAR; PG8_SCHED;
	s_setprio 0
	s_add_i32 s41, 0, 0x18000
	v_add_u32_e32 v144, s41, v139
	s_add_i32 s42, 0, 0x1c000
	ds_read_b128 v[160:163], v144
	ds_read_b128 v[166:169], v144 offset:1024
	ds_read_b128 v[170:173], v144 offset:2048
	ds_read_b128 v[174:177], v144 offset:3072
	v_add_u32_e32 v144, s42, v139
	ds_read_b128 v[178:181], v144
	ds_read_b128 v[184:187], v144 offset:1024
	ds_read_b128 v[188:191], v144 offset:2048
	ds_read_b128 v[192:195], v144 offset:3072
	s_add_u32 s14, s20, 0xb0000
	s_addc_u32 s15, s21, 0
	s_mov_b32 m0, s27
	v_lshl_add_u64 v[236:237], s[14:15], 0, v[130:131]
	ds_read_b128 v[196:199], v165 offset:32768
	ds_read_b128 v[200:203], v165 offset:33792
	ds_read_b128 v[204:207], v165 offset:34816
	ds_read_b128 v[208:211], v165 offset:35840
	ds_read_b128 v[212:215], v165 offset:36864
	ds_read_b128 v[216:219], v165 offset:37888
	ds_read_b128 v[220:223], v165 offset:38912
	ds_read_b128 v[224:227], v165 offset:39936
	global_load_lds_dwordx4 v[236:237], off
	s_mov_b32 m0, s28
	v_lshl_add_u64 v[236:237], s[14:15], 0, v[134:135]
	global_load_lds_dwordx4 v[236:237], off
	s_waitcnt vmcnt(8)
	s_waitcnt lgkmcnt(0)
	s_setprio 1
	s_barrier
	v_mfma_f32_16x16x32_bf16 v[126:129], v[160:163], v[196:199], v[126:129]
	v_mfma_f32_16x16x32_bf16 v[122:125], v[170:173], v[196:199], v[122:125]
	v_mfma_f32_16x16x32_bf16 v[118:121], v[160:163], v[204:207], v[118:121]
	v_mfma_f32_16x16x32_bf16 v[110:113], v[170:173], v[204:207], v[110:113]
	v_mfma_f32_16x16x32_bf16 v[102:105], v[160:163], v[212:215], v[102:105]
	v_mfma_f32_16x16x32_bf16 v[94:97], v[170:173], v[212:215], v[94:97]
	v_mfma_f32_16x16x32_bf16 v[86:89], v[160:163], v[220:223], v[86:89]
	v_mfma_f32_16x16x32_bf16 v[78:81], v[170:173], v[220:223], v[78:81]
	v_mfma_f32_16x16x32_bf16 v[126:129], v[166:169], v[200:203], v[126:129]
	v_mfma_f32_16x16x32_bf16 v[122:125], v[174:177], v[200:203], v[122:125]
	v_mfma_f32_16x16x32_bf16 v[118:121], v[166:169], v[208:211], v[118:121]
	v_mfma_f32_16x16x32_bf16 v[110:113], v[174:177], v[208:211], v[110:113]
	v_mfma_f32_16x16x32_bf16 v[102:105], v[166:169], v[216:219], v[102:105]
	v_mfma_f32_16x16x32_bf16 v[94:97], v[174:177], v[216:219], v[94:97]
	v_mfma_f32_16x16x32_bf16 v[86:89], v[166:169], v[224:227], v[86:89]
	v_mfma_f32_16x16x32_bf16 v[78:81], v[174:177], v[224:227], v[78:81]
	v_mfma_f32_16x16x32_bf16 v[114:117], v[178:181], v[196:199], v[114:117]
	v_mfma_f32_16x16x32_bf16 v[106:109], v[188:191], v[196:199], v[106:109]
	v_mfma_f32_16x16x32_bf16 v[98:101], v[178:181], v[204:207], v[98:101]
	v_mfma_f32_16x16x32_bf16 v[90:93], v[188:191], v[204:207], v[90:93]
	v_mfma_f32_16x16x32_bf16 v[82:85], v[178:181], v[212:215], v[82:85]
	v_mfma_f32_16x16x32_bf16 v[74:77], v[188:191], v[212:215], v[74:77]
	v_mfma_f32_16x16x32_bf16 v[70:73], v[178:181], v[220:223], v[70:73]
	v_mfma_f32_16x16x32_bf16 v[66:69], v[188:191], v[220:223], v[66:69]
	v_mfma_f32_16x16x32_bf16 v[114:117], v[184:187], v[200:203], v[114:117]
	v_mfma_f32_16x16x32_bf16 v[106:109], v[192:195], v[200:203], v[106:109]
	v_mfma_f32_16x16x32_bf16 v[98:101], v[184:187], v[208:211], v[98:101]
	v_mfma_f32_16x16x32_bf16 v[90:93], v[192:195], v[208:211], v[90:93]
	v_mfma_f32_16x16x32_bf16 v[82:85], v[184:187], v[216:219], v[82:85]
	v_mfma_f32_16x16x32_bf16 v[74:77], v[192:195], v[216:219], v[74:77]
	v_mfma_f32_16x16x32_bf16 v[70:73], v[184:187], v[224:227], v[70:73]
	v_mfma_f32_16x16x32_bf16 v[66:69], v[192:195], v[224:227], v[66:69]
	s_barrier
; #define PG8_STAGE(bufoff, gbase, voff) do { _Pragma("unroll") for (int _i = 0; _i < 2; ++_i) \
;         __builtin_amdgcn_global_load_lds((const unsigned*)((const char*)(gbase) + (voff)[_i]), (LAS unsigned*)(lds + (bufoff) + ldsw + _i * 8192), 16, 0, 0); } while (0)
; #define PG8_LDA(dst, b, h) do { _Pragma("unroll") for (int m = 0; m < 4; ++m) _Pragma("unroll") for (int k = 0; k < 2; ++k) dst[m][k] = *(const LAS bf16x8*)(lds + PG8_SA(b, h) + aoff + m * 2048 + k * 1024); } while (0)
; #define PG8_LDB(dst, b, h) do { _Pragma("unroll") for (int n = 0; n < 2; ++n) _Pragma("unroll") for (int k = 0; k < 2; ++k) dst[n][k] = *(const LAS bf16x8*)(lds + PG8_SB(b, h) + boff + n * 2048 + k * 1024); } while (0)
; template <class Epi, bool ALIGN_EPI = PG8_ALIGN, bool SP2 = PG8_SP2>
; __device__ __forceinline__ void gemm_phase(LAS uchar* lds, const Gemm g, const StaticOrder& S, const Epi& E) {
;     ...
;         for (int t = tb; t < tb + tblk; t += 2) {
;             const bool last = (t == nt - 2);
;             const char* a1 = cA + (size_t)(t + 1) * kstep;
;             const char* a2 = last ? nA : cA + (size_t)(t + 2) * kstep; const char* b2 = last ? nB : cB + (size_t)(t + 2) * kstep;
;             const char* a3 = a2 + kstep; const char* b3 = b2 + kstep;
;             if constexpr (SP2) {
;             PG8_LDB(B0, 0, 0); PG8_LDB(B1, 0, 1); PG8_SCHED; PG8_LDA(At, 0, 0); PG8_STAGE(PG8_SA(1, 1), a1 + hstepA, voffA);
;             PG8_WAIT_V(8); PG8_WAIT_L(0); PG8_BAR; PG8_MMA(0, 0, At, B0); PG8_MMA(0, 1, At, B1); PG8_BAR; PG8_SCHED;
;             PG8_LDA(At, 0, 1); PG8_STAGE(PG8_SB(0, 0), b2, voffB); PG8_STAGE(PG8_SB(0, 1), b2 + hstepB, voffB); PG8_STAGE(PG8_SA(0, 0), a2, voffA);
;             PG8_WAIT_V(8); PG8_WAIT_L(0); PG8_BAR; PG8_MMA(1, 0, At, B0); PG8_MMA(1, 1, At, B1); PG8_BAR; PG8_SCHED;
;             PG8_LDB(B0, 1, 0); PG8_LDB(B1, 1, 1); PG8_SCHED; PG8_LDA(At, 1, 0); PG8_STAGE(PG8_SA(0, 1), a2 + hstepA, voffA);
;             PG8_WAIT_V(8); PG8_WAIT_L(0); PG8_BAR; PG8_MMA(0, 0, At, B0); PG8_MMA(0, 1, At, B1); PG8_BAR; PG8_SCHED;
;             PG8_LDA(At, 1, 1); PG8_STAGE(PG8_SB(1, 0), b3, voffB); PG8_STAGE(PG8_SB(1, 1), b3 + hstepB, voffB); PG8_STAGE(PG8_SA(1, 0), a3, voffA);
;             PG8_WAIT_V(8); PG8_WAIT_L(0); PG8_BAR; PG8_MMA(1, 0, At, B0); PG8_MMA(1, 1, At, B1); PG8_BAR; PG8_SCHED;
;     ...
;         if constexpr (ALIGN_EPI) { if (wr == 0) PG8_BAR; }
	s_setprio 0
	s_add_i32 s14, s41, s24
	v_lshl_add_u64 v[228:229], v[228:229], 0, s[84:85]
	s_mov_b32 m0, s14
	ds_read_b128 v[196:199], v165 offset:49152
	ds_read_b128 v[200:203], v165 offset:50176
	ds_read_b128 v[204:207], v165 offset:51200
	ds_read_b128 v[208:211], v165 offset:52224
	ds_read_b128 v[212:215], v165 offset:53248
	ds_read_b128 v[216:219], v165 offset:54272
	ds_read_b128 v[220:223], v165 offset:55296
	ds_read_b128 v[224:227], v165 offset:56320
	global_load_lds_dwordx4 v[228:229], off
	s_add_i32 m0, s14, 0x2000
	s_add_u32 s14, s18, 0xb0080
	v_lshl_add_u64 v[228:229], v[230:231], 0, s[84:85]
	s_addc_u32 s15, s19, 0
	s_add_i32 s18, s42, s24
	global_load_lds_dwordx4 v[228:229], off
	s_mov_b32 m0, s18
	v_lshl_add_u64 v[228:229], s[14:15], 0, v[132:133]
	global_load_lds_dwordx4 v[228:229], off
	s_add_i32 m0, s18, 0x2000
	v_lshl_add_u64 v[228:229], s[14:15], 0, v[154:155]
	global_load_lds_dwordx4 v[228:229], off
	s_mov_b32 m0, s29
	v_lshl_add_u64 v[228:229], v[232:233], 0, s[84:85]
	global_load_lds_dwordx4 v[228:229], off
	s_mov_b32 m0, s30
	v_lshl_add_u64 v[228:229], v[234:235], 0, s[84:85]
	global_load_lds_dwordx4 v[228:229], off
	s_waitcnt vmcnt(8)
	s_waitcnt lgkmcnt(0)
	s_setprio 1
	s_barrier
	v_mfma_f32_16x16x32_bf16 v[62:65], v[160:163], v[196:199], v[62:65]
	v_mfma_f32_16x16x32_bf16 v[58:61], v[170:173], v[196:199], v[58:61]
	v_mfma_f32_16x16x32_bf16 v[54:57], v[160:163], v[204:207], v[54:57]
	v_mfma_f32_16x16x32_bf16 v[46:49], v[170:173], v[204:207], v[46:49]
	v_mfma_f32_16x16x32_bf16 v[38:41], v[160:163], v[212:215], v[38:41]
	v_mfma_f32_16x16x32_bf16 v[30:33], v[170:173], v[212:215], v[30:33]
	v_mfma_f32_16x16x32_bf16 v[22:25], v[160:163], v[220:223], v[22:25]
	v_mfma_f32_16x16x32_bf16 v[14:17], v[170:173], v[220:223], v[14:17]
	v_mfma_f32_16x16x32_bf16 v[62:65], v[166:169], v[200:203], v[62:65]
	v_mfma_f32_16x16x32_bf16 v[58:61], v[174:177], v[200:203], v[58:61]
	v_mfma_f32_16x16x32_bf16 v[54:57], v[166:169], v[208:211], v[54:57]
	v_mfma_f32_16x16x32_bf16 v[46:49], v[174:177], v[208:211], v[46:49]
	v_mfma_f32_16x16x32_bf16 v[38:41], v[166:169], v[216:219], v[38:41]
	v_mfma_f32_16x16x32_bf16 v[30:33], v[174:177], v[216:219], v[30:33]
	v_mfma_f32_16x16x32_bf16 v[22:25], v[166:169], v[224:227], v[22:25]
	v_mfma_f32_16x16x32_bf16 v[14:17], v[174:177], v[224:227], v[14:17]
	v_mfma_f32_16x16x32_bf16 v[50:53], v[178:181], v[196:199], v[50:53]
	v_mfma_f32_16x16x32_bf16 v[42:45], v[188:191], v[196:199], v[42:45]
	v_mfma_f32_16x16x32_bf16 v[34:37], v[178:181], v[204:207], v[34:37]
	v_mfma_f32_16x16x32_bf16 v[26:29], v[188:191], v[204:207], v[26:29]
	v_mfma_f32_16x16x32_bf16 v[18:21], v[178:181], v[212:215], v[18:21]
	v_mfma_f32_16x16x32_bf16 v[10:13], v[188:191], v[212:215], v[10:13]
	v_mfma_f32_16x16x32_bf16 v[6:9], v[178:181], v[220:223], v[6:9]
	v_mfma_f32_16x16x32_bf16 v[2:5], v[188:191], v[220:223], v[2:5]
	v_mfma_f32_16x16x32_bf16 v[50:53], v[184:187], v[200:203], v[50:53]
	v_mfma_f32_16x16x32_bf16 v[42:45], v[192:195], v[200:203], v[42:45]
	v_mfma_f32_16x16x32_bf16 v[34:37], v[184:187], v[208:211], v[34:37]
	v_mfma_f32_16x16x32_bf16 v[26:29], v[192:195], v[208:211], v[26:29]
	v_mfma_f32_16x16x32_bf16 v[18:21], v[184:187], v[216:219], v[18:21]
	v_mfma_f32_16x16x32_bf16 v[10:13], v[192:195], v[216:219], v[10:13]
	v_mfma_f32_16x16x32_bf16 v[6:9], v[184:187], v[224:227], v[6:9]
	v_mfma_f32_16x16x32_bf16 v[2:5], v[192:195], v[224:227], v[2:5]
	s_barrier
	s_setprio 0
	s_add_i32 s40, s40, 2
	s_add_u32 s38, s38, 0x100
	s_addc_u32 s39, s39, 0
	s_cmp_gt_u32 s40, 41
	s_mov_b64 s[14:15], s[16:17]
	s_cbranch_scc0 .LBB0_1143
	s_and_b64 vcc, exec, s[10:11]
	s_cbranch_vccz .LBB0_1146
	s_barrier
